# gdn_prep forward substitution: packed v_pk_fma_f32 on paired X registers (half the FMA instructions), accumulators from zero then added to the rhs
# speedup vs baseline: 1.0125x; 1.0020x over previous
; DI bf16_t f2bf(float a) { return (bf16_t)(pk2(a, 0.f) & 0xffffu); }
; DI float bf2f(bf16_t v) { return __uint_as_float(((unsigned)v) << 16); }
; DI void gdn_prep(const Params& p, int item, unsigned char* smem) {
;     ...
;             const float dec = c >= j ? expf(sgc[c] - gcj) : 0.f;
;             sL[c * 68 + j] = c > j ? sbeta[c] * akk[e] * dec : 0.f;
;             ag[c * 64 + j] = f2bf(aqk[e] * dec);
;         }
;     }
;     __syncthreads();
;     {
;         float X[64];
;         const bf16_t* src = tid < 128 ? (sv + tid) : (sk + tid - 128);
; #pragma unroll
;         for (int i = 0; i < 64; ++i) { float a = bf2f(src[i * 136]) * sbeta[i]; if (tid >= 128) a *= segc[i]; X[i] = a; }
.LBB0_279:
	s_or_b64 exec, exec, s[4:5]
	ds_write_b32 v0, v2 offset:52496
	v_mul_f32_e32 v0, v15, v3
	v_cvt_pk_bf16_f32 v2, v0, s0
	v_lshl_add_u32 v0, v1, 6, v33
	s_add_u32 s4, s72, s36
	v_ashrrev_i32_e32 v1, 31, v0
	s_addc_u32 s5, s73, s37
	v_lshl_add_u64 v[0:1], v[0:1], 1, s[4:5]
	s_mov_b32 s4, 0x3a1c5000
	v_add_co_u32_e32 v0, vcc, s4, v0
	s_movk_i32 s4, 0x80
	s_nop 0
	v_addc_co_u32_e32 v1, vcc, 0, v1, vcc
	v_cmp_gt_i32_e32 vcc, s4, v46
	global_store_short v[0:1], v2, off
	v_lshl_add_u32 v0, v46, 1, s10
	v_cndmask_b32_e32 v1, v205, v206, vcc
	v_add_u32_e32 v0, v0, v1
	v_mov_b32_e32 v1, s49
	s_waitcnt lgkmcnt(0)
	s_barrier
	s_movk_i32 s4, 0x7f
	v_cmp_lt_i32_e32 vcc, s4, v46
	v_mov_b32_e32 v84, s49
	v_mov_b32_e32 v79, v0
	ds_read_u16 v0, v79
	ds_read_u16 v1, v79 offset:272
	ds_read_u16 v2, v79 offset:544
	ds_read_u16 v3, v79 offset:816
	ds_read_u16 v4, v79 offset:1088
	ds_read_u16 v5, v79 offset:1360
	ds_read_u16 v6, v79 offset:1632
	ds_read_u16 v7, v79 offset:1904
	ds_read_b128 v[88:91], v84 offset:0
	ds_read_b128 v[92:95], v84 offset:16
	ds_read_b128 v[96:99], v84 offset:256
	ds_read_b128 v[100:103], v84 offset:272
	s_waitcnt lgkmcnt(0)
	v_lshlrev_b32_e32 v0, 16, v0
	v_cndmask_b32_e32 v104, 1.0, v96, vcc
	v_lshlrev_b32_e32 v1, 16, v1
	v_cndmask_b32_e32 v105, 1.0, v97, vcc
	v_lshlrev_b32_e32 v2, 16, v2
	v_cndmask_b32_e32 v106, 1.0, v98, vcc
	v_lshlrev_b32_e32 v3, 16, v3
	v_cndmask_b32_e32 v107, 1.0, v99, vcc
	v_lshlrev_b32_e32 v4, 16, v4
	v_cndmask_b32_e32 v108, 1.0, v100, vcc
	v_lshlrev_b32_e32 v5, 16, v5
	v_cndmask_b32_e32 v109, 1.0, v101, vcc
	v_lshlrev_b32_e32 v6, 16, v6
	v_cndmask_b32_e32 v110, 1.0, v102, vcc
	v_lshlrev_b32_e32 v7, 16, v7
	v_cndmask_b32_e32 v111, 1.0, v103, vcc
	v_mul_f32_e32 v0, v88, v0
	v_mul_f32_e32 v1, v89, v1
	v_mul_f32_e32 v2, v90, v2
	v_mul_f32_e32 v3, v91, v3
	v_mul_f32_e32 v4, v92, v4
	v_mul_f32_e32 v5, v93, v5
	v_mul_f32_e32 v6, v94, v6
	v_mul_f32_e32 v7, v95, v7
	v_mul_f32_e32 v0, v0, v104
	v_mul_f32_e32 v1, v1, v105
	v_mul_f32_e32 v2, v2, v106
	v_mul_f32_e32 v3, v3, v107
	v_mul_f32_e32 v4, v4, v108
	v_mul_f32_e32 v5, v5, v109
	v_mul_f32_e32 v6, v6, v110
	v_mul_f32_e32 v7, v7, v111
	ds_read_u16 v8, v79 offset:2176
	ds_read_u16 v9, v79 offset:2448
	ds_read_u16 v10, v79 offset:2720
	ds_read_u16 v11, v79 offset:2992
	ds_read_u16 v12, v79 offset:3264
	ds_read_u16 v13, v79 offset:3536
	ds_read_u16 v14, v79 offset:3808
	ds_read_u16 v15, v79 offset:4080
	ds_read_b128 v[88:91], v84 offset:32
	ds_read_b128 v[92:95], v84 offset:48
	ds_read_b128 v[96:99], v84 offset:288
	ds_read_b128 v[100:103], v84 offset:304
	s_waitcnt lgkmcnt(0)
	v_lshlrev_b32_e32 v8, 16, v8
	v_cndmask_b32_e32 v104, 1.0, v96, vcc
	v_lshlrev_b32_e32 v9, 16, v9
	v_cndmask_b32_e32 v105, 1.0, v97, vcc
	v_lshlrev_b32_e32 v10, 16, v10
	v_cndmask_b32_e32 v106, 1.0, v98, vcc
	v_lshlrev_b32_e32 v11, 16, v11
	v_cndmask_b32_e32 v107, 1.0, v99, vcc
	v_lshlrev_b32_e32 v12, 16, v12
	v_cndmask_b32_e32 v108, 1.0, v100, vcc
	v_lshlrev_b32_e32 v13, 16, v13
	v_cndmask_b32_e32 v109, 1.0, v101, vcc
	v_lshlrev_b32_e32 v14, 16, v14
	v_cndmask_b32_e32 v110, 1.0, v102, vcc
	v_lshlrev_b32_e32 v15, 16, v15
	v_cndmask_b32_e32 v111, 1.0, v103, vcc
	v_mul_f32_e32 v8, v88, v8
	v_mul_f32_e32 v9, v89, v9
	v_mul_f32_e32 v10, v90, v10
	v_mul_f32_e32 v11, v91, v11
	v_mul_f32_e32 v12, v92, v12
	v_mul_f32_e32 v13, v93, v13
	v_mul_f32_e32 v14, v94, v14
	v_mul_f32_e32 v15, v95, v15
	v_mul_f32_e32 v8, v8, v104
	v_mul_f32_e32 v9, v9, v105
	v_mul_f32_e32 v10, v10, v106
	v_mul_f32_e32 v11, v11, v107
	v_mul_f32_e32 v12, v12, v108
	v_mul_f32_e32 v13, v13, v109
	v_mul_f32_e32 v14, v14, v110
	v_mul_f32_e32 v15, v15, v111
	ds_read_u16 v16, v79 offset:4352
	ds_read_u16 v17, v79 offset:4624
	ds_read_u16 v18, v79 offset:4896
	ds_read_u16 v19, v79 offset:5168
	ds_read_u16 v20, v79 offset:5440
	ds_read_u16 v21, v79 offset:5712
	ds_read_u16 v22, v79 offset:5984
	ds_read_u16 v23, v79 offset:6256
	ds_read_b128 v[88:91], v84 offset:64
	ds_read_b128 v[92:95], v84 offset:80
	ds_read_b128 v[96:99], v84 offset:320
	ds_read_b128 v[100:103], v84 offset:336
	s_waitcnt lgkmcnt(0)
	v_lshlrev_b32_e32 v16, 16, v16
	v_cndmask_b32_e32 v104, 1.0, v96, vcc
	v_lshlrev_b32_e32 v17, 16, v17
	v_cndmask_b32_e32 v105, 1.0, v97, vcc
	v_lshlrev_b32_e32 v18, 16, v18
	v_cndmask_b32_e32 v106, 1.0, v98, vcc
	v_lshlrev_b32_e32 v19, 16, v19
	v_cndmask_b32_e32 v107, 1.0, v99, vcc
	v_lshlrev_b32_e32 v20, 16, v20
	v_cndmask_b32_e32 v108, 1.0, v100, vcc
	v_lshlrev_b32_e32 v21, 16, v21
	v_cndmask_b32_e32 v109, 1.0, v101, vcc
	v_lshlrev_b32_e32 v22, 16, v22
	v_cndmask_b32_e32 v110, 1.0, v102, vcc
	v_lshlrev_b32_e32 v23, 16, v23
	v_cndmask_b32_e32 v111, 1.0, v103, vcc
	v_mul_f32_e32 v16, v88, v16
	v_mul_f32_e32 v17, v89, v17
	v_mul_f32_e32 v18, v90, v18
	v_mul_f32_e32 v19, v91, v19
	v_mul_f32_e32 v20, v92, v20
	v_mul_f32_e32 v21, v93, v21
	v_mul_f32_e32 v22, v94, v22
	v_mul_f32_e32 v23, v95, v23
	v_mul_f32_e32 v16, v16, v104
	v_mul_f32_e32 v17, v17, v105
	v_mul_f32_e32 v18, v18, v106
	v_mul_f32_e32 v19, v19, v107
	v_mul_f32_e32 v20, v20, v108
	v_mul_f32_e32 v21, v21, v109
	v_mul_f32_e32 v22, v22, v110
	v_mul_f32_e32 v23, v23, v111
	ds_read_u16 v24, v79 offset:6528
	ds_read_u16 v25, v79 offset:6800
	ds_read_u16 v26, v79 offset:7072
	ds_read_u16 v27, v79 offset:7344
	ds_read_u16 v28, v79 offset:7616
	ds_read_u16 v29, v79 offset:7888
	ds_read_u16 v30, v79 offset:8160
	ds_read_u16 v31, v79 offset:8432
	ds_read_b128 v[88:91], v84 offset:96
	ds_read_b128 v[92:95], v84 offset:112
	ds_read_b128 v[96:99], v84 offset:352
	ds_read_b128 v[100:103], v84 offset:368
	s_waitcnt lgkmcnt(0)
; DI float bf2f(bf16_t v) { return __uint_as_float(((unsigned)v) << 16); }
; DI void gdn_prep(const Params& p, int item, unsigned char* smem) {
;     ...
;         const bf16_t* src = tid < 128 ? (sv + tid) : (sk + tid - 128);
; #pragma unroll
;         for (int i = 0; i < 64; ++i) { float a = bf2f(src[i * 136]) * sbeta[i]; if (tid >= 128) a *= segc[i]; X[i] = a; }
	v_lshlrev_b32_e32 v24, 16, v24
	v_cndmask_b32_e32 v104, 1.0, v96, vcc
	v_lshlrev_b32_e32 v25, 16, v25
	v_cndmask_b32_e32 v105, 1.0, v97, vcc
	v_lshlrev_b32_e32 v26, 16, v26
	v_cndmask_b32_e32 v106, 1.0, v98, vcc
	v_lshlrev_b32_e32 v27, 16, v27
	v_cndmask_b32_e32 v107, 1.0, v99, vcc
	v_lshlrev_b32_e32 v28, 16, v28
	v_cndmask_b32_e32 v108, 1.0, v100, vcc
	v_lshlrev_b32_e32 v29, 16, v29
	v_cndmask_b32_e32 v109, 1.0, v101, vcc
	v_lshlrev_b32_e32 v30, 16, v30
	v_cndmask_b32_e32 v110, 1.0, v102, vcc
	v_lshlrev_b32_e32 v31, 16, v31
	v_cndmask_b32_e32 v111, 1.0, v103, vcc
	v_mul_f32_e32 v24, v88, v24
	v_mul_f32_e32 v25, v89, v25
	v_mul_f32_e32 v26, v90, v26
	v_mul_f32_e32 v27, v91, v27
	v_mul_f32_e32 v28, v92, v28
	v_mul_f32_e32 v29, v93, v29
	v_mul_f32_e32 v30, v94, v30
	v_mul_f32_e32 v31, v95, v31
	v_mul_f32_e32 v24, v24, v104
	v_mul_f32_e32 v25, v25, v105
	v_mul_f32_e32 v26, v26, v106
	v_mul_f32_e32 v27, v27, v107
	v_mul_f32_e32 v28, v28, v108
	v_mul_f32_e32 v29, v29, v109
	v_mul_f32_e32 v30, v30, v110
	v_mul_f32_e32 v31, v31, v111
	ds_read_u16 v34, v79 offset:8704
	ds_read_u16 v35, v79 offset:8976
	ds_read_u16 v36, v79 offset:9248
	ds_read_u16 v37, v79 offset:9520
	ds_read_u16 v38, v79 offset:9792
	ds_read_u16 v39, v79 offset:10064
	ds_read_u16 v40, v79 offset:10336
	ds_read_u16 v41, v79 offset:10608
	ds_read_b128 v[88:91], v84 offset:128
	ds_read_b128 v[92:95], v84 offset:144
	ds_read_b128 v[96:99], v84 offset:384
	ds_read_b128 v[100:103], v84 offset:400
	s_waitcnt lgkmcnt(0)
	v_lshlrev_b32_e32 v34, 16, v34
	v_cndmask_b32_e32 v104, 1.0, v96, vcc
	v_lshlrev_b32_e32 v35, 16, v35
	v_cndmask_b32_e32 v105, 1.0, v97, vcc
	v_lshlrev_b32_e32 v36, 16, v36
	v_cndmask_b32_e32 v106, 1.0, v98, vcc
	v_lshlrev_b32_e32 v37, 16, v37
	v_cndmask_b32_e32 v107, 1.0, v99, vcc
	v_lshlrev_b32_e32 v38, 16, v38
	v_cndmask_b32_e32 v108, 1.0, v100, vcc
	v_lshlrev_b32_e32 v39, 16, v39
	v_cndmask_b32_e32 v109, 1.0, v101, vcc
	v_lshlrev_b32_e32 v40, 16, v40
	v_cndmask_b32_e32 v110, 1.0, v102, vcc
	v_lshlrev_b32_e32 v41, 16, v41
	v_cndmask_b32_e32 v111, 1.0, v103, vcc
	v_mul_f32_e32 v34, v88, v34
	v_mul_f32_e32 v35, v89, v35
	v_mul_f32_e32 v36, v90, v36
	v_mul_f32_e32 v37, v91, v37
	v_mul_f32_e32 v38, v92, v38
	v_mul_f32_e32 v39, v93, v39
	v_mul_f32_e32 v40, v94, v40
	v_mul_f32_e32 v41, v95, v41
	v_mul_f32_e32 v34, v34, v104
	v_mul_f32_e32 v35, v35, v105
	v_mul_f32_e32 v36, v36, v106
	v_mul_f32_e32 v37, v37, v107
	v_mul_f32_e32 v38, v38, v108
	v_mul_f32_e32 v39, v39, v109
	v_mul_f32_e32 v40, v40, v110
	v_mul_f32_e32 v41, v41, v111
	ds_read_u16 v42, v79 offset:10880
	ds_read_u16 v43, v79 offset:11152
	ds_read_u16 v44, v79 offset:11424
	ds_read_u16 v45, v79 offset:11696
	ds_read_u16 v48, v79 offset:11968
	ds_read_u16 v49, v79 offset:12240
	ds_read_u16 v50, v79 offset:12512
	ds_read_u16 v51, v79 offset:12784
	ds_read_b128 v[88:91], v84 offset:160
	ds_read_b128 v[92:95], v84 offset:176
	ds_read_b128 v[96:99], v84 offset:416
	ds_read_b128 v[100:103], v84 offset:432
	s_waitcnt lgkmcnt(0)
	v_lshlrev_b32_e32 v42, 16, v42
	v_cndmask_b32_e32 v104, 1.0, v96, vcc
	v_lshlrev_b32_e32 v43, 16, v43
	v_cndmask_b32_e32 v105, 1.0, v97, vcc
	v_lshlrev_b32_e32 v44, 16, v44
	v_cndmask_b32_e32 v106, 1.0, v98, vcc
	v_lshlrev_b32_e32 v45, 16, v45
	v_cndmask_b32_e32 v107, 1.0, v99, vcc
	v_lshlrev_b32_e32 v48, 16, v48
	v_cndmask_b32_e32 v108, 1.0, v100, vcc
	v_lshlrev_b32_e32 v49, 16, v49
	v_cndmask_b32_e32 v109, 1.0, v101, vcc
	v_lshlrev_b32_e32 v50, 16, v50
	v_cndmask_b32_e32 v110, 1.0, v102, vcc
	v_lshlrev_b32_e32 v51, 16, v51
	v_cndmask_b32_e32 v111, 1.0, v103, vcc
	v_mul_f32_e32 v42, v88, v42
	v_mul_f32_e32 v43, v89, v43
	v_mul_f32_e32 v44, v90, v44
	v_mul_f32_e32 v45, v91, v45
	v_mul_f32_e32 v48, v92, v48
	v_mul_f32_e32 v49, v93, v49
	v_mul_f32_e32 v50, v94, v50
	v_mul_f32_e32 v51, v95, v51
	v_mul_f32_e32 v42, v42, v104
	v_mul_f32_e32 v43, v43, v105
	v_mul_f32_e32 v44, v44, v106
	v_mul_f32_e32 v45, v45, v107
	v_mul_f32_e32 v48, v48, v108
	v_mul_f32_e32 v49, v49, v109
	v_mul_f32_e32 v50, v50, v110
	v_mul_f32_e32 v51, v51, v111
	ds_read_u16 v52, v79 offset:13056
	ds_read_u16 v53, v79 offset:13328
	ds_read_u16 v54, v79 offset:13600
	ds_read_u16 v55, v79 offset:13872
	ds_read_u16 v56, v79 offset:14144
	ds_read_u16 v57, v79 offset:14416
	ds_read_u16 v58, v79 offset:14688
	ds_read_u16 v59, v79 offset:14960
	ds_read_b128 v[88:91], v84 offset:192
	ds_read_b128 v[92:95], v84 offset:208
	ds_read_b128 v[96:99], v84 offset:448
	ds_read_b128 v[100:103], v84 offset:464
	s_waitcnt lgkmcnt(0)
	v_lshlrev_b32_e32 v52, 16, v52
	v_cndmask_b32_e32 v104, 1.0, v96, vcc
	v_lshlrev_b32_e32 v53, 16, v53
	v_cndmask_b32_e32 v105, 1.0, v97, vcc
	v_lshlrev_b32_e32 v54, 16, v54
	v_cndmask_b32_e32 v106, 1.0, v98, vcc
	v_lshlrev_b32_e32 v55, 16, v55
	v_cndmask_b32_e32 v107, 1.0, v99, vcc
	v_lshlrev_b32_e32 v56, 16, v56
	v_cndmask_b32_e32 v108, 1.0, v100, vcc
	v_lshlrev_b32_e32 v57, 16, v57
	v_cndmask_b32_e32 v109, 1.0, v101, vcc
	v_lshlrev_b32_e32 v58, 16, v58
	v_cndmask_b32_e32 v110, 1.0, v102, vcc
	v_lshlrev_b32_e32 v59, 16, v59
	v_cndmask_b32_e32 v111, 1.0, v103, vcc
	v_mul_f32_e32 v52, v88, v52
	v_mul_f32_e32 v53, v89, v53
	v_mul_f32_e32 v54, v90, v54
	v_mul_f32_e32 v55, v91, v55
	v_mul_f32_e32 v56, v92, v56
	v_mul_f32_e32 v57, v93, v57
	v_mul_f32_e32 v58, v94, v58
	v_mul_f32_e32 v59, v95, v59
	v_mul_f32_e32 v52, v52, v104
	v_mul_f32_e32 v53, v53, v105
	v_mul_f32_e32 v54, v54, v106
	v_mul_f32_e32 v55, v55, v107
	v_mul_f32_e32 v56, v56, v108
	v_mul_f32_e32 v57, v57, v109
	v_mul_f32_e32 v58, v58, v110
	v_mul_f32_e32 v59, v59, v111
	ds_read_u16 v60, v79 offset:15232
	ds_read_u16 v61, v79 offset:15504
	ds_read_u16 v62, v79 offset:15776
	ds_read_u16 v63, v79 offset:16048
	ds_read_u16 v64, v79 offset:16320
	ds_read_u16 v65, v79 offset:16592
	ds_read_u16 v66, v79 offset:16864
	ds_read_u16 v67, v79 offset:17136
	ds_read_b128 v[88:91], v84 offset:224
	ds_read_b128 v[92:95], v84 offset:240
	ds_read_b128 v[96:99], v84 offset:480
	ds_read_b128 v[100:103], v84 offset:496
	s_waitcnt lgkmcnt(0)
; DI float bf2f(bf16_t v) { return __uint_as_float(((unsigned)v) << 16); }
; DI void gdn_prep(const Params& p, int item, unsigned char* smem) {
;     ...
;         for (int i = 0; i < 64; ++i) { float a = bf2f(src[i * 136]) * sbeta[i]; if (tid >= 128) a *= segc[i]; X[i] = a; }
; #pragma unroll
;         for (int i = 1; i < 64; ++i) {
;             float a = X[i];
;             int dep; asm volatile("v_and_b32 %0, 0, %1" : "=v"(dep) : "v"(X[i - 1]));
;             const float* Lr = sL + i * 68 + dep;
;             float b0 = 0.f, b1 = 0.f, b2 = 0.f;
; #pragma unroll
;             for (int j4 = 0; j4 < (i + 3) / 4; ++j4) {
;                 const f32x4 l = *(const f32x4*)(Lr + 4 * j4);
;                 if (4 * j4 + 0 < i) a -= l.x * X[4 * j4 + 0];
;                 if (4 * j4 + 1 < i) b0 -= l.y * X[4 * j4 + 1];
;                 if (4 * j4 + 2 < i) b1 -= l.z * X[4 * j4 + 2];
;                 if (4 * j4 + 3 < i) b2 -= l.w * X[4 * j4 + 3];
;             }
;             X[i] = (a + b0) + (b1 + b2);
	v_lshlrev_b32_e32 v60, 16, v60
	v_cndmask_b32_e32 v104, 1.0, v96, vcc
	v_lshlrev_b32_e32 v61, 16, v61
	v_cndmask_b32_e32 v105, 1.0, v97, vcc
	v_lshlrev_b32_e32 v62, 16, v62
	v_cndmask_b32_e32 v106, 1.0, v98, vcc
	v_lshlrev_b32_e32 v63, 16, v63
	v_cndmask_b32_e32 v107, 1.0, v99, vcc
	v_lshlrev_b32_e32 v64, 16, v64
	v_cndmask_b32_e32 v108, 1.0, v100, vcc
	v_lshlrev_b32_e32 v65, 16, v65
	v_cndmask_b32_e32 v109, 1.0, v101, vcc
	v_lshlrev_b32_e32 v66, 16, v66
	v_cndmask_b32_e32 v110, 1.0, v102, vcc
	v_lshlrev_b32_e32 v67, 16, v67
	v_cndmask_b32_e32 v111, 1.0, v103, vcc
	v_mul_f32_e32 v60, v88, v60
	v_mul_f32_e32 v61, v89, v61
	v_mul_f32_e32 v62, v90, v62
	v_mul_f32_e32 v63, v91, v63
	v_mul_f32_e32 v64, v92, v64
	v_mul_f32_e32 v65, v93, v65
	v_mul_f32_e32 v66, v94, v66
	v_mul_f32_e32 v67, v95, v67
	v_mul_f32_e32 v60, v60, v104
	v_mul_f32_e32 v61, v61, v105
	v_mul_f32_e32 v62, v62, v106
	v_mul_f32_e32 v63, v63, v107
	v_mul_f32_e32 v64, v64, v108
	v_mul_f32_e32 v65, v65, v109
	v_mul_f32_e32 v66, v66, v110
	v_mul_f32_e32 v67, v67, v111
	v_mov_b32_e32 v78, s10
	v_add_u32_e32 v78, 0xcc00, v78
	ds_read_b128 v[84:87], v78 offset:272
	ds_read_b128 v[88:91], v78 offset:544
	ds_read_b128 v[92:95], v78 offset:816
	ds_read_b128 v[96:99], v78 offset:1088
	ds_read_b128 v[100:103], v78 offset:1360
	ds_read_b128 v[104:107], v78 offset:1376
	ds_read_b128 v[108:111], v78 offset:1632
	s_waitcnt lgkmcnt(6)
	v_mov_b32_e32 v69, v84
	ds_read_b128 v[84:87], v78 offset:1648
	s_waitcnt lgkmcnt(6)
	v_fma_f32 v70, -v0, v88, 0
	v_mov_b32_e32 v68, v89
	v_fma_f32 v74, -v0, v69, 0
	ds_read_b128 v[88:91], v78 offset:1904
	v_add_f32_e32 v1, v1, v74
	s_waitcnt lgkmcnt(6)
	v_pk_fma_f32 v[74:75], v[92:93], v[0:1], 0 neg_lo:[1,0,0] neg_hi:[1,0,0]
	v_mov_b32_e32 v69, v94
	v_fma_f32 v71, -v1, v68, 0
	ds_read_b128 v[92:95], v78 offset:1920
	v_add_f32_e32 v70, v70, v71
	v_add_f32_e32 v2, v2, v70
	s_waitcnt lgkmcnt(6)
	v_pk_fma_f32 v[70:71], v[96:97], v[0:1], 0 neg_lo:[1,0,0] neg_hi:[1,0,0]
	v_fma_f32 v72, -v2, v98, 0
	v_fma_f32 v76, -v2, v69, 0
	v_mov_b32_e32 v68, v99
	ds_read_b128 v[96:99], v78 offset:2176
	v_add_f32_e32 v74, v74, v75
	v_add_f32_e32 v74, v74, v76
	v_add_f32_e32 v3, v3, v74
	s_waitcnt lgkmcnt(6)
	v_pk_fma_f32 v[74:75], v[100:101], v[0:1], 0 neg_lo:[1,0,0] neg_hi:[1,0,0]
	v_pk_fma_f32 v[76:77], v[102:103], v[2:3], 0 neg_lo:[1,0,0] neg_hi:[1,0,0]
	v_fma_f32 v73, -v3, v68, 0
	ds_read_b128 v[100:103], v78 offset:2192
	s_waitcnt lgkmcnt(6)
	v_mov_b32_e32 v69, v104
	ds_read_b128 v[104:107], v78 offset:2448
	v_add_f32_e32 v70, v70, v71
	v_add_f32_e32 v72, v72, v73
	v_add_f32_e32 v70, v70, v72
	v_add_f32_e32 v4, v4, v70
	s_waitcnt lgkmcnt(6)
	v_pk_fma_f32 v[70:71], v[108:109], v[0:1], 0 neg_lo:[1,0,0] neg_hi:[1,0,0]
	v_pk_fma_f32 v[72:73], v[110:111], v[2:3], 0 neg_lo:[1,0,0] neg_hi:[1,0,0]
	v_fma_f32 v74, -v4, v69, v74
	ds_read_b128 v[108:111], v78 offset:2464
	s_waitcnt lgkmcnt(6)
	v_fma_f32 v70, -v4, v84, v70
	v_mov_b32_e32 v68, v85
	v_add_f32_e32 v74, v74, v75
	ds_read_b128 v[84:87], v78 offset:2480
	v_add_f32_e32 v76, v76, v77
	v_add_f32_e32 v74, v74, v76
	v_add_f32_e32 v5, v5, v74
	s_waitcnt lgkmcnt(6)
	v_pk_fma_f32 v[74:75], v[88:89], v[0:1], 0 neg_lo:[1,0,0] neg_hi:[1,0,0]
	v_pk_fma_f32 v[76:77], v[90:91], v[2:3], 0 neg_lo:[1,0,0] neg_hi:[1,0,0]
	v_fma_f32 v71, -v5, v68, v71
	ds_read_b128 v[88:91], v78 offset:2720
	s_waitcnt lgkmcnt(6)
	v_pk_fma_f32 v[74:75], v[92:93], v[4:5], v[74:75] neg_lo:[1,0,0] neg_hi:[1,0,0]
	v_mov_b32_e32 v69, v94
	v_add_f32_e32 v70, v70, v71
	ds_read_b128 v[92:95], v78 offset:2736
	v_add_f32_e32 v72, v72, v73
	v_add_f32_e32 v70, v70, v72
	v_add_f32_e32 v6, v6, v70
	s_waitcnt lgkmcnt(6)
	v_pk_fma_f32 v[70:71], v[96:97], v[0:1], 0 neg_lo:[1,0,0] neg_hi:[1,0,0]
	v_pk_fma_f32 v[72:73], v[98:99], v[2:3], 0 neg_lo:[1,0,0] neg_hi:[1,0,0]
	v_fma_f32 v76, -v6, v69, v76
	ds_read_b128 v[96:99], v78 offset:2752
	s_waitcnt lgkmcnt(6)
	v_pk_fma_f32 v[70:71], v[100:101], v[4:5], v[70:71] neg_lo:[1,0,0] neg_hi:[1,0,0]
	v_fma_f32 v72, -v6, v102, v72
	v_add_f32_e32 v74, v74, v75
	v_mov_b32_e32 v68, v103
	ds_read_b128 v[100:103], v78 offset:2992
	v_add_f32_e32 v76, v76, v77
	v_add_f32_e32 v74, v74, v76
	v_add_f32_e32 v7, v7, v74
	s_waitcnt lgkmcnt(6)
	v_pk_fma_f32 v[74:75], v[104:105], v[0:1], 0 neg_lo:[1,0,0] neg_hi:[1,0,0]
	v_pk_fma_f32 v[76:77], v[106:107], v[2:3], 0 neg_lo:[1,0,0] neg_hi:[1,0,0]
	v_fma_f32 v73, -v7, v68, v73
	ds_read_b128 v[104:107], v78 offset:3008
	s_waitcnt lgkmcnt(6)
	v_pk_fma_f32 v[74:75], v[108:109], v[4:5], v[74:75] neg_lo:[1,0,0] neg_hi:[1,0,0]
	v_pk_fma_f32 v[76:77], v[110:111], v[6:7], v[76:77] neg_lo:[1,0,0] neg_hi:[1,0,0]
	v_add_f32_e32 v70, v70, v71
	ds_read_b128 v[108:111], v78 offset:3024
	s_waitcnt lgkmcnt(6)
	v_mov_b32_e32 v69, v84
	ds_read_b128 v[84:87], v78 offset:3264
	v_add_f32_e32 v72, v72, v73
	v_add_f32_e32 v70, v70, v72
	v_add_f32_e32 v8, v8, v70
	s_waitcnt lgkmcnt(6)
	v_pk_fma_f32 v[70:71], v[88:89], v[0:1], 0 neg_lo:[1,0,0] neg_hi:[1,0,0]
	v_pk_fma_f32 v[72:73], v[90:91], v[2:3], 0 neg_lo:[1,0,0] neg_hi:[1,0,0]
	v_fma_f32 v74, -v8, v69, v74
	ds_read_b128 v[88:91], v78 offset:3280
	s_waitcnt lgkmcnt(6)
	v_pk_fma_f32 v[70:71], v[92:93], v[4:5], v[70:71] neg_lo:[1,0,0] neg_hi:[1,0,0]
	v_pk_fma_f32 v[72:73], v[94:95], v[6:7], v[72:73] neg_lo:[1,0,0] neg_hi:[1,0,0]
	v_add_f32_e32 v74, v74, v75
	ds_read_b128 v[92:95], v78 offset:3296
	s_waitcnt lgkmcnt(6)
	v_fma_f32 v70, -v8, v96, v70
	v_mov_b32_e32 v68, v97
	v_add_f32_e32 v76, v76, v77
	ds_read_b128 v[96:99], v78 offset:3536
	v_add_f32_e32 v74, v74, v76
	v_add_f32_e32 v9, v9, v74
	s_waitcnt lgkmcnt(6)
; DI void gdn_prep(const Params& p, int item, unsigned char* smem) {
;     ...
; #pragma unroll
;         for (int i = 1; i < 64; ++i) {
;             float a = X[i];
;             int dep; asm volatile("v_and_b32 %0, 0, %1" : "=v"(dep) : "v"(X[i - 1]));
;             const float* Lr = sL + i * 68 + dep;
;             float b0 = 0.f, b1 = 0.f, b2 = 0.f;
; #pragma unroll
;             for (int j4 = 0; j4 < (i + 3) / 4; ++j4) {
;                 const f32x4 l = *(const f32x4*)(Lr + 4 * j4);
;                 if (4 * j4 + 0 < i) a -= l.x * X[4 * j4 + 0];
;                 if (4 * j4 + 1 < i) b0 -= l.y * X[4 * j4 + 1];
;                 if (4 * j4 + 2 < i) b1 -= l.z * X[4 * j4 + 2];
;                 if (4 * j4 + 3 < i) b2 -= l.w * X[4 * j4 + 3];
;             }
;             X[i] = (a + b0) + (b1 + b2);
	v_pk_fma_f32 v[74:75], v[100:101], v[0:1], 0 neg_lo:[1,0,0] neg_hi:[1,0,0]
	v_pk_fma_f32 v[76:77], v[102:103], v[2:3], 0 neg_lo:[1,0,0] neg_hi:[1,0,0]
	v_fma_f32 v71, -v9, v68, v71
	ds_read_b128 v[100:103], v78 offset:3552
	s_waitcnt lgkmcnt(6)
	v_pk_fma_f32 v[74:75], v[104:105], v[4:5], v[74:75] neg_lo:[1,0,0] neg_hi:[1,0,0]
	v_pk_fma_f32 v[76:77], v[106:107], v[6:7], v[76:77] neg_lo:[1,0,0] neg_hi:[1,0,0]
	v_add_f32_e32 v70, v70, v71
	ds_read_b128 v[104:107], v78 offset:3568
	s_waitcnt lgkmcnt(6)
	v_pk_fma_f32 v[74:75], v[108:109], v[8:9], v[74:75] neg_lo:[1,0,0] neg_hi:[1,0,0]
	v_mov_b32_e32 v69, v110
	v_add_f32_e32 v72, v72, v73
	ds_read_b128 v[108:111], v78 offset:3584
	v_add_f32_e32 v70, v70, v72
	v_add_f32_e32 v10, v10, v70
	s_waitcnt lgkmcnt(6)
	v_pk_fma_f32 v[70:71], v[84:85], v[0:1], 0 neg_lo:[1,0,0] neg_hi:[1,0,0]
	v_pk_fma_f32 v[72:73], v[86:87], v[2:3], 0 neg_lo:[1,0,0] neg_hi:[1,0,0]
	v_fma_f32 v76, -v10, v69, v76
	ds_read_b128 v[84:87], v78 offset:3808
	s_waitcnt lgkmcnt(6)
	v_pk_fma_f32 v[70:71], v[88:89], v[4:5], v[70:71] neg_lo:[1,0,0] neg_hi:[1,0,0]
	v_pk_fma_f32 v[72:73], v[90:91], v[6:7], v[72:73] neg_lo:[1,0,0] neg_hi:[1,0,0]
	v_add_f32_e32 v74, v74, v75
	ds_read_b128 v[88:91], v78 offset:3824
	s_waitcnt lgkmcnt(6)
	v_pk_fma_f32 v[70:71], v[92:93], v[8:9], v[70:71] neg_lo:[1,0,0] neg_hi:[1,0,0]
	v_fma_f32 v72, -v10, v94, v72
	v_add_f32_e32 v76, v76, v77
	v_mov_b32_e32 v68, v95
	ds_read_b128 v[92:95], v78 offset:3840
	v_add_f32_e32 v74, v74, v76
	v_add_f32_e32 v11, v11, v74
	s_waitcnt lgkmcnt(6)
	v_pk_fma_f32 v[74:75], v[96:97], v[0:1], 0 neg_lo:[1,0,0] neg_hi:[1,0,0]
	v_pk_fma_f32 v[76:77], v[98:99], v[2:3], 0 neg_lo:[1,0,0] neg_hi:[1,0,0]
	v_fma_f32 v73, -v11, v68, v73
	ds_read_b128 v[96:99], v78 offset:3856
	s_waitcnt lgkmcnt(6)
	v_pk_fma_f32 v[74:75], v[100:101], v[4:5], v[74:75] neg_lo:[1,0,0] neg_hi:[1,0,0]
	v_pk_fma_f32 v[76:77], v[102:103], v[6:7], v[76:77] neg_lo:[1,0,0] neg_hi:[1,0,0]
	v_add_f32_e32 v70, v70, v71
	ds_read_b128 v[100:103], v78 offset:4080
	s_waitcnt lgkmcnt(6)
	v_pk_fma_f32 v[74:75], v[104:105], v[8:9], v[74:75] neg_lo:[1,0,0] neg_hi:[1,0,0]
	v_pk_fma_f32 v[76:77], v[106:107], v[10:11], v[76:77] neg_lo:[1,0,0] neg_hi:[1,0,0]
	v_add_f32_e32 v72, v72, v73
	ds_read_b128 v[104:107], v78 offset:4096
	s_waitcnt lgkmcnt(6)
	v_mov_b32_e32 v69, v108
	ds_read_b128 v[108:111], v78 offset:4112
	v_add_f32_e32 v70, v70, v72
	v_add_f32_e32 v12, v12, v70
	s_waitcnt lgkmcnt(6)
	v_pk_fma_f32 v[70:71], v[84:85], v[0:1], 0 neg_lo:[1,0,0] neg_hi:[1,0,0]
	v_pk_fma_f32 v[72:73], v[86:87], v[2:3], 0 neg_lo:[1,0,0] neg_hi:[1,0,0]
	v_fma_f32 v74, -v12, v69, v74
	ds_read_b128 v[84:87], v78 offset:4128
	s_waitcnt lgkmcnt(6)
	v_pk_fma_f32 v[70:71], v[88:89], v[4:5], v[70:71] neg_lo:[1,0,0] neg_hi:[1,0,0]
	v_pk_fma_f32 v[72:73], v[90:91], v[6:7], v[72:73] neg_lo:[1,0,0] neg_hi:[1,0,0]
	v_add_f32_e32 v74, v74, v75
	ds_read_b128 v[88:91], v78 offset:4352
	s_waitcnt lgkmcnt(6)
	v_pk_fma_f32 v[70:71], v[92:93], v[8:9], v[70:71] neg_lo:[1,0,0] neg_hi:[1,0,0]
	v_pk_fma_f32 v[72:73], v[94:95], v[10:11], v[72:73] neg_lo:[1,0,0] neg_hi:[1,0,0]
	v_add_f32_e32 v76, v76, v77
	ds_read_b128 v[92:95], v78 offset:4368
	s_waitcnt lgkmcnt(6)
	v_fma_f32 v70, -v12, v96, v70
	v_mov_b32_e32 v68, v97
	v_add_f32_e32 v74, v74, v76
	ds_read_b128 v[96:99], v78 offset:4384
	v_add_f32_e32 v13, v13, v74
	s_waitcnt lgkmcnt(6)
	v_pk_fma_f32 v[74:75], v[100:101], v[0:1], 0 neg_lo:[1,0,0] neg_hi:[1,0,0]
	v_pk_fma_f32 v[76:77], v[102:103], v[2:3], 0 neg_lo:[1,0,0] neg_hi:[1,0,0]
	v_fma_f32 v71, -v13, v68, v71
	ds_read_b128 v[100:103], v78 offset:4400
	s_waitcnt lgkmcnt(6)
	v_pk_fma_f32 v[74:75], v[104:105], v[4:5], v[74:75] neg_lo:[1,0,0] neg_hi:[1,0,0]
	v_pk_fma_f32 v[76:77], v[106:107], v[6:7], v[76:77] neg_lo:[1,0,0] neg_hi:[1,0,0]
	v_add_f32_e32 v70, v70, v71
	ds_read_b128 v[104:107], v78 offset:4624
	s_waitcnt lgkmcnt(6)
	v_pk_fma_f32 v[74:75], v[108:109], v[8:9], v[74:75] neg_lo:[1,0,0] neg_hi:[1,0,0]
	v_pk_fma_f32 v[76:77], v[110:111], v[10:11], v[76:77] neg_lo:[1,0,0] neg_hi:[1,0,0]
	v_add_f32_e32 v72, v72, v73
	ds_read_b128 v[108:111], v78 offset:4640
	s_waitcnt lgkmcnt(6)
	v_pk_fma_f32 v[74:75], v[84:85], v[12:13], v[74:75] neg_lo:[1,0,0] neg_hi:[1,0,0]
	v_mov_b32_e32 v69, v86
	v_add_f32_e32 v70, v70, v72
	ds_read_b128 v[84:87], v78 offset:4656
	v_add_f32_e32 v14, v14, v70
	s_waitcnt lgkmcnt(6)
	v_pk_fma_f32 v[70:71], v[88:89], v[0:1], 0 neg_lo:[1,0,0] neg_hi:[1,0,0]
	v_pk_fma_f32 v[72:73], v[90:91], v[2:3], 0 neg_lo:[1,0,0] neg_hi:[1,0,0]
	v_fma_f32 v76, -v14, v69, v76
	ds_read_b128 v[88:91], v78 offset:4672
	s_waitcnt lgkmcnt(6)
	v_pk_fma_f32 v[70:71], v[92:93], v[4:5], v[70:71] neg_lo:[1,0,0] neg_hi:[1,0,0]
	v_pk_fma_f32 v[72:73], v[94:95], v[6:7], v[72:73] neg_lo:[1,0,0] neg_hi:[1,0,0]
	v_add_f32_e32 v74, v74, v75
	ds_read_b128 v[92:95], v78 offset:4688
	s_waitcnt lgkmcnt(6)
	v_pk_fma_f32 v[70:71], v[96:97], v[8:9], v[70:71] neg_lo:[1,0,0] neg_hi:[1,0,0]
	v_pk_fma_f32 v[72:73], v[98:99], v[10:11], v[72:73] neg_lo:[1,0,0] neg_hi:[1,0,0]
	v_add_f32_e32 v76, v76, v77
	ds_read_b128 v[96:99], v78 offset:4896
	s_waitcnt lgkmcnt(6)
	v_pk_fma_f32 v[70:71], v[100:101], v[12:13], v[70:71] neg_lo:[1,0,0] neg_hi:[1,0,0]
	v_fma_f32 v72, -v14, v102, v72
	v_add_f32_e32 v74, v74, v76
	v_mov_b32_e32 v68, v103
	ds_read_b128 v[100:103], v78 offset:4912
	v_add_f32_e32 v15, v15, v74
	s_waitcnt lgkmcnt(6)
	v_pk_fma_f32 v[74:75], v[104:105], v[0:1], 0 neg_lo:[1,0,0] neg_hi:[1,0,0]
	v_pk_fma_f32 v[76:77], v[106:107], v[2:3], 0 neg_lo:[1,0,0] neg_hi:[1,0,0]
	v_fma_f32 v73, -v15, v68, v73
	ds_read_b128 v[104:107], v78 offset:4928
	s_waitcnt lgkmcnt(6)
; DI void gdn_prep(const Params& p, int item, unsigned char* smem) {
;     ...
; #pragma unroll
;         for (int i = 1; i < 64; ++i) {
;             float a = X[i];
;             int dep; asm volatile("v_and_b32 %0, 0, %1" : "=v"(dep) : "v"(X[i - 1]));
;             const float* Lr = sL + i * 68 + dep;
;             float b0 = 0.f, b1 = 0.f, b2 = 0.f;
; #pragma unroll
;             for (int j4 = 0; j4 < (i + 3) / 4; ++j4) {
;                 const f32x4 l = *(const f32x4*)(Lr + 4 * j4);
;                 if (4 * j4 + 0 < i) a -= l.x * X[4 * j4 + 0];
;                 if (4 * j4 + 1 < i) b0 -= l.y * X[4 * j4 + 1];
;                 if (4 * j4 + 2 < i) b1 -= l.z * X[4 * j4 + 2];
;                 if (4 * j4 + 3 < i) b2 -= l.w * X[4 * j4 + 3];
;             }
;             X[i] = (a + b0) + (b1 + b2);
	v_pk_fma_f32 v[74:75], v[108:109], v[4:5], v[74:75] neg_lo:[1,0,0] neg_hi:[1,0,0]
	v_pk_fma_f32 v[76:77], v[110:111], v[6:7], v[76:77] neg_lo:[1,0,0] neg_hi:[1,0,0]
	v_add_f32_e32 v70, v70, v71
	ds_read_b128 v[108:111], v78 offset:4944
	s_waitcnt lgkmcnt(6)
	v_pk_fma_f32 v[74:75], v[84:85], v[8:9], v[74:75] neg_lo:[1,0,0] neg_hi:[1,0,0]
	v_pk_fma_f32 v[76:77], v[86:87], v[10:11], v[76:77] neg_lo:[1,0,0] neg_hi:[1,0,0]
	v_add_f32_e32 v72, v72, v73
	ds_read_b128 v[84:87], v78 offset:4960
	s_waitcnt lgkmcnt(6)
	v_pk_fma_f32 v[74:75], v[88:89], v[12:13], v[74:75] neg_lo:[1,0,0] neg_hi:[1,0,0]
	v_pk_fma_f32 v[76:77], v[90:91], v[14:15], v[76:77] neg_lo:[1,0,0] neg_hi:[1,0,0]
	v_add_f32_e32 v70, v70, v72
	ds_read_b128 v[88:91], v78 offset:5168
	s_waitcnt lgkmcnt(6)
	v_mov_b32_e32 v69, v92
	ds_read_b128 v[92:95], v78 offset:5184
	v_add_f32_e32 v16, v16, v70
	s_waitcnt lgkmcnt(6)
	v_pk_fma_f32 v[70:71], v[96:97], v[0:1], 0 neg_lo:[1,0,0] neg_hi:[1,0,0]
	v_pk_fma_f32 v[72:73], v[98:99], v[2:3], 0 neg_lo:[1,0,0] neg_hi:[1,0,0]
	v_fma_f32 v74, -v16, v69, v74
	ds_read_b128 v[96:99], v78 offset:5200
	s_waitcnt lgkmcnt(6)
	v_pk_fma_f32 v[70:71], v[100:101], v[4:5], v[70:71] neg_lo:[1,0,0] neg_hi:[1,0,0]
	v_pk_fma_f32 v[72:73], v[102:103], v[6:7], v[72:73] neg_lo:[1,0,0] neg_hi:[1,0,0]
	v_add_f32_e32 v74, v74, v75
	ds_read_b128 v[100:103], v78 offset:5216
	s_waitcnt lgkmcnt(6)
	v_pk_fma_f32 v[70:71], v[104:105], v[8:9], v[70:71] neg_lo:[1,0,0] neg_hi:[1,0,0]
	v_pk_fma_f32 v[72:73], v[106:107], v[10:11], v[72:73] neg_lo:[1,0,0] neg_hi:[1,0,0]
	v_add_f32_e32 v76, v76, v77
	ds_read_b128 v[104:107], v78 offset:5232
	s_waitcnt lgkmcnt(6)
	v_pk_fma_f32 v[70:71], v[108:109], v[12:13], v[70:71] neg_lo:[1,0,0] neg_hi:[1,0,0]
	v_pk_fma_f32 v[72:73], v[110:111], v[14:15], v[72:73] neg_lo:[1,0,0] neg_hi:[1,0,0]
	v_add_f32_e32 v74, v74, v76
	ds_read_b128 v[108:111], v78 offset:5440
	s_waitcnt lgkmcnt(6)
	v_fma_f32 v70, -v16, v84, v70
	v_mov_b32_e32 v68, v85
	v_add_f32_e32 v17, v17, v74
	ds_read_b128 v[84:87], v78 offset:5456
	s_waitcnt lgkmcnt(6)
	v_pk_fma_f32 v[74:75], v[88:89], v[0:1], 0 neg_lo:[1,0,0] neg_hi:[1,0,0]
	v_pk_fma_f32 v[76:77], v[90:91], v[2:3], 0 neg_lo:[1,0,0] neg_hi:[1,0,0]
	v_fma_f32 v71, -v17, v68, v71
	ds_read_b128 v[88:91], v78 offset:5472
	s_waitcnt lgkmcnt(6)
	v_pk_fma_f32 v[74:75], v[92:93], v[4:5], v[74:75] neg_lo:[1,0,0] neg_hi:[1,0,0]
	v_pk_fma_f32 v[76:77], v[94:95], v[6:7], v[76:77] neg_lo:[1,0,0] neg_hi:[1,0,0]
	v_add_f32_e32 v70, v70, v71
	ds_read_b128 v[92:95], v78 offset:5488
	s_waitcnt lgkmcnt(6)
	v_pk_fma_f32 v[74:75], v[96:97], v[8:9], v[74:75] neg_lo:[1,0,0] neg_hi:[1,0,0]
	v_pk_fma_f32 v[76:77], v[98:99], v[10:11], v[76:77] neg_lo:[1,0,0] neg_hi:[1,0,0]
	v_add_f32_e32 v72, v72, v73
	ds_read_b128 v[96:99], v78 offset:5504
	s_waitcnt lgkmcnt(6)
	v_pk_fma_f32 v[74:75], v[100:101], v[12:13], v[74:75] neg_lo:[1,0,0] neg_hi:[1,0,0]
	v_pk_fma_f32 v[76:77], v[102:103], v[14:15], v[76:77] neg_lo:[1,0,0] neg_hi:[1,0,0]
	v_add_f32_e32 v70, v70, v72
	ds_read_b128 v[100:103], v78 offset:5712
	s_waitcnt lgkmcnt(6)
	v_pk_fma_f32 v[74:75], v[104:105], v[16:17], v[74:75] neg_lo:[1,0,0] neg_hi:[1,0,0]
	v_mov_b32_e32 v69, v106
	v_add_f32_e32 v18, v18, v70
	ds_read_b128 v[104:107], v78 offset:5728
	s_waitcnt lgkmcnt(6)
	v_pk_fma_f32 v[70:71], v[108:109], v[0:1], 0 neg_lo:[1,0,0] neg_hi:[1,0,0]
	v_pk_fma_f32 v[72:73], v[110:111], v[2:3], 0 neg_lo:[1,0,0] neg_hi:[1,0,0]
	v_fma_f32 v76, -v18, v69, v76
	ds_read_b128 v[108:111], v78 offset:5744
	s_waitcnt lgkmcnt(6)
	v_pk_fma_f32 v[70:71], v[84:85], v[4:5], v[70:71] neg_lo:[1,0,0] neg_hi:[1,0,0]
	v_pk_fma_f32 v[72:73], v[86:87], v[6:7], v[72:73] neg_lo:[1,0,0] neg_hi:[1,0,0]
	v_add_f32_e32 v74, v74, v75
	ds_read_b128 v[84:87], v78 offset:5760
	s_waitcnt lgkmcnt(6)
	v_pk_fma_f32 v[70:71], v[88:89], v[8:9], v[70:71] neg_lo:[1,0,0] neg_hi:[1,0,0]
	v_pk_fma_f32 v[72:73], v[90:91], v[10:11], v[72:73] neg_lo:[1,0,0] neg_hi:[1,0,0]
	v_add_f32_e32 v76, v76, v77
	ds_read_b128 v[88:91], v78 offset:5776
	s_waitcnt lgkmcnt(6)
	v_pk_fma_f32 v[70:71], v[92:93], v[12:13], v[70:71] neg_lo:[1,0,0] neg_hi:[1,0,0]
	v_pk_fma_f32 v[72:73], v[94:95], v[14:15], v[72:73] neg_lo:[1,0,0] neg_hi:[1,0,0]
	v_add_f32_e32 v74, v74, v76
	ds_read_b128 v[92:95], v78 offset:5792
	s_waitcnt lgkmcnt(6)
	v_pk_fma_f32 v[70:71], v[96:97], v[16:17], v[70:71] neg_lo:[1,0,0] neg_hi:[1,0,0]
	v_fma_f32 v72, -v18, v98, v72
	v_add_f32_e32 v19, v19, v74
	v_mov_b32_e32 v68, v99
	ds_read_b128 v[96:99], v78 offset:5984
	s_waitcnt lgkmcnt(6)
	v_pk_fma_f32 v[74:75], v[100:101], v[0:1], 0 neg_lo:[1,0,0] neg_hi:[1,0,0]
	v_pk_fma_f32 v[76:77], v[102:103], v[2:3], 0 neg_lo:[1,0,0] neg_hi:[1,0,0]
	v_fma_f32 v73, -v19, v68, v73
	ds_read_b128 v[100:103], v78 offset:6000
	s_waitcnt lgkmcnt(6)
	v_pk_fma_f32 v[74:75], v[104:105], v[4:5], v[74:75] neg_lo:[1,0,0] neg_hi:[1,0,0]
	v_pk_fma_f32 v[76:77], v[106:107], v[6:7], v[76:77] neg_lo:[1,0,0] neg_hi:[1,0,0]
	v_add_f32_e32 v70, v70, v71
	ds_read_b128 v[104:107], v78 offset:6016
	s_waitcnt lgkmcnt(6)
	v_pk_fma_f32 v[74:75], v[108:109], v[8:9], v[74:75] neg_lo:[1,0,0] neg_hi:[1,0,0]
	v_pk_fma_f32 v[76:77], v[110:111], v[10:11], v[76:77] neg_lo:[1,0,0] neg_hi:[1,0,0]
	v_add_f32_e32 v72, v72, v73
	ds_read_b128 v[108:111], v78 offset:6032
	s_waitcnt lgkmcnt(6)
	v_pk_fma_f32 v[74:75], v[84:85], v[12:13], v[74:75] neg_lo:[1,0,0] neg_hi:[1,0,0]
	v_pk_fma_f32 v[76:77], v[86:87], v[14:15], v[76:77] neg_lo:[1,0,0] neg_hi:[1,0,0]
	v_add_f32_e32 v70, v70, v72
	ds_read_b128 v[84:87], v78 offset:6048
	s_waitcnt lgkmcnt(6)
; DI void gdn_prep(const Params& p, int item, unsigned char* smem) {
;     ...
; #pragma unroll
;         for (int i = 1; i < 64; ++i) {
;             float a = X[i];
;             int dep; asm volatile("v_and_b32 %0, 0, %1" : "=v"(dep) : "v"(X[i - 1]));
;             const float* Lr = sL + i * 68 + dep;
;             float b0 = 0.f, b1 = 0.f, b2 = 0.f;
; #pragma unroll
;             for (int j4 = 0; j4 < (i + 3) / 4; ++j4) {
;                 const f32x4 l = *(const f32x4*)(Lr + 4 * j4);
;                 if (4 * j4 + 0 < i) a -= l.x * X[4 * j4 + 0];
;                 if (4 * j4 + 1 < i) b0 -= l.y * X[4 * j4 + 1];
;                 if (4 * j4 + 2 < i) b1 -= l.z * X[4 * j4 + 2];
;                 if (4 * j4 + 3 < i) b2 -= l.w * X[4 * j4 + 3];
;             }
;             X[i] = (a + b0) + (b1 + b2);
	v_pk_fma_f32 v[74:75], v[88:89], v[16:17], v[74:75] neg_lo:[1,0,0] neg_hi:[1,0,0]
	v_pk_fma_f32 v[76:77], v[90:91], v[18:19], v[76:77] neg_lo:[1,0,0] neg_hi:[1,0,0]
	v_add_f32_e32 v20, v20, v70
	ds_read_b128 v[88:91], v78 offset:6064
	s_waitcnt lgkmcnt(6)
	v_mov_b32_e32 v69, v92
	ds_read_b128 v[92:95], v78 offset:6256
	s_waitcnt lgkmcnt(6)
	v_pk_fma_f32 v[70:71], v[96:97], v[0:1], 0 neg_lo:[1,0,0] neg_hi:[1,0,0]
	v_pk_fma_f32 v[72:73], v[98:99], v[2:3], 0 neg_lo:[1,0,0] neg_hi:[1,0,0]
	v_fma_f32 v74, -v20, v69, v74
	ds_read_b128 v[96:99], v78 offset:6272
	s_waitcnt lgkmcnt(6)
	v_pk_fma_f32 v[70:71], v[100:101], v[4:5], v[70:71] neg_lo:[1,0,0] neg_hi:[1,0,0]
	v_pk_fma_f32 v[72:73], v[102:103], v[6:7], v[72:73] neg_lo:[1,0,0] neg_hi:[1,0,0]
	v_add_f32_e32 v74, v74, v75
	ds_read_b128 v[100:103], v78 offset:6288
	s_waitcnt lgkmcnt(6)
	v_pk_fma_f32 v[70:71], v[104:105], v[8:9], v[70:71] neg_lo:[1,0,0] neg_hi:[1,0,0]
	v_pk_fma_f32 v[72:73], v[106:107], v[10:11], v[72:73] neg_lo:[1,0,0] neg_hi:[1,0,0]
	v_add_f32_e32 v76, v76, v77
	ds_read_b128 v[104:107], v78 offset:6304
	s_waitcnt lgkmcnt(6)
	v_pk_fma_f32 v[70:71], v[108:109], v[12:13], v[70:71] neg_lo:[1,0,0] neg_hi:[1,0,0]
	v_pk_fma_f32 v[72:73], v[110:111], v[14:15], v[72:73] neg_lo:[1,0,0] neg_hi:[1,0,0]
	v_add_f32_e32 v74, v74, v76
	ds_read_b128 v[108:111], v78 offset:6320
	s_waitcnt lgkmcnt(6)
	v_pk_fma_f32 v[70:71], v[84:85], v[16:17], v[70:71] neg_lo:[1,0,0] neg_hi:[1,0,0]
	v_pk_fma_f32 v[72:73], v[86:87], v[18:19], v[72:73] neg_lo:[1,0,0] neg_hi:[1,0,0]
	v_add_f32_e32 v21, v21, v74
	ds_read_b128 v[84:87], v78 offset:6336
	s_waitcnt lgkmcnt(6)
	v_fma_f32 v70, -v20, v88, v70
	v_mov_b32_e32 v68, v89
	ds_read_b128 v[88:91], v78 offset:6528
	s_waitcnt lgkmcnt(6)
	v_pk_fma_f32 v[74:75], v[92:93], v[0:1], 0 neg_lo:[1,0,0] neg_hi:[1,0,0]
	v_pk_fma_f32 v[76:77], v[94:95], v[2:3], 0 neg_lo:[1,0,0] neg_hi:[1,0,0]
	v_fma_f32 v71, -v21, v68, v71
	ds_read_b128 v[92:95], v78 offset:6544
	s_waitcnt lgkmcnt(6)
	v_pk_fma_f32 v[74:75], v[96:97], v[4:5], v[74:75] neg_lo:[1,0,0] neg_hi:[1,0,0]
	v_pk_fma_f32 v[76:77], v[98:99], v[6:7], v[76:77] neg_lo:[1,0,0] neg_hi:[1,0,0]
	v_add_f32_e32 v70, v70, v71
	ds_read_b128 v[96:99], v78 offset:6560
	s_waitcnt lgkmcnt(6)
	v_pk_fma_f32 v[74:75], v[100:101], v[8:9], v[74:75] neg_lo:[1,0,0] neg_hi:[1,0,0]
	v_pk_fma_f32 v[76:77], v[102:103], v[10:11], v[76:77] neg_lo:[1,0,0] neg_hi:[1,0,0]
	v_add_f32_e32 v72, v72, v73
	ds_read_b128 v[100:103], v78 offset:6576
	s_waitcnt lgkmcnt(6)
	v_pk_fma_f32 v[74:75], v[104:105], v[12:13], v[74:75] neg_lo:[1,0,0] neg_hi:[1,0,0]
	v_pk_fma_f32 v[76:77], v[106:107], v[14:15], v[76:77] neg_lo:[1,0,0] neg_hi:[1,0,0]
	v_add_f32_e32 v70, v70, v72
	ds_read_b128 v[104:107], v78 offset:6592
	s_waitcnt lgkmcnt(6)
	v_pk_fma_f32 v[74:75], v[108:109], v[16:17], v[74:75] neg_lo:[1,0,0] neg_hi:[1,0,0]
	v_pk_fma_f32 v[76:77], v[110:111], v[18:19], v[76:77] neg_lo:[1,0,0] neg_hi:[1,0,0]
	v_add_f32_e32 v22, v22, v70
	ds_read_b128 v[108:111], v78 offset:6608
	s_waitcnt lgkmcnt(6)
	v_pk_fma_f32 v[74:75], v[84:85], v[20:21], v[74:75] neg_lo:[1,0,0] neg_hi:[1,0,0]
	v_mov_b32_e32 v69, v86
	ds_read_b128 v[84:87], v78 offset:6800
	s_waitcnt lgkmcnt(6)
	v_pk_fma_f32 v[70:71], v[88:89], v[0:1], 0 neg_lo:[1,0,0] neg_hi:[1,0,0]
	v_pk_fma_f32 v[72:73], v[90:91], v[2:3], 0 neg_lo:[1,0,0] neg_hi:[1,0,0]
	v_fma_f32 v76, -v22, v69, v76
	ds_read_b128 v[88:91], v78 offset:6816
	s_waitcnt lgkmcnt(6)
	v_pk_fma_f32 v[70:71], v[92:93], v[4:5], v[70:71] neg_lo:[1,0,0] neg_hi:[1,0,0]
	v_pk_fma_f32 v[72:73], v[94:95], v[6:7], v[72:73] neg_lo:[1,0,0] neg_hi:[1,0,0]
	v_add_f32_e32 v74, v74, v75
	ds_read_b128 v[92:95], v78 offset:6832
	s_waitcnt lgkmcnt(6)
	v_pk_fma_f32 v[70:71], v[96:97], v[8:9], v[70:71] neg_lo:[1,0,0] neg_hi:[1,0,0]
	v_pk_fma_f32 v[72:73], v[98:99], v[10:11], v[72:73] neg_lo:[1,0,0] neg_hi:[1,0,0]
	v_add_f32_e32 v76, v76, v77
	ds_read_b128 v[96:99], v78 offset:6848
	s_waitcnt lgkmcnt(6)
	v_pk_fma_f32 v[70:71], v[100:101], v[12:13], v[70:71] neg_lo:[1,0,0] neg_hi:[1,0,0]
	v_pk_fma_f32 v[72:73], v[102:103], v[14:15], v[72:73] neg_lo:[1,0,0] neg_hi:[1,0,0]
	v_add_f32_e32 v74, v74, v76
	ds_read_b128 v[100:103], v78 offset:6864
	s_waitcnt lgkmcnt(6)
	v_pk_fma_f32 v[70:71], v[104:105], v[16:17], v[70:71] neg_lo:[1,0,0] neg_hi:[1,0,0]
	v_pk_fma_f32 v[72:73], v[106:107], v[18:19], v[72:73] neg_lo:[1,0,0] neg_hi:[1,0,0]
	v_add_f32_e32 v23, v23, v74
	ds_read_b128 v[104:107], v78 offset:6880
	s_waitcnt lgkmcnt(6)
	v_pk_fma_f32 v[70:71], v[108:109], v[20:21], v[70:71] neg_lo:[1,0,0] neg_hi:[1,0,0]
	v_fma_f32 v72, -v22, v110, v72
	v_mov_b32_e32 v68, v111
	ds_read_b128 v[108:111], v78 offset:6896
	s_waitcnt lgkmcnt(6)
	v_pk_fma_f32 v[74:75], v[84:85], v[0:1], 0 neg_lo:[1,0,0] neg_hi:[1,0,0]
	v_pk_fma_f32 v[76:77], v[86:87], v[2:3], 0 neg_lo:[1,0,0] neg_hi:[1,0,0]
	v_fma_f32 v73, -v23, v68, v73
	ds_read_b128 v[84:87], v78 offset:7072
	s_waitcnt lgkmcnt(6)
	v_pk_fma_f32 v[74:75], v[88:89], v[4:5], v[74:75] neg_lo:[1,0,0] neg_hi:[1,0,0]
	v_pk_fma_f32 v[76:77], v[90:91], v[6:7], v[76:77] neg_lo:[1,0,0] neg_hi:[1,0,0]
	v_add_f32_e32 v70, v70, v71
	ds_read_b128 v[88:91], v78 offset:7088
	s_waitcnt lgkmcnt(6)
	v_pk_fma_f32 v[74:75], v[92:93], v[8:9], v[74:75] neg_lo:[1,0,0] neg_hi:[1,0,0]
	v_pk_fma_f32 v[76:77], v[94:95], v[10:11], v[76:77] neg_lo:[1,0,0] neg_hi:[1,0,0]
	v_add_f32_e32 v72, v72, v73
	ds_read_b128 v[92:95], v78 offset:7104
	s_waitcnt lgkmcnt(6)
	v_pk_fma_f32 v[74:75], v[96:97], v[12:13], v[74:75] neg_lo:[1,0,0] neg_hi:[1,0,0]
	v_pk_fma_f32 v[76:77], v[98:99], v[14:15], v[76:77] neg_lo:[1,0,0] neg_hi:[1,0,0]
	v_add_f32_e32 v70, v70, v72
	ds_read_b128 v[96:99], v78 offset:7120
	s_waitcnt lgkmcnt(6)
; DI void gdn_prep(const Params& p, int item, unsigned char* smem) {
;     ...
; #pragma unroll
;         for (int i = 1; i < 64; ++i) {
;             float a = X[i];
;             int dep; asm volatile("v_and_b32 %0, 0, %1" : "=v"(dep) : "v"(X[i - 1]));
;             const float* Lr = sL + i * 68 + dep;
;             float b0 = 0.f, b1 = 0.f, b2 = 0.f;
; #pragma unroll
;             for (int j4 = 0; j4 < (i + 3) / 4; ++j4) {
;                 const f32x4 l = *(const f32x4*)(Lr + 4 * j4);
;                 if (4 * j4 + 0 < i) a -= l.x * X[4 * j4 + 0];
;                 if (4 * j4 + 1 < i) b0 -= l.y * X[4 * j4 + 1];
;                 if (4 * j4 + 2 < i) b1 -= l.z * X[4 * j4 + 2];
;                 if (4 * j4 + 3 < i) b2 -= l.w * X[4 * j4 + 3];
;             }
;             X[i] = (a + b0) + (b1 + b2);
	v_pk_fma_f32 v[74:75], v[100:101], v[16:17], v[74:75] neg_lo:[1,0,0] neg_hi:[1,0,0]
	v_pk_fma_f32 v[76:77], v[102:103], v[18:19], v[76:77] neg_lo:[1,0,0] neg_hi:[1,0,0]
	v_add_f32_e32 v24, v24, v70
	ds_read_b128 v[100:103], v78 offset:7136
	s_waitcnt lgkmcnt(6)
	v_pk_fma_f32 v[74:75], v[104:105], v[20:21], v[74:75] neg_lo:[1,0,0] neg_hi:[1,0,0]
	v_pk_fma_f32 v[76:77], v[106:107], v[22:23], v[76:77] neg_lo:[1,0,0] neg_hi:[1,0,0]
	ds_read_b128 v[104:107], v78 offset:7152
	s_waitcnt lgkmcnt(6)
	v_mov_b32_e32 v69, v108
	ds_read_b128 v[108:111], v78 offset:7168
	s_waitcnt lgkmcnt(6)
	v_pk_fma_f32 v[70:71], v[84:85], v[0:1], 0 neg_lo:[1,0,0] neg_hi:[1,0,0]
	v_pk_fma_f32 v[72:73], v[86:87], v[2:3], 0 neg_lo:[1,0,0] neg_hi:[1,0,0]
	v_fma_f32 v74, -v24, v69, v74
	ds_read_b128 v[84:87], v78 offset:7344
	s_waitcnt lgkmcnt(6)
	v_pk_fma_f32 v[70:71], v[88:89], v[4:5], v[70:71] neg_lo:[1,0,0] neg_hi:[1,0,0]
	v_pk_fma_f32 v[72:73], v[90:91], v[6:7], v[72:73] neg_lo:[1,0,0] neg_hi:[1,0,0]
	v_add_f32_e32 v74, v74, v75
	ds_read_b128 v[88:91], v78 offset:7360
	s_waitcnt lgkmcnt(6)
	v_pk_fma_f32 v[70:71], v[92:93], v[8:9], v[70:71] neg_lo:[1,0,0] neg_hi:[1,0,0]
	v_pk_fma_f32 v[72:73], v[94:95], v[10:11], v[72:73] neg_lo:[1,0,0] neg_hi:[1,0,0]
	v_add_f32_e32 v76, v76, v77
	ds_read_b128 v[92:95], v78 offset:7376
	s_waitcnt lgkmcnt(6)
	v_pk_fma_f32 v[70:71], v[96:97], v[12:13], v[70:71] neg_lo:[1,0,0] neg_hi:[1,0,0]
	v_pk_fma_f32 v[72:73], v[98:99], v[14:15], v[72:73] neg_lo:[1,0,0] neg_hi:[1,0,0]
	v_add_f32_e32 v74, v74, v76
	ds_read_b128 v[96:99], v78 offset:7392
	s_waitcnt lgkmcnt(6)
	v_pk_fma_f32 v[70:71], v[100:101], v[16:17], v[70:71] neg_lo:[1,0,0] neg_hi:[1,0,0]
	v_pk_fma_f32 v[72:73], v[102:103], v[18:19], v[72:73] neg_lo:[1,0,0] neg_hi:[1,0,0]
	v_add_f32_e32 v25, v25, v74
	ds_read_b128 v[100:103], v78 offset:7408
	s_waitcnt lgkmcnt(6)
	v_pk_fma_f32 v[70:71], v[104:105], v[20:21], v[70:71] neg_lo:[1,0,0] neg_hi:[1,0,0]
	v_pk_fma_f32 v[72:73], v[106:107], v[22:23], v[72:73] neg_lo:[1,0,0] neg_hi:[1,0,0]
	ds_read_b128 v[104:107], v78 offset:7424
	s_waitcnt lgkmcnt(6)
	v_fma_f32 v70, -v24, v108, v70
	v_mov_b32_e32 v68, v109
	ds_read_b128 v[108:111], v78 offset:7440
	s_waitcnt lgkmcnt(6)
	v_pk_fma_f32 v[74:75], v[84:85], v[0:1], 0 neg_lo:[1,0,0] neg_hi:[1,0,0]
	v_pk_fma_f32 v[76:77], v[86:87], v[2:3], 0 neg_lo:[1,0,0] neg_hi:[1,0,0]
	v_fma_f32 v71, -v25, v68, v71
	ds_read_b128 v[84:87], v78 offset:7616
	s_waitcnt lgkmcnt(6)
	v_pk_fma_f32 v[74:75], v[88:89], v[4:5], v[74:75] neg_lo:[1,0,0] neg_hi:[1,0,0]
	v_pk_fma_f32 v[76:77], v[90:91], v[6:7], v[76:77] neg_lo:[1,0,0] neg_hi:[1,0,0]
	v_add_f32_e32 v70, v70, v71
	ds_read_b128 v[88:91], v78 offset:7632
	s_waitcnt lgkmcnt(6)
	v_pk_fma_f32 v[74:75], v[92:93], v[8:9], v[74:75] neg_lo:[1,0,0] neg_hi:[1,0,0]
	v_pk_fma_f32 v[76:77], v[94:95], v[10:11], v[76:77] neg_lo:[1,0,0] neg_hi:[1,0,0]
	v_add_f32_e32 v72, v72, v73
	ds_read_b128 v[92:95], v78 offset:7648
	s_waitcnt lgkmcnt(6)
	v_pk_fma_f32 v[74:75], v[96:97], v[12:13], v[74:75] neg_lo:[1,0,0] neg_hi:[1,0,0]
	v_pk_fma_f32 v[76:77], v[98:99], v[14:15], v[76:77] neg_lo:[1,0,0] neg_hi:[1,0,0]
	v_add_f32_e32 v70, v70, v72
	ds_read_b128 v[96:99], v78 offset:7664
	s_waitcnt lgkmcnt(6)
	v_pk_fma_f32 v[74:75], v[100:101], v[16:17], v[74:75] neg_lo:[1,0,0] neg_hi:[1,0,0]
	v_pk_fma_f32 v[76:77], v[102:103], v[18:19], v[76:77] neg_lo:[1,0,0] neg_hi:[1,0,0]
	v_add_f32_e32 v26, v26, v70
	ds_read_b128 v[100:103], v78 offset:7680
	s_waitcnt lgkmcnt(6)
	v_pk_fma_f32 v[74:75], v[104:105], v[20:21], v[74:75] neg_lo:[1,0,0] neg_hi:[1,0,0]
	v_pk_fma_f32 v[76:77], v[106:107], v[22:23], v[76:77] neg_lo:[1,0,0] neg_hi:[1,0,0]
	ds_read_b128 v[104:107], v78 offset:7696
	s_waitcnt lgkmcnt(6)
	v_pk_fma_f32 v[74:75], v[108:109], v[24:25], v[74:75] neg_lo:[1,0,0] neg_hi:[1,0,0]
	v_mov_b32_e32 v69, v110
	ds_read_b128 v[108:111], v78 offset:7712
	s_waitcnt lgkmcnt(6)
	v_pk_fma_f32 v[70:71], v[84:85], v[0:1], 0 neg_lo:[1,0,0] neg_hi:[1,0,0]
	v_pk_fma_f32 v[72:73], v[86:87], v[2:3], 0 neg_lo:[1,0,0] neg_hi:[1,0,0]
	v_fma_f32 v76, -v26, v69, v76
	ds_read_b128 v[84:87], v78 offset:7888
	s_waitcnt lgkmcnt(6)
	v_pk_fma_f32 v[70:71], v[88:89], v[4:5], v[70:71] neg_lo:[1,0,0] neg_hi:[1,0,0]
	v_pk_fma_f32 v[72:73], v[90:91], v[6:7], v[72:73] neg_lo:[1,0,0] neg_hi:[1,0,0]
	v_add_f32_e32 v74, v74, v75
	ds_read_b128 v[88:91], v78 offset:7904
	s_waitcnt lgkmcnt(6)
	v_pk_fma_f32 v[70:71], v[92:93], v[8:9], v[70:71] neg_lo:[1,0,0] neg_hi:[1,0,0]
	v_pk_fma_f32 v[72:73], v[94:95], v[10:11], v[72:73] neg_lo:[1,0,0] neg_hi:[1,0,0]
	v_add_f32_e32 v76, v76, v77
	ds_read_b128 v[92:95], v78 offset:7920
	s_waitcnt lgkmcnt(6)
	v_pk_fma_f32 v[70:71], v[96:97], v[12:13], v[70:71] neg_lo:[1,0,0] neg_hi:[1,0,0]
	v_pk_fma_f32 v[72:73], v[98:99], v[14:15], v[72:73] neg_lo:[1,0,0] neg_hi:[1,0,0]
	v_add_f32_e32 v74, v74, v76
	ds_read_b128 v[96:99], v78 offset:7936
	s_waitcnt lgkmcnt(6)
	v_pk_fma_f32 v[70:71], v[100:101], v[16:17], v[70:71] neg_lo:[1,0,0] neg_hi:[1,0,0]
	v_pk_fma_f32 v[72:73], v[102:103], v[18:19], v[72:73] neg_lo:[1,0,0] neg_hi:[1,0,0]
	v_add_f32_e32 v27, v27, v74
	ds_read_b128 v[100:103], v78 offset:7952
	s_waitcnt lgkmcnt(6)
	v_pk_fma_f32 v[70:71], v[104:105], v[20:21], v[70:71] neg_lo:[1,0,0] neg_hi:[1,0,0]
	v_pk_fma_f32 v[72:73], v[106:107], v[22:23], v[72:73] neg_lo:[1,0,0] neg_hi:[1,0,0]
	ds_read_b128 v[104:107], v78 offset:7968
	s_waitcnt lgkmcnt(6)
	v_pk_fma_f32 v[70:71], v[108:109], v[24:25], v[70:71] neg_lo:[1,0,0] neg_hi:[1,0,0]
	v_fma_f32 v72, -v26, v110, v72
	v_mov_b32_e32 v68, v111
	ds_read_b128 v[108:111], v78 offset:7984
	s_waitcnt lgkmcnt(6)
; DI void gdn_prep(const Params& p, int item, unsigned char* smem) {
;     ...
; #pragma unroll
;         for (int i = 1; i < 64; ++i) {
;             float a = X[i];
;             int dep; asm volatile("v_and_b32 %0, 0, %1" : "=v"(dep) : "v"(X[i - 1]));
;             const float* Lr = sL + i * 68 + dep;
;             float b0 = 0.f, b1 = 0.f, b2 = 0.f;
; #pragma unroll
;             for (int j4 = 0; j4 < (i + 3) / 4; ++j4) {
;                 const f32x4 l = *(const f32x4*)(Lr + 4 * j4);
;                 if (4 * j4 + 0 < i) a -= l.x * X[4 * j4 + 0];
;                 if (4 * j4 + 1 < i) b0 -= l.y * X[4 * j4 + 1];
;                 if (4 * j4 + 2 < i) b1 -= l.z * X[4 * j4 + 2];
;                 if (4 * j4 + 3 < i) b2 -= l.w * X[4 * j4 + 3];
;             }
;             X[i] = (a + b0) + (b1 + b2);
	v_pk_fma_f32 v[74:75], v[84:85], v[0:1], 0 neg_lo:[1,0,0] neg_hi:[1,0,0]
	v_pk_fma_f32 v[76:77], v[86:87], v[2:3], 0 neg_lo:[1,0,0] neg_hi:[1,0,0]
	v_fma_f32 v73, -v27, v68, v73
	ds_read_b128 v[84:87], v78 offset:8000
	s_waitcnt lgkmcnt(6)
	v_pk_fma_f32 v[74:75], v[88:89], v[4:5], v[74:75] neg_lo:[1,0,0] neg_hi:[1,0,0]
	v_pk_fma_f32 v[76:77], v[90:91], v[6:7], v[76:77] neg_lo:[1,0,0] neg_hi:[1,0,0]
	v_add_f32_e32 v70, v70, v71
	ds_read_b128 v[88:91], v78 offset:8160
	s_waitcnt lgkmcnt(6)
	v_pk_fma_f32 v[74:75], v[92:93], v[8:9], v[74:75] neg_lo:[1,0,0] neg_hi:[1,0,0]
	v_pk_fma_f32 v[76:77], v[94:95], v[10:11], v[76:77] neg_lo:[1,0,0] neg_hi:[1,0,0]
	v_add_f32_e32 v72, v72, v73
	ds_read_b128 v[92:95], v78 offset:8176
	s_waitcnt lgkmcnt(6)
	v_pk_fma_f32 v[74:75], v[96:97], v[12:13], v[74:75] neg_lo:[1,0,0] neg_hi:[1,0,0]
	v_pk_fma_f32 v[76:77], v[98:99], v[14:15], v[76:77] neg_lo:[1,0,0] neg_hi:[1,0,0]
	v_add_f32_e32 v70, v70, v72
	ds_read_b128 v[96:99], v78 offset:8192
	s_waitcnt lgkmcnt(6)
	v_pk_fma_f32 v[74:75], v[100:101], v[16:17], v[74:75] neg_lo:[1,0,0] neg_hi:[1,0,0]
	v_pk_fma_f32 v[76:77], v[102:103], v[18:19], v[76:77] neg_lo:[1,0,0] neg_hi:[1,0,0]
	v_add_f32_e32 v28, v28, v70
	ds_read_b128 v[100:103], v78 offset:8208
	s_waitcnt lgkmcnt(6)
	v_pk_fma_f32 v[74:75], v[104:105], v[20:21], v[74:75] neg_lo:[1,0,0] neg_hi:[1,0,0]
	v_pk_fma_f32 v[76:77], v[106:107], v[22:23], v[76:77] neg_lo:[1,0,0] neg_hi:[1,0,0]
	ds_read_b128 v[104:107], v78 offset:8224
	s_waitcnt lgkmcnt(6)
	v_pk_fma_f32 v[74:75], v[108:109], v[24:25], v[74:75] neg_lo:[1,0,0] neg_hi:[1,0,0]
	v_pk_fma_f32 v[76:77], v[110:111], v[26:27], v[76:77] neg_lo:[1,0,0] neg_hi:[1,0,0]
	ds_read_b128 v[108:111], v78 offset:8240
	s_waitcnt lgkmcnt(6)
	v_mov_b32_e32 v69, v84
	ds_read_b128 v[84:87], v78 offset:8256
	s_waitcnt lgkmcnt(6)
	v_pk_fma_f32 v[70:71], v[88:89], v[0:1], 0 neg_lo:[1,0,0] neg_hi:[1,0,0]
	v_pk_fma_f32 v[72:73], v[90:91], v[2:3], 0 neg_lo:[1,0,0] neg_hi:[1,0,0]
	v_fma_f32 v74, -v28, v69, v74
	ds_read_b128 v[88:91], v78 offset:8272
	s_waitcnt lgkmcnt(6)
	v_pk_fma_f32 v[70:71], v[92:93], v[4:5], v[70:71] neg_lo:[1,0,0] neg_hi:[1,0,0]
	v_pk_fma_f32 v[72:73], v[94:95], v[6:7], v[72:73] neg_lo:[1,0,0] neg_hi:[1,0,0]
	v_add_f32_e32 v74, v74, v75
	ds_read_b128 v[92:95], v78 offset:8432
	s_waitcnt lgkmcnt(6)
	v_pk_fma_f32 v[70:71], v[96:97], v[8:9], v[70:71] neg_lo:[1,0,0] neg_hi:[1,0,0]
	v_pk_fma_f32 v[72:73], v[98:99], v[10:11], v[72:73] neg_lo:[1,0,0] neg_hi:[1,0,0]
	v_add_f32_e32 v76, v76, v77
	ds_read_b128 v[96:99], v78 offset:8448
	s_waitcnt lgkmcnt(6)
	v_pk_fma_f32 v[70:71], v[100:101], v[12:13], v[70:71] neg_lo:[1,0,0] neg_hi:[1,0,0]
	v_pk_fma_f32 v[72:73], v[102:103], v[14:15], v[72:73] neg_lo:[1,0,0] neg_hi:[1,0,0]
	v_add_f32_e32 v74, v74, v76
	ds_read_b128 v[100:103], v78 offset:8464
	s_waitcnt lgkmcnt(6)
	v_pk_fma_f32 v[70:71], v[104:105], v[16:17], v[70:71] neg_lo:[1,0,0] neg_hi:[1,0,0]
	v_pk_fma_f32 v[72:73], v[106:107], v[18:19], v[72:73] neg_lo:[1,0,0] neg_hi:[1,0,0]
	v_add_f32_e32 v29, v29, v74
	ds_read_b128 v[104:107], v78 offset:8480
	s_waitcnt lgkmcnt(6)
	v_pk_fma_f32 v[70:71], v[108:109], v[20:21], v[70:71] neg_lo:[1,0,0] neg_hi:[1,0,0]
	v_pk_fma_f32 v[72:73], v[110:111], v[22:23], v[72:73] neg_lo:[1,0,0] neg_hi:[1,0,0]
	ds_read_b128 v[108:111], v78 offset:8496
	s_waitcnt lgkmcnt(6)
	v_pk_fma_f32 v[70:71], v[84:85], v[24:25], v[70:71] neg_lo:[1,0,0] neg_hi:[1,0,0]
	v_pk_fma_f32 v[72:73], v[86:87], v[26:27], v[72:73] neg_lo:[1,0,0] neg_hi:[1,0,0]
	ds_read_b128 v[84:87], v78 offset:8512
	s_waitcnt lgkmcnt(6)
	v_fma_f32 v70, -v28, v88, v70
	v_mov_b32_e32 v68, v89
	ds_read_b128 v[88:91], v78 offset:8528
	s_waitcnt lgkmcnt(6)
	v_pk_fma_f32 v[74:75], v[92:93], v[0:1], 0 neg_lo:[1,0,0] neg_hi:[1,0,0]
	v_pk_fma_f32 v[76:77], v[94:95], v[2:3], 0 neg_lo:[1,0,0] neg_hi:[1,0,0]
	v_fma_f32 v71, -v29, v68, v71
	ds_read_b128 v[92:95], v78 offset:8544
	s_waitcnt lgkmcnt(6)
	v_pk_fma_f32 v[74:75], v[96:97], v[4:5], v[74:75] neg_lo:[1,0,0] neg_hi:[1,0,0]
	v_pk_fma_f32 v[76:77], v[98:99], v[6:7], v[76:77] neg_lo:[1,0,0] neg_hi:[1,0,0]
	v_add_f32_e32 v70, v70, v71
	ds_read_b128 v[96:99], v78 offset:8704
	s_waitcnt lgkmcnt(6)
	v_pk_fma_f32 v[74:75], v[100:101], v[8:9], v[74:75] neg_lo:[1,0,0] neg_hi:[1,0,0]
	v_pk_fma_f32 v[76:77], v[102:103], v[10:11], v[76:77] neg_lo:[1,0,0] neg_hi:[1,0,0]
	v_add_f32_e32 v72, v72, v73
	ds_read_b128 v[100:103], v78 offset:8720
	s_waitcnt lgkmcnt(6)
	v_pk_fma_f32 v[74:75], v[104:105], v[12:13], v[74:75] neg_lo:[1,0,0] neg_hi:[1,0,0]
	v_pk_fma_f32 v[76:77], v[106:107], v[14:15], v[76:77] neg_lo:[1,0,0] neg_hi:[1,0,0]
	v_add_f32_e32 v70, v70, v72
	ds_read_b128 v[104:107], v78 offset:8736
	s_waitcnt lgkmcnt(6)
	v_pk_fma_f32 v[74:75], v[108:109], v[16:17], v[74:75] neg_lo:[1,0,0] neg_hi:[1,0,0]
	v_pk_fma_f32 v[76:77], v[110:111], v[18:19], v[76:77] neg_lo:[1,0,0] neg_hi:[1,0,0]
	v_add_f32_e32 v30, v30, v70
	ds_read_b128 v[108:111], v78 offset:8752
	s_waitcnt lgkmcnt(6)
	v_pk_fma_f32 v[74:75], v[84:85], v[20:21], v[74:75] neg_lo:[1,0,0] neg_hi:[1,0,0]
	v_pk_fma_f32 v[76:77], v[86:87], v[22:23], v[76:77] neg_lo:[1,0,0] neg_hi:[1,0,0]
	ds_read_b128 v[84:87], v78 offset:8768
	s_waitcnt lgkmcnt(6)
	v_pk_fma_f32 v[74:75], v[88:89], v[24:25], v[74:75] neg_lo:[1,0,0] neg_hi:[1,0,0]
	v_pk_fma_f32 v[76:77], v[90:91], v[26:27], v[76:77] neg_lo:[1,0,0] neg_hi:[1,0,0]
	ds_read_b128 v[88:91], v78 offset:8784
	s_waitcnt lgkmcnt(6)
	v_pk_fma_f32 v[74:75], v[92:93], v[28:29], v[74:75] neg_lo:[1,0,0] neg_hi:[1,0,0]
	v_mov_b32_e32 v69, v94
	ds_read_b128 v[92:95], v78 offset:8800
	s_waitcnt lgkmcnt(6)
; DI void gdn_prep(const Params& p, int item, unsigned char* smem) {
;     ...
; #pragma unroll
;         for (int i = 1; i < 64; ++i) {
;             float a = X[i];
;             int dep; asm volatile("v_and_b32 %0, 0, %1" : "=v"(dep) : "v"(X[i - 1]));
;             const float* Lr = sL + i * 68 + dep;
;             float b0 = 0.f, b1 = 0.f, b2 = 0.f;
; #pragma unroll
;             for (int j4 = 0; j4 < (i + 3) / 4; ++j4) {
;                 const f32x4 l = *(const f32x4*)(Lr + 4 * j4);
;                 if (4 * j4 + 0 < i) a -= l.x * X[4 * j4 + 0];
;                 if (4 * j4 + 1 < i) b0 -= l.y * X[4 * j4 + 1];
;                 if (4 * j4 + 2 < i) b1 -= l.z * X[4 * j4 + 2];
;                 if (4 * j4 + 3 < i) b2 -= l.w * X[4 * j4 + 3];
;             }
;             X[i] = (a + b0) + (b1 + b2);
	v_pk_fma_f32 v[70:71], v[96:97], v[0:1], 0 neg_lo:[1,0,0] neg_hi:[1,0,0]
	v_pk_fma_f32 v[72:73], v[98:99], v[2:3], 0 neg_lo:[1,0,0] neg_hi:[1,0,0]
	v_fma_f32 v76, -v30, v69, v76
	ds_read_b128 v[96:99], v78 offset:8816
	s_waitcnt lgkmcnt(6)
	v_pk_fma_f32 v[70:71], v[100:101], v[4:5], v[70:71] neg_lo:[1,0,0] neg_hi:[1,0,0]
	v_pk_fma_f32 v[72:73], v[102:103], v[6:7], v[72:73] neg_lo:[1,0,0] neg_hi:[1,0,0]
	v_add_f32_e32 v74, v74, v75
	ds_read_b128 v[100:103], v78 offset:8976
	s_waitcnt lgkmcnt(6)
	v_pk_fma_f32 v[70:71], v[104:105], v[8:9], v[70:71] neg_lo:[1,0,0] neg_hi:[1,0,0]
	v_pk_fma_f32 v[72:73], v[106:107], v[10:11], v[72:73] neg_lo:[1,0,0] neg_hi:[1,0,0]
	v_add_f32_e32 v76, v76, v77
	ds_read_b128 v[104:107], v78 offset:8992
	s_waitcnt lgkmcnt(6)
	v_pk_fma_f32 v[70:71], v[108:109], v[12:13], v[70:71] neg_lo:[1,0,0] neg_hi:[1,0,0]
	v_pk_fma_f32 v[72:73], v[110:111], v[14:15], v[72:73] neg_lo:[1,0,0] neg_hi:[1,0,0]
	v_add_f32_e32 v74, v74, v76
	ds_read_b128 v[108:111], v78 offset:9008
	s_waitcnt lgkmcnt(6)
	v_pk_fma_f32 v[70:71], v[84:85], v[16:17], v[70:71] neg_lo:[1,0,0] neg_hi:[1,0,0]
	v_pk_fma_f32 v[72:73], v[86:87], v[18:19], v[72:73] neg_lo:[1,0,0] neg_hi:[1,0,0]
	v_add_f32_e32 v31, v31, v74
	ds_read_b128 v[84:87], v78 offset:9024
	s_waitcnt lgkmcnt(6)
	v_pk_fma_f32 v[70:71], v[88:89], v[20:21], v[70:71] neg_lo:[1,0,0] neg_hi:[1,0,0]
	v_pk_fma_f32 v[72:73], v[90:91], v[22:23], v[72:73] neg_lo:[1,0,0] neg_hi:[1,0,0]
	ds_read_b128 v[88:91], v78 offset:9040
	s_waitcnt lgkmcnt(6)
	v_pk_fma_f32 v[70:71], v[92:93], v[24:25], v[70:71] neg_lo:[1,0,0] neg_hi:[1,0,0]
	v_pk_fma_f32 v[72:73], v[94:95], v[26:27], v[72:73] neg_lo:[1,0,0] neg_hi:[1,0,0]
	ds_read_b128 v[92:95], v78 offset:9056
	s_waitcnt lgkmcnt(6)
	v_pk_fma_f32 v[70:71], v[96:97], v[28:29], v[70:71] neg_lo:[1,0,0] neg_hi:[1,0,0]
	v_fma_f32 v72, -v30, v98, v72
	v_mov_b32_e32 v68, v99
	ds_read_b128 v[96:99], v78 offset:9072
	s_waitcnt lgkmcnt(6)
	v_pk_fma_f32 v[74:75], v[100:101], v[0:1], 0 neg_lo:[1,0,0] neg_hi:[1,0,0]
	v_pk_fma_f32 v[76:77], v[102:103], v[2:3], 0 neg_lo:[1,0,0] neg_hi:[1,0,0]
	v_fma_f32 v73, -v31, v68, v73
	ds_read_b128 v[100:103], v78 offset:9088
	s_waitcnt lgkmcnt(6)
	v_pk_fma_f32 v[74:75], v[104:105], v[4:5], v[74:75] neg_lo:[1,0,0] neg_hi:[1,0,0]
	v_pk_fma_f32 v[76:77], v[106:107], v[6:7], v[76:77] neg_lo:[1,0,0] neg_hi:[1,0,0]
	v_add_f32_e32 v70, v70, v71
	ds_read_b128 v[104:107], v78 offset:9104
	s_waitcnt lgkmcnt(6)
	v_pk_fma_f32 v[74:75], v[108:109], v[8:9], v[74:75] neg_lo:[1,0,0] neg_hi:[1,0,0]
	v_pk_fma_f32 v[76:77], v[110:111], v[10:11], v[76:77] neg_lo:[1,0,0] neg_hi:[1,0,0]
	v_add_f32_e32 v72, v72, v73
	ds_read_b128 v[108:111], v78 offset:9248
	s_waitcnt lgkmcnt(6)
	v_pk_fma_f32 v[74:75], v[84:85], v[12:13], v[74:75] neg_lo:[1,0,0] neg_hi:[1,0,0]
	v_pk_fma_f32 v[76:77], v[86:87], v[14:15], v[76:77] neg_lo:[1,0,0] neg_hi:[1,0,0]
	v_add_f32_e32 v70, v70, v72
	ds_read_b128 v[84:87], v78 offset:9264
	s_waitcnt lgkmcnt(6)
	v_pk_fma_f32 v[74:75], v[88:89], v[16:17], v[74:75] neg_lo:[1,0,0] neg_hi:[1,0,0]
	v_pk_fma_f32 v[76:77], v[90:91], v[18:19], v[76:77] neg_lo:[1,0,0] neg_hi:[1,0,0]
	v_add_f32_e32 v34, v34, v70
	ds_read_b128 v[88:91], v78 offset:9280
	s_waitcnt lgkmcnt(6)
	v_pk_fma_f32 v[74:75], v[92:93], v[20:21], v[74:75] neg_lo:[1,0,0] neg_hi:[1,0,0]
	v_pk_fma_f32 v[76:77], v[94:95], v[22:23], v[76:77] neg_lo:[1,0,0] neg_hi:[1,0,0]
	ds_read_b128 v[92:95], v78 offset:9296
	s_waitcnt lgkmcnt(6)
	v_pk_fma_f32 v[74:75], v[96:97], v[24:25], v[74:75] neg_lo:[1,0,0] neg_hi:[1,0,0]
	v_pk_fma_f32 v[76:77], v[98:99], v[26:27], v[76:77] neg_lo:[1,0,0] neg_hi:[1,0,0]
	ds_read_b128 v[96:99], v78 offset:9312
	s_waitcnt lgkmcnt(6)
	v_pk_fma_f32 v[74:75], v[100:101], v[28:29], v[74:75] neg_lo:[1,0,0] neg_hi:[1,0,0]
	v_pk_fma_f32 v[76:77], v[102:103], v[30:31], v[76:77] neg_lo:[1,0,0] neg_hi:[1,0,0]
	ds_read_b128 v[100:103], v78 offset:9328
	s_waitcnt lgkmcnt(6)
	v_mov_b32_e32 v69, v104
	ds_read_b128 v[104:107], v78 offset:9344
	s_waitcnt lgkmcnt(6)
	v_pk_fma_f32 v[70:71], v[108:109], v[0:1], 0 neg_lo:[1,0,0] neg_hi:[1,0,0]
	v_pk_fma_f32 v[72:73], v[110:111], v[2:3], 0 neg_lo:[1,0,0] neg_hi:[1,0,0]
	v_fma_f32 v74, -v34, v69, v74
	ds_read_b128 v[108:111], v78 offset:9360
	s_waitcnt lgkmcnt(6)
	v_pk_fma_f32 v[70:71], v[84:85], v[4:5], v[70:71] neg_lo:[1,0,0] neg_hi:[1,0,0]
	v_pk_fma_f32 v[72:73], v[86:87], v[6:7], v[72:73] neg_lo:[1,0,0] neg_hi:[1,0,0]
	v_add_f32_e32 v74, v74, v75
	ds_read_b128 v[84:87], v78 offset:9376
	s_waitcnt lgkmcnt(6)
	v_pk_fma_f32 v[70:71], v[88:89], v[8:9], v[70:71] neg_lo:[1,0,0] neg_hi:[1,0,0]
	v_pk_fma_f32 v[72:73], v[90:91], v[10:11], v[72:73] neg_lo:[1,0,0] neg_hi:[1,0,0]
	v_add_f32_e32 v76, v76, v77
	ds_read_b128 v[88:91], v78 offset:9520
	s_waitcnt lgkmcnt(6)
	v_pk_fma_f32 v[70:71], v[92:93], v[12:13], v[70:71] neg_lo:[1,0,0] neg_hi:[1,0,0]
	v_pk_fma_f32 v[72:73], v[94:95], v[14:15], v[72:73] neg_lo:[1,0,0] neg_hi:[1,0,0]
	v_add_f32_e32 v74, v74, v76
	ds_read_b128 v[92:95], v78 offset:9536
	s_waitcnt lgkmcnt(6)
	v_pk_fma_f32 v[70:71], v[96:97], v[16:17], v[70:71] neg_lo:[1,0,0] neg_hi:[1,0,0]
	v_pk_fma_f32 v[72:73], v[98:99], v[18:19], v[72:73] neg_lo:[1,0,0] neg_hi:[1,0,0]
	v_add_f32_e32 v35, v35, v74
	ds_read_b128 v[96:99], v78 offset:9552
	s_waitcnt lgkmcnt(6)
	v_pk_fma_f32 v[70:71], v[100:101], v[20:21], v[70:71] neg_lo:[1,0,0] neg_hi:[1,0,0]
	v_pk_fma_f32 v[72:73], v[102:103], v[22:23], v[72:73] neg_lo:[1,0,0] neg_hi:[1,0,0]
	ds_read_b128 v[100:103], v78 offset:9568
	s_waitcnt lgkmcnt(6)
	v_pk_fma_f32 v[70:71], v[104:105], v[24:25], v[70:71] neg_lo:[1,0,0] neg_hi:[1,0,0]
	v_pk_fma_f32 v[72:73], v[106:107], v[26:27], v[72:73] neg_lo:[1,0,0] neg_hi:[1,0,0]
	ds_read_b128 v[104:107], v78 offset:9584
	s_waitcnt lgkmcnt(6)
; DI void gdn_prep(const Params& p, int item, unsigned char* smem) {
;     ...
; #pragma unroll
;         for (int i = 1; i < 64; ++i) {
;             float a = X[i];
;             int dep; asm volatile("v_and_b32 %0, 0, %1" : "=v"(dep) : "v"(X[i - 1]));
;             const float* Lr = sL + i * 68 + dep;
;             float b0 = 0.f, b1 = 0.f, b2 = 0.f;
; #pragma unroll
;             for (int j4 = 0; j4 < (i + 3) / 4; ++j4) {
;                 const f32x4 l = *(const f32x4*)(Lr + 4 * j4);
;                 if (4 * j4 + 0 < i) a -= l.x * X[4 * j4 + 0];
;                 if (4 * j4 + 1 < i) b0 -= l.y * X[4 * j4 + 1];
;                 if (4 * j4 + 2 < i) b1 -= l.z * X[4 * j4 + 2];
;                 if (4 * j4 + 3 < i) b2 -= l.w * X[4 * j4 + 3];
;             }
;             X[i] = (a + b0) + (b1 + b2);
	v_pk_fma_f32 v[70:71], v[108:109], v[28:29], v[70:71] neg_lo:[1,0,0] neg_hi:[1,0,0]
	v_pk_fma_f32 v[72:73], v[110:111], v[30:31], v[72:73] neg_lo:[1,0,0] neg_hi:[1,0,0]
	ds_read_b128 v[108:111], v78 offset:9600
	s_waitcnt lgkmcnt(6)
	v_fma_f32 v70, -v34, v84, v70
	v_mov_b32_e32 v68, v85
	ds_read_b128 v[84:87], v78 offset:9616
	s_waitcnt lgkmcnt(6)
	v_pk_fma_f32 v[74:75], v[88:89], v[0:1], 0 neg_lo:[1,0,0] neg_hi:[1,0,0]
	v_pk_fma_f32 v[76:77], v[90:91], v[2:3], 0 neg_lo:[1,0,0] neg_hi:[1,0,0]
	v_fma_f32 v71, -v35, v68, v71
	ds_read_b128 v[88:91], v78 offset:9632
	s_waitcnt lgkmcnt(6)
	v_pk_fma_f32 v[74:75], v[92:93], v[4:5], v[74:75] neg_lo:[1,0,0] neg_hi:[1,0,0]
	v_pk_fma_f32 v[76:77], v[94:95], v[6:7], v[76:77] neg_lo:[1,0,0] neg_hi:[1,0,0]
	v_add_f32_e32 v70, v70, v71
	ds_read_b128 v[92:95], v78 offset:9648
	s_waitcnt lgkmcnt(6)
	v_pk_fma_f32 v[74:75], v[96:97], v[8:9], v[74:75] neg_lo:[1,0,0] neg_hi:[1,0,0]
	v_pk_fma_f32 v[76:77], v[98:99], v[10:11], v[76:77] neg_lo:[1,0,0] neg_hi:[1,0,0]
	v_add_f32_e32 v72, v72, v73
	ds_read_b128 v[96:99], v78 offset:9792
	s_waitcnt lgkmcnt(6)
	v_pk_fma_f32 v[74:75], v[100:101], v[12:13], v[74:75] neg_lo:[1,0,0] neg_hi:[1,0,0]
	v_pk_fma_f32 v[76:77], v[102:103], v[14:15], v[76:77] neg_lo:[1,0,0] neg_hi:[1,0,0]
	v_add_f32_e32 v70, v70, v72
	ds_read_b128 v[100:103], v78 offset:9808
	s_waitcnt lgkmcnt(6)
	v_pk_fma_f32 v[74:75], v[104:105], v[16:17], v[74:75] neg_lo:[1,0,0] neg_hi:[1,0,0]
	v_pk_fma_f32 v[76:77], v[106:107], v[18:19], v[76:77] neg_lo:[1,0,0] neg_hi:[1,0,0]
	v_add_f32_e32 v36, v36, v70
	ds_read_b128 v[104:107], v78 offset:9824
	s_waitcnt lgkmcnt(6)
	v_pk_fma_f32 v[74:75], v[108:109], v[20:21], v[74:75] neg_lo:[1,0,0] neg_hi:[1,0,0]
	v_pk_fma_f32 v[76:77], v[110:111], v[22:23], v[76:77] neg_lo:[1,0,0] neg_hi:[1,0,0]
	ds_read_b128 v[108:111], v78 offset:9840
	s_waitcnt lgkmcnt(6)
	v_pk_fma_f32 v[74:75], v[84:85], v[24:25], v[74:75] neg_lo:[1,0,0] neg_hi:[1,0,0]
	v_pk_fma_f32 v[76:77], v[86:87], v[26:27], v[76:77] neg_lo:[1,0,0] neg_hi:[1,0,0]
	ds_read_b128 v[84:87], v78 offset:9856
	s_waitcnt lgkmcnt(6)
	v_pk_fma_f32 v[74:75], v[88:89], v[28:29], v[74:75] neg_lo:[1,0,0] neg_hi:[1,0,0]
	v_pk_fma_f32 v[76:77], v[90:91], v[30:31], v[76:77] neg_lo:[1,0,0] neg_hi:[1,0,0]
	ds_read_b128 v[88:91], v78 offset:9872
	s_waitcnt lgkmcnt(6)
	v_pk_fma_f32 v[74:75], v[92:93], v[34:35], v[74:75] neg_lo:[1,0,0] neg_hi:[1,0,0]
	v_mov_b32_e32 v69, v94
	ds_read_b128 v[92:95], v78 offset:9888
	s_waitcnt lgkmcnt(6)
	v_pk_fma_f32 v[70:71], v[96:97], v[0:1], 0 neg_lo:[1,0,0] neg_hi:[1,0,0]
	v_pk_fma_f32 v[72:73], v[98:99], v[2:3], 0 neg_lo:[1,0,0] neg_hi:[1,0,0]
	v_fma_f32 v76, -v36, v69, v76
	ds_read_b128 v[96:99], v78 offset:9904
	s_waitcnt lgkmcnt(6)
	v_pk_fma_f32 v[70:71], v[100:101], v[4:5], v[70:71] neg_lo:[1,0,0] neg_hi:[1,0,0]
	v_pk_fma_f32 v[72:73], v[102:103], v[6:7], v[72:73] neg_lo:[1,0,0] neg_hi:[1,0,0]
	v_add_f32_e32 v74, v74, v75
	ds_read_b128 v[100:103], v78 offset:9920
	s_waitcnt lgkmcnt(6)
	v_pk_fma_f32 v[70:71], v[104:105], v[8:9], v[70:71] neg_lo:[1,0,0] neg_hi:[1,0,0]
	v_pk_fma_f32 v[72:73], v[106:107], v[10:11], v[72:73] neg_lo:[1,0,0] neg_hi:[1,0,0]
	v_add_f32_e32 v76, v76, v77
	ds_read_b128 v[104:107], v78 offset:10064
	s_waitcnt lgkmcnt(6)
	v_pk_fma_f32 v[70:71], v[108:109], v[12:13], v[70:71] neg_lo:[1,0,0] neg_hi:[1,0,0]
	v_pk_fma_f32 v[72:73], v[110:111], v[14:15], v[72:73] neg_lo:[1,0,0] neg_hi:[1,0,0]
	v_add_f32_e32 v74, v74, v76
	ds_read_b128 v[108:111], v78 offset:10080
	s_waitcnt lgkmcnt(6)
	v_pk_fma_f32 v[70:71], v[84:85], v[16:17], v[70:71] neg_lo:[1,0,0] neg_hi:[1,0,0]
	v_pk_fma_f32 v[72:73], v[86:87], v[18:19], v[72:73] neg_lo:[1,0,0] neg_hi:[1,0,0]
	v_add_f32_e32 v37, v37, v74
	ds_read_b128 v[84:87], v78 offset:10096
	s_waitcnt lgkmcnt(6)
	v_pk_fma_f32 v[70:71], v[88:89], v[20:21], v[70:71] neg_lo:[1,0,0] neg_hi:[1,0,0]
	v_pk_fma_f32 v[72:73], v[90:91], v[22:23], v[72:73] neg_lo:[1,0,0] neg_hi:[1,0,0]
	ds_read_b128 v[88:91], v78 offset:10112
	s_waitcnt lgkmcnt(6)
	v_pk_fma_f32 v[70:71], v[92:93], v[24:25], v[70:71] neg_lo:[1,0,0] neg_hi:[1,0,0]
	v_pk_fma_f32 v[72:73], v[94:95], v[26:27], v[72:73] neg_lo:[1,0,0] neg_hi:[1,0,0]
	ds_read_b128 v[92:95], v78 offset:10128
	s_waitcnt lgkmcnt(6)
	v_pk_fma_f32 v[70:71], v[96:97], v[28:29], v[70:71] neg_lo:[1,0,0] neg_hi:[1,0,0]
	v_pk_fma_f32 v[72:73], v[98:99], v[30:31], v[72:73] neg_lo:[1,0,0] neg_hi:[1,0,0]
	ds_read_b128 v[96:99], v78 offset:10144
	s_waitcnt lgkmcnt(6)
	v_pk_fma_f32 v[70:71], v[100:101], v[34:35], v[70:71] neg_lo:[1,0,0] neg_hi:[1,0,0]
	v_fma_f32 v72, -v36, v102, v72
	v_mov_b32_e32 v68, v103
	ds_read_b128 v[100:103], v78 offset:10160
	s_waitcnt lgkmcnt(6)
	v_pk_fma_f32 v[74:75], v[104:105], v[0:1], 0 neg_lo:[1,0,0] neg_hi:[1,0,0]
	v_pk_fma_f32 v[76:77], v[106:107], v[2:3], 0 neg_lo:[1,0,0] neg_hi:[1,0,0]
	v_fma_f32 v73, -v37, v68, v73
	ds_read_b128 v[104:107], v78 offset:10176
	s_waitcnt lgkmcnt(6)
	v_pk_fma_f32 v[74:75], v[108:109], v[4:5], v[74:75] neg_lo:[1,0,0] neg_hi:[1,0,0]
	v_pk_fma_f32 v[76:77], v[110:111], v[6:7], v[76:77] neg_lo:[1,0,0] neg_hi:[1,0,0]
	v_add_f32_e32 v70, v70, v71
	ds_read_b128 v[108:111], v78 offset:10192
	s_waitcnt lgkmcnt(6)
	v_pk_fma_f32 v[74:75], v[84:85], v[8:9], v[74:75] neg_lo:[1,0,0] neg_hi:[1,0,0]
	v_pk_fma_f32 v[76:77], v[86:87], v[10:11], v[76:77] neg_lo:[1,0,0] neg_hi:[1,0,0]
	v_add_f32_e32 v72, v72, v73
	ds_read_b128 v[84:87], v78 offset:10208
	s_waitcnt lgkmcnt(6)
	v_pk_fma_f32 v[74:75], v[88:89], v[12:13], v[74:75] neg_lo:[1,0,0] neg_hi:[1,0,0]
	v_pk_fma_f32 v[76:77], v[90:91], v[14:15], v[76:77] neg_lo:[1,0,0] neg_hi:[1,0,0]
	v_add_f32_e32 v70, v70, v72
	ds_read_b128 v[88:91], v78 offset:10336
	s_waitcnt lgkmcnt(6)
; DI void gdn_prep(const Params& p, int item, unsigned char* smem) {
;     ...
; #pragma unroll
;         for (int i = 1; i < 64; ++i) {
;             float a = X[i];
;             int dep; asm volatile("v_and_b32 %0, 0, %1" : "=v"(dep) : "v"(X[i - 1]));
;             const float* Lr = sL + i * 68 + dep;
;             float b0 = 0.f, b1 = 0.f, b2 = 0.f;
; #pragma unroll
;             for (int j4 = 0; j4 < (i + 3) / 4; ++j4) {
;                 const f32x4 l = *(const f32x4*)(Lr + 4 * j4);
;                 if (4 * j4 + 0 < i) a -= l.x * X[4 * j4 + 0];
;                 if (4 * j4 + 1 < i) b0 -= l.y * X[4 * j4 + 1];
;                 if (4 * j4 + 2 < i) b1 -= l.z * X[4 * j4 + 2];
;                 if (4 * j4 + 3 < i) b2 -= l.w * X[4 * j4 + 3];
;             }
;             X[i] = (a + b0) + (b1 + b2);
	v_pk_fma_f32 v[74:75], v[92:93], v[16:17], v[74:75] neg_lo:[1,0,0] neg_hi:[1,0,0]
	v_pk_fma_f32 v[76:77], v[94:95], v[18:19], v[76:77] neg_lo:[1,0,0] neg_hi:[1,0,0]
	v_add_f32_e32 v38, v38, v70
	ds_read_b128 v[92:95], v78 offset:10352
	s_waitcnt lgkmcnt(6)
	v_pk_fma_f32 v[74:75], v[96:97], v[20:21], v[74:75] neg_lo:[1,0,0] neg_hi:[1,0,0]
	v_pk_fma_f32 v[76:77], v[98:99], v[22:23], v[76:77] neg_lo:[1,0,0] neg_hi:[1,0,0]
	ds_read_b128 v[96:99], v78 offset:10368
	s_waitcnt lgkmcnt(6)
	v_pk_fma_f32 v[74:75], v[100:101], v[24:25], v[74:75] neg_lo:[1,0,0] neg_hi:[1,0,0]
	v_pk_fma_f32 v[76:77], v[102:103], v[26:27], v[76:77] neg_lo:[1,0,0] neg_hi:[1,0,0]
	ds_read_b128 v[100:103], v78 offset:10384
	s_waitcnt lgkmcnt(6)
	v_pk_fma_f32 v[74:75], v[104:105], v[28:29], v[74:75] neg_lo:[1,0,0] neg_hi:[1,0,0]
	v_pk_fma_f32 v[76:77], v[106:107], v[30:31], v[76:77] neg_lo:[1,0,0] neg_hi:[1,0,0]
	ds_read_b128 v[104:107], v78 offset:10400
	s_waitcnt lgkmcnt(6)
	v_pk_fma_f32 v[74:75], v[108:109], v[34:35], v[74:75] neg_lo:[1,0,0] neg_hi:[1,0,0]
	v_pk_fma_f32 v[76:77], v[110:111], v[36:37], v[76:77] neg_lo:[1,0,0] neg_hi:[1,0,0]
	ds_read_b128 v[108:111], v78 offset:10416
	s_waitcnt lgkmcnt(6)
	v_mov_b32_e32 v69, v84
	ds_read_b128 v[84:87], v78 offset:10432
	s_waitcnt lgkmcnt(6)
	v_pk_fma_f32 v[70:71], v[88:89], v[0:1], 0 neg_lo:[1,0,0] neg_hi:[1,0,0]
	v_pk_fma_f32 v[72:73], v[90:91], v[2:3], 0 neg_lo:[1,0,0] neg_hi:[1,0,0]
	v_fma_f32 v74, -v38, v69, v74
	ds_read_b128 v[88:91], v78 offset:10448
	s_waitcnt lgkmcnt(6)
	v_pk_fma_f32 v[70:71], v[92:93], v[4:5], v[70:71] neg_lo:[1,0,0] neg_hi:[1,0,0]
	v_pk_fma_f32 v[72:73], v[94:95], v[6:7], v[72:73] neg_lo:[1,0,0] neg_hi:[1,0,0]
	v_add_f32_e32 v74, v74, v75
	ds_read_b128 v[92:95], v78 offset:10464
	s_waitcnt lgkmcnt(6)
	v_pk_fma_f32 v[70:71], v[96:97], v[8:9], v[70:71] neg_lo:[1,0,0] neg_hi:[1,0,0]
	v_pk_fma_f32 v[72:73], v[98:99], v[10:11], v[72:73] neg_lo:[1,0,0] neg_hi:[1,0,0]
	v_add_f32_e32 v76, v76, v77
	ds_read_b128 v[96:99], v78 offset:10480
	s_waitcnt lgkmcnt(6)
	v_pk_fma_f32 v[70:71], v[100:101], v[12:13], v[70:71] neg_lo:[1,0,0] neg_hi:[1,0,0]
	v_pk_fma_f32 v[72:73], v[102:103], v[14:15], v[72:73] neg_lo:[1,0,0] neg_hi:[1,0,0]
	v_add_f32_e32 v74, v74, v76
	ds_read_b128 v[100:103], v78 offset:10608
	s_waitcnt lgkmcnt(6)
	v_pk_fma_f32 v[70:71], v[104:105], v[16:17], v[70:71] neg_lo:[1,0,0] neg_hi:[1,0,0]
	v_pk_fma_f32 v[72:73], v[106:107], v[18:19], v[72:73] neg_lo:[1,0,0] neg_hi:[1,0,0]
	v_add_f32_e32 v39, v39, v74
	ds_read_b128 v[104:107], v78 offset:10624
	s_waitcnt lgkmcnt(6)
	v_pk_fma_f32 v[70:71], v[108:109], v[20:21], v[70:71] neg_lo:[1,0,0] neg_hi:[1,0,0]
	v_pk_fma_f32 v[72:73], v[110:111], v[22:23], v[72:73] neg_lo:[1,0,0] neg_hi:[1,0,0]
	ds_read_b128 v[108:111], v78 offset:10640
	s_waitcnt lgkmcnt(6)
	v_pk_fma_f32 v[70:71], v[84:85], v[24:25], v[70:71] neg_lo:[1,0,0] neg_hi:[1,0,0]
	v_pk_fma_f32 v[72:73], v[86:87], v[26:27], v[72:73] neg_lo:[1,0,0] neg_hi:[1,0,0]
	ds_read_b128 v[84:87], v78 offset:10656
	s_waitcnt lgkmcnt(6)
	v_pk_fma_f32 v[70:71], v[88:89], v[28:29], v[70:71] neg_lo:[1,0,0] neg_hi:[1,0,0]
	v_pk_fma_f32 v[72:73], v[90:91], v[30:31], v[72:73] neg_lo:[1,0,0] neg_hi:[1,0,0]
	ds_read_b128 v[88:91], v78 offset:10672
	s_waitcnt lgkmcnt(6)
	v_pk_fma_f32 v[70:71], v[92:93], v[34:35], v[70:71] neg_lo:[1,0,0] neg_hi:[1,0,0]
	v_pk_fma_f32 v[72:73], v[94:95], v[36:37], v[72:73] neg_lo:[1,0,0] neg_hi:[1,0,0]
	ds_read_b128 v[92:95], v78 offset:10688
	s_waitcnt lgkmcnt(6)
	v_fma_f32 v70, -v38, v96, v70
	v_mov_b32_e32 v68, v97
	ds_read_b128 v[96:99], v78 offset:10704
	s_waitcnt lgkmcnt(6)
	v_pk_fma_f32 v[74:75], v[100:101], v[0:1], 0 neg_lo:[1,0,0] neg_hi:[1,0,0]
	v_pk_fma_f32 v[76:77], v[102:103], v[2:3], 0 neg_lo:[1,0,0] neg_hi:[1,0,0]
	v_fma_f32 v71, -v39, v68, v71
	ds_read_b128 v[100:103], v78 offset:10720
	s_waitcnt lgkmcnt(6)
	v_pk_fma_f32 v[74:75], v[104:105], v[4:5], v[74:75] neg_lo:[1,0,0] neg_hi:[1,0,0]
	v_pk_fma_f32 v[76:77], v[106:107], v[6:7], v[76:77] neg_lo:[1,0,0] neg_hi:[1,0,0]
	v_add_f32_e32 v70, v70, v71
	ds_read_b128 v[104:107], v78 offset:10736
	s_waitcnt lgkmcnt(6)
	v_pk_fma_f32 v[74:75], v[108:109], v[8:9], v[74:75] neg_lo:[1,0,0] neg_hi:[1,0,0]
	v_pk_fma_f32 v[76:77], v[110:111], v[10:11], v[76:77] neg_lo:[1,0,0] neg_hi:[1,0,0]
	v_add_f32_e32 v72, v72, v73
	ds_read_b128 v[108:111], v78 offset:10752
	s_waitcnt lgkmcnt(6)
	v_pk_fma_f32 v[74:75], v[84:85], v[12:13], v[74:75] neg_lo:[1,0,0] neg_hi:[1,0,0]
	v_pk_fma_f32 v[76:77], v[86:87], v[14:15], v[76:77] neg_lo:[1,0,0] neg_hi:[1,0,0]
	v_add_f32_e32 v70, v70, v72
	ds_read_b128 v[84:87], v78 offset:10880
	s_waitcnt lgkmcnt(6)
	v_pk_fma_f32 v[74:75], v[88:89], v[16:17], v[74:75] neg_lo:[1,0,0] neg_hi:[1,0,0]
	v_pk_fma_f32 v[76:77], v[90:91], v[18:19], v[76:77] neg_lo:[1,0,0] neg_hi:[1,0,0]
	v_add_f32_e32 v40, v40, v70
	ds_read_b128 v[88:91], v78 offset:10896
	s_waitcnt lgkmcnt(6)
	v_pk_fma_f32 v[74:75], v[92:93], v[20:21], v[74:75] neg_lo:[1,0,0] neg_hi:[1,0,0]
	v_pk_fma_f32 v[76:77], v[94:95], v[22:23], v[76:77] neg_lo:[1,0,0] neg_hi:[1,0,0]
	ds_read_b128 v[92:95], v78 offset:10912
	s_waitcnt lgkmcnt(6)
	v_pk_fma_f32 v[74:75], v[96:97], v[24:25], v[74:75] neg_lo:[1,0,0] neg_hi:[1,0,0]
	v_pk_fma_f32 v[76:77], v[98:99], v[26:27], v[76:77] neg_lo:[1,0,0] neg_hi:[1,0,0]
	ds_read_b128 v[96:99], v78 offset:10928
	s_waitcnt lgkmcnt(6)
	v_pk_fma_f32 v[74:75], v[100:101], v[28:29], v[74:75] neg_lo:[1,0,0] neg_hi:[1,0,0]
	v_pk_fma_f32 v[76:77], v[102:103], v[30:31], v[76:77] neg_lo:[1,0,0] neg_hi:[1,0,0]
	ds_read_b128 v[100:103], v78 offset:10944
	s_waitcnt lgkmcnt(6)
; DI void gdn_prep(const Params& p, int item, unsigned char* smem) {
;     ...
; #pragma unroll
;         for (int i = 1; i < 64; ++i) {
;             float a = X[i];
;             int dep; asm volatile("v_and_b32 %0, 0, %1" : "=v"(dep) : "v"(X[i - 1]));
;             const float* Lr = sL + i * 68 + dep;
;             float b0 = 0.f, b1 = 0.f, b2 = 0.f;
; #pragma unroll
;             for (int j4 = 0; j4 < (i + 3) / 4; ++j4) {
;                 const f32x4 l = *(const f32x4*)(Lr + 4 * j4);
;                 if (4 * j4 + 0 < i) a -= l.x * X[4 * j4 + 0];
;                 if (4 * j4 + 1 < i) b0 -= l.y * X[4 * j4 + 1];
;                 if (4 * j4 + 2 < i) b1 -= l.z * X[4 * j4 + 2];
;                 if (4 * j4 + 3 < i) b2 -= l.w * X[4 * j4 + 3];
;             }
;             X[i] = (a + b0) + (b1 + b2);
;         }
	v_pk_fma_f32 v[74:75], v[104:105], v[34:35], v[74:75] neg_lo:[1,0,0] neg_hi:[1,0,0]
	v_pk_fma_f32 v[76:77], v[106:107], v[36:37], v[76:77] neg_lo:[1,0,0] neg_hi:[1,0,0]
	ds_read_b128 v[104:107], v78 offset:10960
	s_waitcnt lgkmcnt(6)
	v_pk_fma_f32 v[74:75], v[108:109], v[38:39], v[74:75] neg_lo:[1,0,0] neg_hi:[1,0,0]
	v_mov_b32_e32 v69, v110
	ds_read_b128 v[108:111], v78 offset:10976
	s_waitcnt lgkmcnt(6)
	v_pk_fma_f32 v[70:71], v[84:85], v[0:1], 0 neg_lo:[1,0,0] neg_hi:[1,0,0]
	v_pk_fma_f32 v[72:73], v[86:87], v[2:3], 0 neg_lo:[1,0,0] neg_hi:[1,0,0]
	v_fma_f32 v76, -v40, v69, v76
	ds_read_b128 v[84:87], v78 offset:10992
	s_waitcnt lgkmcnt(6)
	v_pk_fma_f32 v[70:71], v[88:89], v[4:5], v[70:71] neg_lo:[1,0,0] neg_hi:[1,0,0]
	v_pk_fma_f32 v[72:73], v[90:91], v[6:7], v[72:73] neg_lo:[1,0,0] neg_hi:[1,0,0]
	v_add_f32_e32 v74, v74, v75
	ds_read_b128 v[88:91], v78 offset:11008
	s_waitcnt lgkmcnt(6)
	v_pk_fma_f32 v[70:71], v[92:93], v[8:9], v[70:71] neg_lo:[1,0,0] neg_hi:[1,0,0]
	v_pk_fma_f32 v[72:73], v[94:95], v[10:11], v[72:73] neg_lo:[1,0,0] neg_hi:[1,0,0]
	v_add_f32_e32 v76, v76, v77
	ds_read_b128 v[92:95], v78 offset:11024
	s_waitcnt lgkmcnt(6)
	v_pk_fma_f32 v[70:71], v[96:97], v[12:13], v[70:71] neg_lo:[1,0,0] neg_hi:[1,0,0]
	v_pk_fma_f32 v[72:73], v[98:99], v[14:15], v[72:73] neg_lo:[1,0,0] neg_hi:[1,0,0]
	v_add_f32_e32 v74, v74, v76
	ds_read_b128 v[96:99], v78 offset:11152
	s_waitcnt lgkmcnt(6)
	v_pk_fma_f32 v[70:71], v[100:101], v[16:17], v[70:71] neg_lo:[1,0,0] neg_hi:[1,0,0]
	v_pk_fma_f32 v[72:73], v[102:103], v[18:19], v[72:73] neg_lo:[1,0,0] neg_hi:[1,0,0]
	v_add_f32_e32 v41, v41, v74
	ds_read_b128 v[100:103], v78 offset:11168
	s_waitcnt lgkmcnt(6)
	v_pk_fma_f32 v[70:71], v[104:105], v[20:21], v[70:71] neg_lo:[1,0,0] neg_hi:[1,0,0]
	v_pk_fma_f32 v[72:73], v[106:107], v[22:23], v[72:73] neg_lo:[1,0,0] neg_hi:[1,0,0]
	ds_read_b128 v[104:107], v78 offset:11184
	s_waitcnt lgkmcnt(6)
	v_pk_fma_f32 v[70:71], v[108:109], v[24:25], v[70:71] neg_lo:[1,0,0] neg_hi:[1,0,0]
	v_pk_fma_f32 v[72:73], v[110:111], v[26:27], v[72:73] neg_lo:[1,0,0] neg_hi:[1,0,0]
	ds_read_b128 v[108:111], v78 offset:11200
	s_waitcnt lgkmcnt(6)
	v_pk_fma_f32 v[70:71], v[84:85], v[28:29], v[70:71] neg_lo:[1,0,0] neg_hi:[1,0,0]
	v_pk_fma_f32 v[72:73], v[86:87], v[30:31], v[72:73] neg_lo:[1,0,0] neg_hi:[1,0,0]
	ds_read_b128 v[84:87], v78 offset:11216
	s_waitcnt lgkmcnt(6)
	v_pk_fma_f32 v[70:71], v[88:89], v[34:35], v[70:71] neg_lo:[1,0,0] neg_hi:[1,0,0]
	v_pk_fma_f32 v[72:73], v[90:91], v[36:37], v[72:73] neg_lo:[1,0,0] neg_hi:[1,0,0]
	ds_read_b128 v[88:91], v78 offset:11232
	s_waitcnt lgkmcnt(6)
	v_pk_fma_f32 v[70:71], v[92:93], v[38:39], v[70:71] neg_lo:[1,0,0] neg_hi:[1,0,0]
	v_fma_f32 v72, -v40, v94, v72
	v_mov_b32_e32 v68, v95
	ds_read_b128 v[92:95], v78 offset:11248
	s_waitcnt lgkmcnt(6)
	v_pk_fma_f32 v[74:75], v[96:97], v[0:1], 0 neg_lo:[1,0,0] neg_hi:[1,0,0]
	v_pk_fma_f32 v[76:77], v[98:99], v[2:3], 0 neg_lo:[1,0,0] neg_hi:[1,0,0]
	v_fma_f32 v73, -v41, v68, v73
	ds_read_b128 v[96:99], v78 offset:11264
	s_waitcnt lgkmcnt(6)
	v_pk_fma_f32 v[74:75], v[100:101], v[4:5], v[74:75] neg_lo:[1,0,0] neg_hi:[1,0,0]
	v_pk_fma_f32 v[76:77], v[102:103], v[6:7], v[76:77] neg_lo:[1,0,0] neg_hi:[1,0,0]
	v_add_f32_e32 v70, v70, v71
	ds_read_b128 v[100:103], v78 offset:11280
	s_waitcnt lgkmcnt(6)
	v_pk_fma_f32 v[74:75], v[104:105], v[8:9], v[74:75] neg_lo:[1,0,0] neg_hi:[1,0,0]
	v_pk_fma_f32 v[76:77], v[106:107], v[10:11], v[76:77] neg_lo:[1,0,0] neg_hi:[1,0,0]
	v_add_f32_e32 v72, v72, v73
	ds_read_b128 v[104:107], v78 offset:11296
	s_waitcnt lgkmcnt(6)
	v_pk_fma_f32 v[74:75], v[108:109], v[12:13], v[74:75] neg_lo:[1,0,0] neg_hi:[1,0,0]
	v_pk_fma_f32 v[76:77], v[110:111], v[14:15], v[76:77] neg_lo:[1,0,0] neg_hi:[1,0,0]
	v_add_f32_e32 v70, v70, v72
	ds_read_b128 v[108:111], v78 offset:11312
	s_waitcnt lgkmcnt(6)
	v_pk_fma_f32 v[74:75], v[84:85], v[16:17], v[74:75] neg_lo:[1,0,0] neg_hi:[1,0,0]
	v_pk_fma_f32 v[76:77], v[86:87], v[18:19], v[76:77] neg_lo:[1,0,0] neg_hi:[1,0,0]
	v_add_f32_e32 v42, v42, v70
	ds_read_b128 v[84:87], v78 offset:11424
	s_waitcnt lgkmcnt(6)
	v_pk_fma_f32 v[74:75], v[88:89], v[20:21], v[74:75] neg_lo:[1,0,0] neg_hi:[1,0,0]
	v_pk_fma_f32 v[76:77], v[90:91], v[22:23], v[76:77] neg_lo:[1,0,0] neg_hi:[1,0,0]
	ds_read_b128 v[88:91], v78 offset:11440
	s_waitcnt lgkmcnt(6)
	v_pk_fma_f32 v[74:75], v[92:93], v[24:25], v[74:75] neg_lo:[1,0,0] neg_hi:[1,0,0]
	v_pk_fma_f32 v[76:77], v[94:95], v[26:27], v[76:77] neg_lo:[1,0,0] neg_hi:[1,0,0]
	ds_read_b128 v[92:95], v78 offset:11456
	s_waitcnt lgkmcnt(6)
	v_pk_fma_f32 v[74:75], v[96:97], v[28:29], v[74:75] neg_lo:[1,0,0] neg_hi:[1,0,0]
	v_pk_fma_f32 v[76:77], v[98:99], v[30:31], v[76:77] neg_lo:[1,0,0] neg_hi:[1,0,0]
	ds_read_b128 v[96:99], v78 offset:11472
	s_waitcnt lgkmcnt(6)
	v_pk_fma_f32 v[74:75], v[100:101], v[34:35], v[74:75] neg_lo:[1,0,0] neg_hi:[1,0,0]
	v_pk_fma_f32 v[76:77], v[102:103], v[36:37], v[76:77] neg_lo:[1,0,0] neg_hi:[1,0,0]
	ds_read_b128 v[100:103], v78 offset:11488
	s_waitcnt lgkmcnt(6)
	v_pk_fma_f32 v[74:75], v[104:105], v[38:39], v[74:75] neg_lo:[1,0,0] neg_hi:[1,0,0]
	v_pk_fma_f32 v[76:77], v[106:107], v[40:41], v[76:77] neg_lo:[1,0,0] neg_hi:[1,0,0]
	ds_read_b128 v[104:107], v78 offset:11504
	s_waitcnt lgkmcnt(6)
	v_mov_b32_e32 v69, v108
	ds_read_b128 v[108:111], v78 offset:11520
	s_waitcnt lgkmcnt(6)
	v_pk_fma_f32 v[70:71], v[84:85], v[0:1], 0 neg_lo:[1,0,0] neg_hi:[1,0,0]
	v_pk_fma_f32 v[72:73], v[86:87], v[2:3], 0 neg_lo:[1,0,0] neg_hi:[1,0,0]
	v_fma_f32 v74, -v42, v69, v74
	ds_read_b128 v[84:87], v78 offset:11536
	s_waitcnt lgkmcnt(6)
; DI void gdn_prep(const Params& p, int item, unsigned char* smem) {
;     ...
; #pragma unroll
;         for (int i = 1; i < 64; ++i) {
;             float a = X[i];
;             int dep; asm volatile("v_and_b32 %0, 0, %1" : "=v"(dep) : "v"(X[i - 1]));
;             const float* Lr = sL + i * 68 + dep;
;             float b0 = 0.f, b1 = 0.f, b2 = 0.f;
; #pragma unroll
;             for (int j4 = 0; j4 < (i + 3) / 4; ++j4) {
;                 const f32x4 l = *(const f32x4*)(Lr + 4 * j4);
;                 if (4 * j4 + 0 < i) a -= l.x * X[4 * j4 + 0];
;                 if (4 * j4 + 1 < i) b0 -= l.y * X[4 * j4 + 1];
;                 if (4 * j4 + 2 < i) b1 -= l.z * X[4 * j4 + 2];
;                 if (4 * j4 + 3 < i) b2 -= l.w * X[4 * j4 + 3];
;             }
;             X[i] = (a + b0) + (b1 + b2);
;         }
	v_pk_fma_f32 v[70:71], v[88:89], v[4:5], v[70:71] neg_lo:[1,0,0] neg_hi:[1,0,0]
	v_pk_fma_f32 v[72:73], v[90:91], v[6:7], v[72:73] neg_lo:[1,0,0] neg_hi:[1,0,0]
	v_add_f32_e32 v74, v74, v75
	ds_read_b128 v[88:91], v78 offset:11552
	s_waitcnt lgkmcnt(6)
	v_pk_fma_f32 v[70:71], v[92:93], v[8:9], v[70:71] neg_lo:[1,0,0] neg_hi:[1,0,0]
	v_pk_fma_f32 v[72:73], v[94:95], v[10:11], v[72:73] neg_lo:[1,0,0] neg_hi:[1,0,0]
	v_add_f32_e32 v76, v76, v77
	ds_read_b128 v[92:95], v78 offset:11568
	s_waitcnt lgkmcnt(6)
	v_pk_fma_f32 v[70:71], v[96:97], v[12:13], v[70:71] neg_lo:[1,0,0] neg_hi:[1,0,0]
	v_pk_fma_f32 v[72:73], v[98:99], v[14:15], v[72:73] neg_lo:[1,0,0] neg_hi:[1,0,0]
	v_add_f32_e32 v74, v74, v76
	ds_read_b128 v[96:99], v78 offset:11584
	s_waitcnt lgkmcnt(6)
	v_pk_fma_f32 v[70:71], v[100:101], v[16:17], v[70:71] neg_lo:[1,0,0] neg_hi:[1,0,0]
	v_pk_fma_f32 v[72:73], v[102:103], v[18:19], v[72:73] neg_lo:[1,0,0] neg_hi:[1,0,0]
	v_add_f32_e32 v43, v43, v74
	ds_read_b128 v[100:103], v78 offset:11696
	s_waitcnt lgkmcnt(6)
	v_pk_fma_f32 v[70:71], v[104:105], v[20:21], v[70:71] neg_lo:[1,0,0] neg_hi:[1,0,0]
	v_pk_fma_f32 v[72:73], v[106:107], v[22:23], v[72:73] neg_lo:[1,0,0] neg_hi:[1,0,0]
	ds_read_b128 v[104:107], v78 offset:11712
	s_waitcnt lgkmcnt(6)
	v_pk_fma_f32 v[70:71], v[108:109], v[24:25], v[70:71] neg_lo:[1,0,0] neg_hi:[1,0,0]
	v_pk_fma_f32 v[72:73], v[110:111], v[26:27], v[72:73] neg_lo:[1,0,0] neg_hi:[1,0,0]
	ds_read_b128 v[108:111], v78 offset:11728
	s_waitcnt lgkmcnt(6)
	v_pk_fma_f32 v[70:71], v[84:85], v[28:29], v[70:71] neg_lo:[1,0,0] neg_hi:[1,0,0]
	v_pk_fma_f32 v[72:73], v[86:87], v[30:31], v[72:73] neg_lo:[1,0,0] neg_hi:[1,0,0]
	ds_read_b128 v[84:87], v78 offset:11744
	s_waitcnt lgkmcnt(6)
	v_pk_fma_f32 v[70:71], v[88:89], v[34:35], v[70:71] neg_lo:[1,0,0] neg_hi:[1,0,0]
	v_pk_fma_f32 v[72:73], v[90:91], v[36:37], v[72:73] neg_lo:[1,0,0] neg_hi:[1,0,0]
	ds_read_b128 v[88:91], v78 offset:11760
	s_waitcnt lgkmcnt(6)
	v_pk_fma_f32 v[70:71], v[92:93], v[38:39], v[70:71] neg_lo:[1,0,0] neg_hi:[1,0,0]
	v_pk_fma_f32 v[72:73], v[94:95], v[40:41], v[72:73] neg_lo:[1,0,0] neg_hi:[1,0,0]
	ds_read_b128 v[92:95], v78 offset:11776
	s_waitcnt lgkmcnt(6)
	v_fma_f32 v70, -v42, v96, v70
	v_mov_b32_e32 v68, v97
	ds_read_b128 v[96:99], v78 offset:11792
	s_waitcnt lgkmcnt(6)
	v_pk_fma_f32 v[74:75], v[100:101], v[0:1], 0 neg_lo:[1,0,0] neg_hi:[1,0,0]
	v_pk_fma_f32 v[76:77], v[102:103], v[2:3], 0 neg_lo:[1,0,0] neg_hi:[1,0,0]
	v_fma_f32 v71, -v43, v68, v71
	ds_read_b128 v[100:103], v78 offset:11808
	s_waitcnt lgkmcnt(6)
	v_pk_fma_f32 v[74:75], v[104:105], v[4:5], v[74:75] neg_lo:[1,0,0] neg_hi:[1,0,0]
	v_pk_fma_f32 v[76:77], v[106:107], v[6:7], v[76:77] neg_lo:[1,0,0] neg_hi:[1,0,0]
	v_add_f32_e32 v70, v70, v71
	ds_read_b128 v[104:107], v78 offset:11824
	s_waitcnt lgkmcnt(6)
	v_pk_fma_f32 v[74:75], v[108:109], v[8:9], v[74:75] neg_lo:[1,0,0] neg_hi:[1,0,0]
	v_pk_fma_f32 v[76:77], v[110:111], v[10:11], v[76:77] neg_lo:[1,0,0] neg_hi:[1,0,0]
	v_add_f32_e32 v72, v72, v73
	ds_read_b128 v[108:111], v78 offset:11840
	s_waitcnt lgkmcnt(6)
	v_pk_fma_f32 v[74:75], v[84:85], v[12:13], v[74:75] neg_lo:[1,0,0] neg_hi:[1,0,0]
	v_pk_fma_f32 v[76:77], v[86:87], v[14:15], v[76:77] neg_lo:[1,0,0] neg_hi:[1,0,0]
	v_add_f32_e32 v70, v70, v72
	ds_read_b128 v[84:87], v78 offset:11856
	s_waitcnt lgkmcnt(6)
	v_pk_fma_f32 v[74:75], v[88:89], v[16:17], v[74:75] neg_lo:[1,0,0] neg_hi:[1,0,0]
	v_pk_fma_f32 v[76:77], v[90:91], v[18:19], v[76:77] neg_lo:[1,0,0] neg_hi:[1,0,0]
	v_add_f32_e32 v44, v44, v70
	ds_read_b128 v[88:91], v78 offset:11968
	s_waitcnt lgkmcnt(6)
	v_pk_fma_f32 v[74:75], v[92:93], v[20:21], v[74:75] neg_lo:[1,0,0] neg_hi:[1,0,0]
	v_pk_fma_f32 v[76:77], v[94:95], v[22:23], v[76:77] neg_lo:[1,0,0] neg_hi:[1,0,0]
	ds_read_b128 v[92:95], v78 offset:11984
	s_waitcnt lgkmcnt(6)
	v_pk_fma_f32 v[74:75], v[96:97], v[24:25], v[74:75] neg_lo:[1,0,0] neg_hi:[1,0,0]
	v_pk_fma_f32 v[76:77], v[98:99], v[26:27], v[76:77] neg_lo:[1,0,0] neg_hi:[1,0,0]
	ds_read_b128 v[96:99], v78 offset:12000
	s_waitcnt lgkmcnt(6)
	v_pk_fma_f32 v[74:75], v[100:101], v[28:29], v[74:75] neg_lo:[1,0,0] neg_hi:[1,0,0]
	v_pk_fma_f32 v[76:77], v[102:103], v[30:31], v[76:77] neg_lo:[1,0,0] neg_hi:[1,0,0]
	ds_read_b128 v[100:103], v78 offset:12016
	s_waitcnt lgkmcnt(6)
	v_pk_fma_f32 v[74:75], v[104:105], v[34:35], v[74:75] neg_lo:[1,0,0] neg_hi:[1,0,0]
	v_pk_fma_f32 v[76:77], v[106:107], v[36:37], v[76:77] neg_lo:[1,0,0] neg_hi:[1,0,0]
	ds_read_b128 v[104:107], v78 offset:12032
	s_waitcnt lgkmcnt(6)
	v_pk_fma_f32 v[74:75], v[108:109], v[38:39], v[74:75] neg_lo:[1,0,0] neg_hi:[1,0,0]
	v_pk_fma_f32 v[76:77], v[110:111], v[40:41], v[76:77] neg_lo:[1,0,0] neg_hi:[1,0,0]
	ds_read_b128 v[108:111], v78 offset:12048
	s_waitcnt lgkmcnt(6)
	v_pk_fma_f32 v[74:75], v[84:85], v[42:43], v[74:75] neg_lo:[1,0,0] neg_hi:[1,0,0]
	v_mov_b32_e32 v69, v86
	ds_read_b128 v[84:87], v78 offset:12064
	s_waitcnt lgkmcnt(6)
	v_pk_fma_f32 v[70:71], v[88:89], v[0:1], 0 neg_lo:[1,0,0] neg_hi:[1,0,0]
	v_pk_fma_f32 v[72:73], v[90:91], v[2:3], 0 neg_lo:[1,0,0] neg_hi:[1,0,0]
	v_fma_f32 v76, -v44, v69, v76
	ds_read_b128 v[88:91], v78 offset:12080
	s_waitcnt lgkmcnt(6)
	v_pk_fma_f32 v[70:71], v[92:93], v[4:5], v[70:71] neg_lo:[1,0,0] neg_hi:[1,0,0]
	v_pk_fma_f32 v[72:73], v[94:95], v[6:7], v[72:73] neg_lo:[1,0,0] neg_hi:[1,0,0]
	v_add_f32_e32 v74, v74, v75
	ds_read_b128 v[92:95], v78 offset:12096
	s_waitcnt lgkmcnt(6)
	v_pk_fma_f32 v[70:71], v[96:97], v[8:9], v[70:71] neg_lo:[1,0,0] neg_hi:[1,0,0]
	v_pk_fma_f32 v[72:73], v[98:99], v[10:11], v[72:73] neg_lo:[1,0,0] neg_hi:[1,0,0]
	v_add_f32_e32 v76, v76, v77
	ds_read_b128 v[96:99], v78 offset:12112
	s_waitcnt lgkmcnt(6)
; DI void gdn_prep(const Params& p, int item, unsigned char* smem) {
;     ...
; #pragma unroll
;         for (int i = 1; i < 64; ++i) {
;             float a = X[i];
;             int dep; asm volatile("v_and_b32 %0, 0, %1" : "=v"(dep) : "v"(X[i - 1]));
;             const float* Lr = sL + i * 68 + dep;
;             float b0 = 0.f, b1 = 0.f, b2 = 0.f;
; #pragma unroll
;             for (int j4 = 0; j4 < (i + 3) / 4; ++j4) {
;                 const f32x4 l = *(const f32x4*)(Lr + 4 * j4);
;                 if (4 * j4 + 0 < i) a -= l.x * X[4 * j4 + 0];
;                 if (4 * j4 + 1 < i) b0 -= l.y * X[4 * j4 + 1];
;                 if (4 * j4 + 2 < i) b1 -= l.z * X[4 * j4 + 2];
;                 if (4 * j4 + 3 < i) b2 -= l.w * X[4 * j4 + 3];
;             }
;             X[i] = (a + b0) + (b1 + b2);
;         }
	v_pk_fma_f32 v[70:71], v[100:101], v[12:13], v[70:71] neg_lo:[1,0,0] neg_hi:[1,0,0]
	v_pk_fma_f32 v[72:73], v[102:103], v[14:15], v[72:73] neg_lo:[1,0,0] neg_hi:[1,0,0]
	v_add_f32_e32 v74, v74, v76
	ds_read_b128 v[100:103], v78 offset:12128
	s_waitcnt lgkmcnt(6)
	v_pk_fma_f32 v[70:71], v[104:105], v[16:17], v[70:71] neg_lo:[1,0,0] neg_hi:[1,0,0]
	v_pk_fma_f32 v[72:73], v[106:107], v[18:19], v[72:73] neg_lo:[1,0,0] neg_hi:[1,0,0]
	v_add_f32_e32 v45, v45, v74
	ds_read_b128 v[104:107], v78 offset:12240
	s_waitcnt lgkmcnt(6)
	v_pk_fma_f32 v[70:71], v[108:109], v[20:21], v[70:71] neg_lo:[1,0,0] neg_hi:[1,0,0]
	v_pk_fma_f32 v[72:73], v[110:111], v[22:23], v[72:73] neg_lo:[1,0,0] neg_hi:[1,0,0]
	ds_read_b128 v[108:111], v78 offset:12256
	s_waitcnt lgkmcnt(6)
	v_pk_fma_f32 v[70:71], v[84:85], v[24:25], v[70:71] neg_lo:[1,0,0] neg_hi:[1,0,0]
	v_pk_fma_f32 v[72:73], v[86:87], v[26:27], v[72:73] neg_lo:[1,0,0] neg_hi:[1,0,0]
	ds_read_b128 v[84:87], v78 offset:12272
	s_waitcnt lgkmcnt(6)
	v_pk_fma_f32 v[70:71], v[88:89], v[28:29], v[70:71] neg_lo:[1,0,0] neg_hi:[1,0,0]
	v_pk_fma_f32 v[72:73], v[90:91], v[30:31], v[72:73] neg_lo:[1,0,0] neg_hi:[1,0,0]
	ds_read_b128 v[88:91], v78 offset:12288
	s_waitcnt lgkmcnt(6)
	v_pk_fma_f32 v[70:71], v[92:93], v[34:35], v[70:71] neg_lo:[1,0,0] neg_hi:[1,0,0]
	v_pk_fma_f32 v[72:73], v[94:95], v[36:37], v[72:73] neg_lo:[1,0,0] neg_hi:[1,0,0]
	ds_read_b128 v[92:95], v78 offset:12304
	s_waitcnt lgkmcnt(6)
	v_pk_fma_f32 v[70:71], v[96:97], v[38:39], v[70:71] neg_lo:[1,0,0] neg_hi:[1,0,0]
	v_pk_fma_f32 v[72:73], v[98:99], v[40:41], v[72:73] neg_lo:[1,0,0] neg_hi:[1,0,0]
	ds_read_b128 v[96:99], v78 offset:12320
	s_waitcnt lgkmcnt(6)
	v_pk_fma_f32 v[70:71], v[100:101], v[42:43], v[70:71] neg_lo:[1,0,0] neg_hi:[1,0,0]
	v_fma_f32 v72, -v44, v102, v72
	v_mov_b32_e32 v68, v103
	ds_read_b128 v[100:103], v78 offset:12336
	s_waitcnt lgkmcnt(6)
	v_pk_fma_f32 v[74:75], v[104:105], v[0:1], 0 neg_lo:[1,0,0] neg_hi:[1,0,0]
	v_pk_fma_f32 v[76:77], v[106:107], v[2:3], 0 neg_lo:[1,0,0] neg_hi:[1,0,0]
	v_fma_f32 v73, -v45, v68, v73
	ds_read_b128 v[104:107], v78 offset:12352
	s_waitcnt lgkmcnt(6)
	v_pk_fma_f32 v[74:75], v[108:109], v[4:5], v[74:75] neg_lo:[1,0,0] neg_hi:[1,0,0]
	v_pk_fma_f32 v[76:77], v[110:111], v[6:7], v[76:77] neg_lo:[1,0,0] neg_hi:[1,0,0]
	v_add_f32_e32 v70, v70, v71
	ds_read_b128 v[108:111], v78 offset:12368
	s_waitcnt lgkmcnt(6)
	v_pk_fma_f32 v[74:75], v[84:85], v[8:9], v[74:75] neg_lo:[1,0,0] neg_hi:[1,0,0]
	v_pk_fma_f32 v[76:77], v[86:87], v[10:11], v[76:77] neg_lo:[1,0,0] neg_hi:[1,0,0]
	v_add_f32_e32 v72, v72, v73
	ds_read_b128 v[84:87], v78 offset:12384
	s_waitcnt lgkmcnt(6)
	v_pk_fma_f32 v[74:75], v[88:89], v[12:13], v[74:75] neg_lo:[1,0,0] neg_hi:[1,0,0]
	v_pk_fma_f32 v[76:77], v[90:91], v[14:15], v[76:77] neg_lo:[1,0,0] neg_hi:[1,0,0]
	v_add_f32_e32 v70, v70, v72
	ds_read_b128 v[88:91], v78 offset:12400
	s_waitcnt lgkmcnt(6)
	v_pk_fma_f32 v[74:75], v[92:93], v[16:17], v[74:75] neg_lo:[1,0,0] neg_hi:[1,0,0]
	v_pk_fma_f32 v[76:77], v[94:95], v[18:19], v[76:77] neg_lo:[1,0,0] neg_hi:[1,0,0]
	v_add_f32_e32 v48, v48, v70
	ds_read_b128 v[92:95], v78 offset:12416
	s_waitcnt lgkmcnt(6)
	v_pk_fma_f32 v[74:75], v[96:97], v[20:21], v[74:75] neg_lo:[1,0,0] neg_hi:[1,0,0]
	v_pk_fma_f32 v[76:77], v[98:99], v[22:23], v[76:77] neg_lo:[1,0,0] neg_hi:[1,0,0]
	ds_read_b128 v[96:99], v78 offset:12512
	s_waitcnt lgkmcnt(6)
	v_pk_fma_f32 v[74:75], v[100:101], v[24:25], v[74:75] neg_lo:[1,0,0] neg_hi:[1,0,0]
	v_pk_fma_f32 v[76:77], v[102:103], v[26:27], v[76:77] neg_lo:[1,0,0] neg_hi:[1,0,0]
	ds_read_b128 v[100:103], v78 offset:12528
	s_waitcnt lgkmcnt(6)
	v_pk_fma_f32 v[74:75], v[104:105], v[28:29], v[74:75] neg_lo:[1,0,0] neg_hi:[1,0,0]
	v_pk_fma_f32 v[76:77], v[106:107], v[30:31], v[76:77] neg_lo:[1,0,0] neg_hi:[1,0,0]
	ds_read_b128 v[104:107], v78 offset:12544
	s_waitcnt lgkmcnt(6)
	v_pk_fma_f32 v[74:75], v[108:109], v[34:35], v[74:75] neg_lo:[1,0,0] neg_hi:[1,0,0]
	v_pk_fma_f32 v[76:77], v[110:111], v[36:37], v[76:77] neg_lo:[1,0,0] neg_hi:[1,0,0]
	ds_read_b128 v[108:111], v78 offset:12560
	s_waitcnt lgkmcnt(6)
	v_pk_fma_f32 v[74:75], v[84:85], v[38:39], v[74:75] neg_lo:[1,0,0] neg_hi:[1,0,0]
	v_pk_fma_f32 v[76:77], v[86:87], v[40:41], v[76:77] neg_lo:[1,0,0] neg_hi:[1,0,0]
	ds_read_b128 v[84:87], v78 offset:12576
	s_waitcnt lgkmcnt(6)
	v_pk_fma_f32 v[74:75], v[88:89], v[42:43], v[74:75] neg_lo:[1,0,0] neg_hi:[1,0,0]
	v_pk_fma_f32 v[76:77], v[90:91], v[44:45], v[76:77] neg_lo:[1,0,0] neg_hi:[1,0,0]
	ds_read_b128 v[88:91], v78 offset:12592
	s_waitcnt lgkmcnt(6)
	v_mov_b32_e32 v69, v92
	ds_read_b128 v[92:95], v78 offset:12608
	s_waitcnt lgkmcnt(6)
	v_pk_fma_f32 v[70:71], v[96:97], v[0:1], 0 neg_lo:[1,0,0] neg_hi:[1,0,0]
	v_pk_fma_f32 v[72:73], v[98:99], v[2:3], 0 neg_lo:[1,0,0] neg_hi:[1,0,0]
	v_fma_f32 v74, -v48, v69, v74
	ds_read_b128 v[96:99], v78 offset:12624
	s_waitcnt lgkmcnt(6)
	v_pk_fma_f32 v[70:71], v[100:101], v[4:5], v[70:71] neg_lo:[1,0,0] neg_hi:[1,0,0]
	v_pk_fma_f32 v[72:73], v[102:103], v[6:7], v[72:73] neg_lo:[1,0,0] neg_hi:[1,0,0]
	v_add_f32_e32 v74, v74, v75
	ds_read_b128 v[100:103], v78 offset:12640
	s_waitcnt lgkmcnt(6)
	v_pk_fma_f32 v[70:71], v[104:105], v[8:9], v[70:71] neg_lo:[1,0,0] neg_hi:[1,0,0]
	v_pk_fma_f32 v[72:73], v[106:107], v[10:11], v[72:73] neg_lo:[1,0,0] neg_hi:[1,0,0]
	v_add_f32_e32 v76, v76, v77
	ds_read_b128 v[104:107], v78 offset:12656
	s_waitcnt lgkmcnt(6)
	v_pk_fma_f32 v[70:71], v[108:109], v[12:13], v[70:71] neg_lo:[1,0,0] neg_hi:[1,0,0]
	v_pk_fma_f32 v[72:73], v[110:111], v[14:15], v[72:73] neg_lo:[1,0,0] neg_hi:[1,0,0]
	v_add_f32_e32 v74, v74, v76
	ds_read_b128 v[108:111], v78 offset:12672
	s_waitcnt lgkmcnt(6)
; DI void gdn_prep(const Params& p, int item, unsigned char* smem) {
;     ...
; #pragma unroll
;         for (int i = 1; i < 64; ++i) {
;             float a = X[i];
;             int dep; asm volatile("v_and_b32 %0, 0, %1" : "=v"(dep) : "v"(X[i - 1]));
;             const float* Lr = sL + i * 68 + dep;
;             float b0 = 0.f, b1 = 0.f, b2 = 0.f;
; #pragma unroll
;             for (int j4 = 0; j4 < (i + 3) / 4; ++j4) {
;                 const f32x4 l = *(const f32x4*)(Lr + 4 * j4);
;                 if (4 * j4 + 0 < i) a -= l.x * X[4 * j4 + 0];
;                 if (4 * j4 + 1 < i) b0 -= l.y * X[4 * j4 + 1];
;                 if (4 * j4 + 2 < i) b1 -= l.z * X[4 * j4 + 2];
;                 if (4 * j4 + 3 < i) b2 -= l.w * X[4 * j4 + 3];
;             }
;             X[i] = (a + b0) + (b1 + b2);
;         }
	v_pk_fma_f32 v[70:71], v[84:85], v[16:17], v[70:71] neg_lo:[1,0,0] neg_hi:[1,0,0]
	v_pk_fma_f32 v[72:73], v[86:87], v[18:19], v[72:73] neg_lo:[1,0,0] neg_hi:[1,0,0]
	v_add_f32_e32 v49, v49, v74
	ds_read_b128 v[84:87], v78 offset:12688
	s_waitcnt lgkmcnt(6)
	v_pk_fma_f32 v[70:71], v[88:89], v[20:21], v[70:71] neg_lo:[1,0,0] neg_hi:[1,0,0]
	v_pk_fma_f32 v[72:73], v[90:91], v[22:23], v[72:73] neg_lo:[1,0,0] neg_hi:[1,0,0]
	ds_read_b128 v[88:91], v78 offset:12784
	s_waitcnt lgkmcnt(6)
	v_pk_fma_f32 v[70:71], v[92:93], v[24:25], v[70:71] neg_lo:[1,0,0] neg_hi:[1,0,0]
	v_pk_fma_f32 v[72:73], v[94:95], v[26:27], v[72:73] neg_lo:[1,0,0] neg_hi:[1,0,0]
	ds_read_b128 v[92:95], v78 offset:12800
	s_waitcnt lgkmcnt(6)
	v_pk_fma_f32 v[70:71], v[96:97], v[28:29], v[70:71] neg_lo:[1,0,0] neg_hi:[1,0,0]
	v_pk_fma_f32 v[72:73], v[98:99], v[30:31], v[72:73] neg_lo:[1,0,0] neg_hi:[1,0,0]
	ds_read_b128 v[96:99], v78 offset:12816
	s_waitcnt lgkmcnt(6)
	v_pk_fma_f32 v[70:71], v[100:101], v[34:35], v[70:71] neg_lo:[1,0,0] neg_hi:[1,0,0]
	v_pk_fma_f32 v[72:73], v[102:103], v[36:37], v[72:73] neg_lo:[1,0,0] neg_hi:[1,0,0]
	ds_read_b128 v[100:103], v78 offset:12832
	s_waitcnt lgkmcnt(6)
	v_pk_fma_f32 v[70:71], v[104:105], v[38:39], v[70:71] neg_lo:[1,0,0] neg_hi:[1,0,0]
	v_pk_fma_f32 v[72:73], v[106:107], v[40:41], v[72:73] neg_lo:[1,0,0] neg_hi:[1,0,0]
	ds_read_b128 v[104:107], v78 offset:12848
	s_waitcnt lgkmcnt(6)
	v_pk_fma_f32 v[70:71], v[108:109], v[42:43], v[70:71] neg_lo:[1,0,0] neg_hi:[1,0,0]
	v_pk_fma_f32 v[72:73], v[110:111], v[44:45], v[72:73] neg_lo:[1,0,0] neg_hi:[1,0,0]
	ds_read_b128 v[108:111], v78 offset:12864
	s_waitcnt lgkmcnt(6)
	v_fma_f32 v70, -v48, v84, v70
	v_mov_b32_e32 v68, v85
	ds_read_b128 v[84:87], v78 offset:12880
	s_waitcnt lgkmcnt(6)
	v_pk_fma_f32 v[74:75], v[88:89], v[0:1], 0 neg_lo:[1,0,0] neg_hi:[1,0,0]
	v_pk_fma_f32 v[76:77], v[90:91], v[2:3], 0 neg_lo:[1,0,0] neg_hi:[1,0,0]
	v_fma_f32 v71, -v49, v68, v71
	ds_read_b128 v[88:91], v78 offset:12896
	s_waitcnt lgkmcnt(6)
	v_pk_fma_f32 v[74:75], v[92:93], v[4:5], v[74:75] neg_lo:[1,0,0] neg_hi:[1,0,0]
	v_pk_fma_f32 v[76:77], v[94:95], v[6:7], v[76:77] neg_lo:[1,0,0] neg_hi:[1,0,0]
	v_add_f32_e32 v70, v70, v71
	ds_read_b128 v[92:95], v78 offset:12912
	s_waitcnt lgkmcnt(6)
	v_pk_fma_f32 v[74:75], v[96:97], v[8:9], v[74:75] neg_lo:[1,0,0] neg_hi:[1,0,0]
	v_pk_fma_f32 v[76:77], v[98:99], v[10:11], v[76:77] neg_lo:[1,0,0] neg_hi:[1,0,0]
	v_add_f32_e32 v72, v72, v73
	ds_read_b128 v[96:99], v78 offset:12928
	s_waitcnt lgkmcnt(6)
	v_pk_fma_f32 v[74:75], v[100:101], v[12:13], v[74:75] neg_lo:[1,0,0] neg_hi:[1,0,0]
	v_pk_fma_f32 v[76:77], v[102:103], v[14:15], v[76:77] neg_lo:[1,0,0] neg_hi:[1,0,0]
	v_add_f32_e32 v70, v70, v72
	ds_read_b128 v[100:103], v78 offset:12944
	s_waitcnt lgkmcnt(6)
	v_pk_fma_f32 v[74:75], v[104:105], v[16:17], v[74:75] neg_lo:[1,0,0] neg_hi:[1,0,0]
	v_pk_fma_f32 v[76:77], v[106:107], v[18:19], v[76:77] neg_lo:[1,0,0] neg_hi:[1,0,0]
	v_add_f32_e32 v50, v50, v70
	ds_read_b128 v[104:107], v78 offset:12960
	s_waitcnt lgkmcnt(6)
	v_pk_fma_f32 v[74:75], v[108:109], v[20:21], v[74:75] neg_lo:[1,0,0] neg_hi:[1,0,0]
	v_pk_fma_f32 v[76:77], v[110:111], v[22:23], v[76:77] neg_lo:[1,0,0] neg_hi:[1,0,0]
	ds_read_b128 v[108:111], v78 offset:13056
	s_waitcnt lgkmcnt(6)
	v_pk_fma_f32 v[74:75], v[84:85], v[24:25], v[74:75] neg_lo:[1,0,0] neg_hi:[1,0,0]
	v_pk_fma_f32 v[76:77], v[86:87], v[26:27], v[76:77] neg_lo:[1,0,0] neg_hi:[1,0,0]
	ds_read_b128 v[84:87], v78 offset:13072
	s_waitcnt lgkmcnt(6)
	v_pk_fma_f32 v[74:75], v[88:89], v[28:29], v[74:75] neg_lo:[1,0,0] neg_hi:[1,0,0]
	v_pk_fma_f32 v[76:77], v[90:91], v[30:31], v[76:77] neg_lo:[1,0,0] neg_hi:[1,0,0]
	ds_read_b128 v[88:91], v78 offset:13088
	s_waitcnt lgkmcnt(6)
	v_pk_fma_f32 v[74:75], v[92:93], v[34:35], v[74:75] neg_lo:[1,0,0] neg_hi:[1,0,0]
	v_pk_fma_f32 v[76:77], v[94:95], v[36:37], v[76:77] neg_lo:[1,0,0] neg_hi:[1,0,0]
	ds_read_b128 v[92:95], v78 offset:13104
	s_waitcnt lgkmcnt(6)
	v_pk_fma_f32 v[74:75], v[96:97], v[38:39], v[74:75] neg_lo:[1,0,0] neg_hi:[1,0,0]
	v_pk_fma_f32 v[76:77], v[98:99], v[40:41], v[76:77] neg_lo:[1,0,0] neg_hi:[1,0,0]
	ds_read_b128 v[96:99], v78 offset:13120
	s_waitcnt lgkmcnt(6)
	v_pk_fma_f32 v[74:75], v[100:101], v[42:43], v[74:75] neg_lo:[1,0,0] neg_hi:[1,0,0]
	v_pk_fma_f32 v[76:77], v[102:103], v[44:45], v[76:77] neg_lo:[1,0,0] neg_hi:[1,0,0]
	ds_read_b128 v[100:103], v78 offset:13136
	s_waitcnt lgkmcnt(6)
	v_pk_fma_f32 v[74:75], v[104:105], v[48:49], v[74:75] neg_lo:[1,0,0] neg_hi:[1,0,0]
	v_mov_b32_e32 v69, v106
	ds_read_b128 v[104:107], v78 offset:13152
	s_waitcnt lgkmcnt(6)
	v_pk_fma_f32 v[70:71], v[108:109], v[0:1], 0 neg_lo:[1,0,0] neg_hi:[1,0,0]
	v_pk_fma_f32 v[72:73], v[110:111], v[2:3], 0 neg_lo:[1,0,0] neg_hi:[1,0,0]
	v_fma_f32 v76, -v50, v69, v76
	ds_read_b128 v[108:111], v78 offset:13168
	s_waitcnt lgkmcnt(6)
	v_pk_fma_f32 v[70:71], v[84:85], v[4:5], v[70:71] neg_lo:[1,0,0] neg_hi:[1,0,0]
	v_pk_fma_f32 v[72:73], v[86:87], v[6:7], v[72:73] neg_lo:[1,0,0] neg_hi:[1,0,0]
	v_add_f32_e32 v74, v74, v75
	ds_read_b128 v[84:87], v78 offset:13184
	s_waitcnt lgkmcnt(6)
	v_pk_fma_f32 v[70:71], v[88:89], v[8:9], v[70:71] neg_lo:[1,0,0] neg_hi:[1,0,0]
	v_pk_fma_f32 v[72:73], v[90:91], v[10:11], v[72:73] neg_lo:[1,0,0] neg_hi:[1,0,0]
	v_add_f32_e32 v76, v76, v77
	ds_read_b128 v[88:91], v78 offset:13200
	s_waitcnt lgkmcnt(6)
	v_pk_fma_f32 v[70:71], v[92:93], v[12:13], v[70:71] neg_lo:[1,0,0] neg_hi:[1,0,0]
	v_pk_fma_f32 v[72:73], v[94:95], v[14:15], v[72:73] neg_lo:[1,0,0] neg_hi:[1,0,0]
	v_add_f32_e32 v74, v74, v76
	ds_read_b128 v[92:95], v78 offset:13216
	s_waitcnt lgkmcnt(6)
; DI void gdn_prep(const Params& p, int item, unsigned char* smem) {
;     ...
; #pragma unroll
;         for (int i = 1; i < 64; ++i) {
;             float a = X[i];
;             int dep; asm volatile("v_and_b32 %0, 0, %1" : "=v"(dep) : "v"(X[i - 1]));
;             const float* Lr = sL + i * 68 + dep;
;             float b0 = 0.f, b1 = 0.f, b2 = 0.f;
; #pragma unroll
;             for (int j4 = 0; j4 < (i + 3) / 4; ++j4) {
;                 const f32x4 l = *(const f32x4*)(Lr + 4 * j4);
;                 if (4 * j4 + 0 < i) a -= l.x * X[4 * j4 + 0];
;                 if (4 * j4 + 1 < i) b0 -= l.y * X[4 * j4 + 1];
;                 if (4 * j4 + 2 < i) b1 -= l.z * X[4 * j4 + 2];
;                 if (4 * j4 + 3 < i) b2 -= l.w * X[4 * j4 + 3];
;             }
;             X[i] = (a + b0) + (b1 + b2);
;         }
	v_pk_fma_f32 v[70:71], v[96:97], v[16:17], v[70:71] neg_lo:[1,0,0] neg_hi:[1,0,0]
	v_pk_fma_f32 v[72:73], v[98:99], v[18:19], v[72:73] neg_lo:[1,0,0] neg_hi:[1,0,0]
	v_add_f32_e32 v51, v51, v74
	ds_read_b128 v[96:99], v78 offset:13232
	s_waitcnt lgkmcnt(6)
	v_pk_fma_f32 v[70:71], v[100:101], v[20:21], v[70:71] neg_lo:[1,0,0] neg_hi:[1,0,0]
	v_pk_fma_f32 v[72:73], v[102:103], v[22:23], v[72:73] neg_lo:[1,0,0] neg_hi:[1,0,0]
	ds_read_b128 v[100:103], v78 offset:13328
	s_waitcnt lgkmcnt(6)
	v_pk_fma_f32 v[70:71], v[104:105], v[24:25], v[70:71] neg_lo:[1,0,0] neg_hi:[1,0,0]
	v_pk_fma_f32 v[72:73], v[106:107], v[26:27], v[72:73] neg_lo:[1,0,0] neg_hi:[1,0,0]
	ds_read_b128 v[104:107], v78 offset:13344
	s_waitcnt lgkmcnt(6)
	v_pk_fma_f32 v[70:71], v[108:109], v[28:29], v[70:71] neg_lo:[1,0,0] neg_hi:[1,0,0]
	v_pk_fma_f32 v[72:73], v[110:111], v[30:31], v[72:73] neg_lo:[1,0,0] neg_hi:[1,0,0]
	ds_read_b128 v[108:111], v78 offset:13360
	s_waitcnt lgkmcnt(6)
	v_pk_fma_f32 v[70:71], v[84:85], v[34:35], v[70:71] neg_lo:[1,0,0] neg_hi:[1,0,0]
	v_pk_fma_f32 v[72:73], v[86:87], v[36:37], v[72:73] neg_lo:[1,0,0] neg_hi:[1,0,0]
	ds_read_b128 v[84:87], v78 offset:13376
	s_waitcnt lgkmcnt(6)
	v_pk_fma_f32 v[70:71], v[88:89], v[38:39], v[70:71] neg_lo:[1,0,0] neg_hi:[1,0,0]
	v_pk_fma_f32 v[72:73], v[90:91], v[40:41], v[72:73] neg_lo:[1,0,0] neg_hi:[1,0,0]
	ds_read_b128 v[88:91], v78 offset:13392
	s_waitcnt lgkmcnt(6)
	v_pk_fma_f32 v[70:71], v[92:93], v[42:43], v[70:71] neg_lo:[1,0,0] neg_hi:[1,0,0]
	v_pk_fma_f32 v[72:73], v[94:95], v[44:45], v[72:73] neg_lo:[1,0,0] neg_hi:[1,0,0]
	ds_read_b128 v[92:95], v78 offset:13408
	s_waitcnt lgkmcnt(6)
	v_pk_fma_f32 v[70:71], v[96:97], v[48:49], v[70:71] neg_lo:[1,0,0] neg_hi:[1,0,0]
	v_fma_f32 v72, -v50, v98, v72
	v_mov_b32_e32 v68, v99
	ds_read_b128 v[96:99], v78 offset:13424
	s_waitcnt lgkmcnt(6)
	v_pk_fma_f32 v[74:75], v[100:101], v[0:1], 0 neg_lo:[1,0,0] neg_hi:[1,0,0]
	v_pk_fma_f32 v[76:77], v[102:103], v[2:3], 0 neg_lo:[1,0,0] neg_hi:[1,0,0]
	v_fma_f32 v73, -v51, v68, v73
	ds_read_b128 v[100:103], v78 offset:13440
	s_waitcnt lgkmcnt(6)
	v_pk_fma_f32 v[74:75], v[104:105], v[4:5], v[74:75] neg_lo:[1,0,0] neg_hi:[1,0,0]
	v_pk_fma_f32 v[76:77], v[106:107], v[6:7], v[76:77] neg_lo:[1,0,0] neg_hi:[1,0,0]
	v_add_f32_e32 v70, v70, v71
	ds_read_b128 v[104:107], v78 offset:13456
	s_waitcnt lgkmcnt(6)
	v_pk_fma_f32 v[74:75], v[108:109], v[8:9], v[74:75] neg_lo:[1,0,0] neg_hi:[1,0,0]
	v_pk_fma_f32 v[76:77], v[110:111], v[10:11], v[76:77] neg_lo:[1,0,0] neg_hi:[1,0,0]
	v_add_f32_e32 v72, v72, v73
	ds_read_b128 v[108:111], v78 offset:13472
	s_waitcnt lgkmcnt(6)
	v_pk_fma_f32 v[74:75], v[84:85], v[12:13], v[74:75] neg_lo:[1,0,0] neg_hi:[1,0,0]
	v_pk_fma_f32 v[76:77], v[86:87], v[14:15], v[76:77] neg_lo:[1,0,0] neg_hi:[1,0,0]
	v_add_f32_e32 v70, v70, v72
	ds_read_b128 v[84:87], v78 offset:13488
	s_waitcnt lgkmcnt(6)
	v_pk_fma_f32 v[74:75], v[88:89], v[16:17], v[74:75] neg_lo:[1,0,0] neg_hi:[1,0,0]
	v_pk_fma_f32 v[76:77], v[90:91], v[18:19], v[76:77] neg_lo:[1,0,0] neg_hi:[1,0,0]
	v_add_f32_e32 v52, v52, v70
	ds_read_b128 v[88:91], v78 offset:13504
	s_waitcnt lgkmcnt(6)
	v_pk_fma_f32 v[74:75], v[92:93], v[20:21], v[74:75] neg_lo:[1,0,0] neg_hi:[1,0,0]
	v_pk_fma_f32 v[76:77], v[94:95], v[22:23], v[76:77] neg_lo:[1,0,0] neg_hi:[1,0,0]
	ds_read_b128 v[92:95], v78 offset:13520
	s_waitcnt lgkmcnt(6)
	v_pk_fma_f32 v[74:75], v[96:97], v[24:25], v[74:75] neg_lo:[1,0,0] neg_hi:[1,0,0]
	v_pk_fma_f32 v[76:77], v[98:99], v[26:27], v[76:77] neg_lo:[1,0,0] neg_hi:[1,0,0]
	ds_read_b128 v[96:99], v78 offset:13600
	s_waitcnt lgkmcnt(6)
	v_pk_fma_f32 v[74:75], v[100:101], v[28:29], v[74:75] neg_lo:[1,0,0] neg_hi:[1,0,0]
	v_pk_fma_f32 v[76:77], v[102:103], v[30:31], v[76:77] neg_lo:[1,0,0] neg_hi:[1,0,0]
	ds_read_b128 v[100:103], v78 offset:13616
	s_waitcnt lgkmcnt(6)
	v_pk_fma_f32 v[74:75], v[104:105], v[34:35], v[74:75] neg_lo:[1,0,0] neg_hi:[1,0,0]
	v_pk_fma_f32 v[76:77], v[106:107], v[36:37], v[76:77] neg_lo:[1,0,0] neg_hi:[1,0,0]
	ds_read_b128 v[104:107], v78 offset:13632
	s_waitcnt lgkmcnt(6)
	v_pk_fma_f32 v[74:75], v[108:109], v[38:39], v[74:75] neg_lo:[1,0,0] neg_hi:[1,0,0]
	v_pk_fma_f32 v[76:77], v[110:111], v[40:41], v[76:77] neg_lo:[1,0,0] neg_hi:[1,0,0]
	ds_read_b128 v[108:111], v78 offset:13648
	s_waitcnt lgkmcnt(6)
	v_pk_fma_f32 v[74:75], v[84:85], v[42:43], v[74:75] neg_lo:[1,0,0] neg_hi:[1,0,0]
	v_pk_fma_f32 v[76:77], v[86:87], v[44:45], v[76:77] neg_lo:[1,0,0] neg_hi:[1,0,0]
	ds_read_b128 v[84:87], v78 offset:13664
	s_waitcnt lgkmcnt(6)
	v_pk_fma_f32 v[74:75], v[88:89], v[48:49], v[74:75] neg_lo:[1,0,0] neg_hi:[1,0,0]
	v_pk_fma_f32 v[76:77], v[90:91], v[50:51], v[76:77] neg_lo:[1,0,0] neg_hi:[1,0,0]
	ds_read_b128 v[88:91], v78 offset:13680
	s_waitcnt lgkmcnt(6)
	v_mov_b32_e32 v69, v92
	ds_read_b128 v[92:95], v78 offset:13696
	s_waitcnt lgkmcnt(6)
	v_pk_fma_f32 v[70:71], v[96:97], v[0:1], 0 neg_lo:[1,0,0] neg_hi:[1,0,0]
	v_pk_fma_f32 v[72:73], v[98:99], v[2:3], 0 neg_lo:[1,0,0] neg_hi:[1,0,0]
	v_fma_f32 v74, -v52, v69, v74
	ds_read_b128 v[96:99], v78 offset:13712
	s_waitcnt lgkmcnt(6)
	v_pk_fma_f32 v[70:71], v[100:101], v[4:5], v[70:71] neg_lo:[1,0,0] neg_hi:[1,0,0]
	v_pk_fma_f32 v[72:73], v[102:103], v[6:7], v[72:73] neg_lo:[1,0,0] neg_hi:[1,0,0]
	v_add_f32_e32 v74, v74, v75
	ds_read_b128 v[100:103], v78 offset:13728
	s_waitcnt lgkmcnt(6)
	v_pk_fma_f32 v[70:71], v[104:105], v[8:9], v[70:71] neg_lo:[1,0,0] neg_hi:[1,0,0]
	v_pk_fma_f32 v[72:73], v[106:107], v[10:11], v[72:73] neg_lo:[1,0,0] neg_hi:[1,0,0]
	v_add_f32_e32 v76, v76, v77
	ds_read_b128 v[104:107], v78 offset:13744
	s_waitcnt lgkmcnt(6)
; DI void gdn_prep(const Params& p, int item, unsigned char* smem) {
;     ...
; #pragma unroll
;         for (int i = 1; i < 64; ++i) {
;             float a = X[i];
;             int dep; asm volatile("v_and_b32 %0, 0, %1" : "=v"(dep) : "v"(X[i - 1]));
;             const float* Lr = sL + i * 68 + dep;
;             float b0 = 0.f, b1 = 0.f, b2 = 0.f;
; #pragma unroll
;             for (int j4 = 0; j4 < (i + 3) / 4; ++j4) {
;                 const f32x4 l = *(const f32x4*)(Lr + 4 * j4);
;                 if (4 * j4 + 0 < i) a -= l.x * X[4 * j4 + 0];
;                 if (4 * j4 + 1 < i) b0 -= l.y * X[4 * j4 + 1];
;                 if (4 * j4 + 2 < i) b1 -= l.z * X[4 * j4 + 2];
;                 if (4 * j4 + 3 < i) b2 -= l.w * X[4 * j4 + 3];
;             }
;             X[i] = (a + b0) + (b1 + b2);
;         }
	v_pk_fma_f32 v[70:71], v[108:109], v[12:13], v[70:71] neg_lo:[1,0,0] neg_hi:[1,0,0]
	v_pk_fma_f32 v[72:73], v[110:111], v[14:15], v[72:73] neg_lo:[1,0,0] neg_hi:[1,0,0]
	v_add_f32_e32 v74, v74, v76
	ds_read_b128 v[108:111], v78 offset:13760
	s_waitcnt lgkmcnt(6)
	v_pk_fma_f32 v[70:71], v[84:85], v[16:17], v[70:71] neg_lo:[1,0,0] neg_hi:[1,0,0]
	v_pk_fma_f32 v[72:73], v[86:87], v[18:19], v[72:73] neg_lo:[1,0,0] neg_hi:[1,0,0]
	v_add_f32_e32 v53, v53, v74
	ds_read_b128 v[84:87], v78 offset:13776
	s_waitcnt lgkmcnt(6)
	v_pk_fma_f32 v[70:71], v[88:89], v[20:21], v[70:71] neg_lo:[1,0,0] neg_hi:[1,0,0]
	v_pk_fma_f32 v[72:73], v[90:91], v[22:23], v[72:73] neg_lo:[1,0,0] neg_hi:[1,0,0]
	ds_read_b128 v[88:91], v78 offset:13792
	s_waitcnt lgkmcnt(6)
	v_pk_fma_f32 v[70:71], v[92:93], v[24:25], v[70:71] neg_lo:[1,0,0] neg_hi:[1,0,0]
	v_pk_fma_f32 v[72:73], v[94:95], v[26:27], v[72:73] neg_lo:[1,0,0] neg_hi:[1,0,0]
	ds_read_b128 v[92:95], v78 offset:13872
	s_waitcnt lgkmcnt(6)
	v_pk_fma_f32 v[70:71], v[96:97], v[28:29], v[70:71] neg_lo:[1,0,0] neg_hi:[1,0,0]
	v_pk_fma_f32 v[72:73], v[98:99], v[30:31], v[72:73] neg_lo:[1,0,0] neg_hi:[1,0,0]
	ds_read_b128 v[96:99], v78 offset:13888
	s_waitcnt lgkmcnt(6)
	v_pk_fma_f32 v[70:71], v[100:101], v[34:35], v[70:71] neg_lo:[1,0,0] neg_hi:[1,0,0]
	v_pk_fma_f32 v[72:73], v[102:103], v[36:37], v[72:73] neg_lo:[1,0,0] neg_hi:[1,0,0]
	ds_read_b128 v[100:103], v78 offset:13904
	s_waitcnt lgkmcnt(6)
	v_pk_fma_f32 v[70:71], v[104:105], v[38:39], v[70:71] neg_lo:[1,0,0] neg_hi:[1,0,0]
	v_pk_fma_f32 v[72:73], v[106:107], v[40:41], v[72:73] neg_lo:[1,0,0] neg_hi:[1,0,0]
	ds_read_b128 v[104:107], v78 offset:13920
	s_waitcnt lgkmcnt(6)
	v_pk_fma_f32 v[70:71], v[108:109], v[42:43], v[70:71] neg_lo:[1,0,0] neg_hi:[1,0,0]
	v_pk_fma_f32 v[72:73], v[110:111], v[44:45], v[72:73] neg_lo:[1,0,0] neg_hi:[1,0,0]
	ds_read_b128 v[108:111], v78 offset:13936
	s_waitcnt lgkmcnt(6)
	v_pk_fma_f32 v[70:71], v[84:85], v[48:49], v[70:71] neg_lo:[1,0,0] neg_hi:[1,0,0]
	v_pk_fma_f32 v[72:73], v[86:87], v[50:51], v[72:73] neg_lo:[1,0,0] neg_hi:[1,0,0]
	ds_read_b128 v[84:87], v78 offset:13952
	s_waitcnt lgkmcnt(6)
	v_fma_f32 v70, -v52, v88, v70
	v_mov_b32_e32 v68, v89
	ds_read_b128 v[88:91], v78 offset:13968
	s_waitcnt lgkmcnt(6)
	v_pk_fma_f32 v[74:75], v[92:93], v[0:1], 0 neg_lo:[1,0,0] neg_hi:[1,0,0]
	v_pk_fma_f32 v[76:77], v[94:95], v[2:3], 0 neg_lo:[1,0,0] neg_hi:[1,0,0]
	v_fma_f32 v71, -v53, v68, v71
	ds_read_b128 v[92:95], v78 offset:13984
	s_waitcnt lgkmcnt(6)
	v_pk_fma_f32 v[74:75], v[96:97], v[4:5], v[74:75] neg_lo:[1,0,0] neg_hi:[1,0,0]
	v_pk_fma_f32 v[76:77], v[98:99], v[6:7], v[76:77] neg_lo:[1,0,0] neg_hi:[1,0,0]
	v_add_f32_e32 v70, v70, v71
	ds_read_b128 v[96:99], v78 offset:14000
	s_waitcnt lgkmcnt(6)
	v_pk_fma_f32 v[74:75], v[100:101], v[8:9], v[74:75] neg_lo:[1,0,0] neg_hi:[1,0,0]
	v_pk_fma_f32 v[76:77], v[102:103], v[10:11], v[76:77] neg_lo:[1,0,0] neg_hi:[1,0,0]
	v_add_f32_e32 v72, v72, v73
	ds_read_b128 v[100:103], v78 offset:14016
	s_waitcnt lgkmcnt(6)
	v_pk_fma_f32 v[74:75], v[104:105], v[12:13], v[74:75] neg_lo:[1,0,0] neg_hi:[1,0,0]
	v_pk_fma_f32 v[76:77], v[106:107], v[14:15], v[76:77] neg_lo:[1,0,0] neg_hi:[1,0,0]
	v_add_f32_e32 v70, v70, v72
	ds_read_b128 v[104:107], v78 offset:14032
	s_waitcnt lgkmcnt(6)
	v_pk_fma_f32 v[74:75], v[108:109], v[16:17], v[74:75] neg_lo:[1,0,0] neg_hi:[1,0,0]
	v_pk_fma_f32 v[76:77], v[110:111], v[18:19], v[76:77] neg_lo:[1,0,0] neg_hi:[1,0,0]
	v_add_f32_e32 v54, v54, v70
	ds_read_b128 v[108:111], v78 offset:14048
	s_waitcnt lgkmcnt(6)
	v_pk_fma_f32 v[74:75], v[84:85], v[20:21], v[74:75] neg_lo:[1,0,0] neg_hi:[1,0,0]
	v_pk_fma_f32 v[76:77], v[86:87], v[22:23], v[76:77] neg_lo:[1,0,0] neg_hi:[1,0,0]
	ds_read_b128 v[84:87], v78 offset:14064
	s_waitcnt lgkmcnt(6)
	v_pk_fma_f32 v[74:75], v[88:89], v[24:25], v[74:75] neg_lo:[1,0,0] neg_hi:[1,0,0]
	v_pk_fma_f32 v[76:77], v[90:91], v[26:27], v[76:77] neg_lo:[1,0,0] neg_hi:[1,0,0]
	ds_read_b128 v[88:91], v78 offset:14144
	s_waitcnt lgkmcnt(6)
	v_pk_fma_f32 v[74:75], v[92:93], v[28:29], v[74:75] neg_lo:[1,0,0] neg_hi:[1,0,0]
	v_pk_fma_f32 v[76:77], v[94:95], v[30:31], v[76:77] neg_lo:[1,0,0] neg_hi:[1,0,0]
	ds_read_b128 v[92:95], v78 offset:14160
	s_waitcnt lgkmcnt(6)
	v_pk_fma_f32 v[74:75], v[96:97], v[34:35], v[74:75] neg_lo:[1,0,0] neg_hi:[1,0,0]
	v_pk_fma_f32 v[76:77], v[98:99], v[36:37], v[76:77] neg_lo:[1,0,0] neg_hi:[1,0,0]
	ds_read_b128 v[96:99], v78 offset:14176
	s_waitcnt lgkmcnt(6)
	v_pk_fma_f32 v[74:75], v[100:101], v[38:39], v[74:75] neg_lo:[1,0,0] neg_hi:[1,0,0]
	v_pk_fma_f32 v[76:77], v[102:103], v[40:41], v[76:77] neg_lo:[1,0,0] neg_hi:[1,0,0]
	ds_read_b128 v[100:103], v78 offset:14192
	s_waitcnt lgkmcnt(6)
	v_pk_fma_f32 v[74:75], v[104:105], v[42:43], v[74:75] neg_lo:[1,0,0] neg_hi:[1,0,0]
	v_pk_fma_f32 v[76:77], v[106:107], v[44:45], v[76:77] neg_lo:[1,0,0] neg_hi:[1,0,0]
	ds_read_b128 v[104:107], v78 offset:14208
	s_waitcnt lgkmcnt(6)
	v_pk_fma_f32 v[74:75], v[108:109], v[48:49], v[74:75] neg_lo:[1,0,0] neg_hi:[1,0,0]
	v_pk_fma_f32 v[76:77], v[110:111], v[50:51], v[76:77] neg_lo:[1,0,0] neg_hi:[1,0,0]
	ds_read_b128 v[108:111], v78 offset:14224
	s_waitcnt lgkmcnt(6)
	v_pk_fma_f32 v[74:75], v[84:85], v[52:53], v[74:75] neg_lo:[1,0,0] neg_hi:[1,0,0]
	v_mov_b32_e32 v69, v86
	ds_read_b128 v[84:87], v78 offset:14240
	s_waitcnt lgkmcnt(6)
	v_pk_fma_f32 v[70:71], v[88:89], v[0:1], 0 neg_lo:[1,0,0] neg_hi:[1,0,0]
	v_pk_fma_f32 v[72:73], v[90:91], v[2:3], 0 neg_lo:[1,0,0] neg_hi:[1,0,0]
	v_fma_f32 v76, -v54, v69, v76
	ds_read_b128 v[88:91], v78 offset:14256
	s_waitcnt lgkmcnt(6)
; DI void gdn_prep(const Params& p, int item, unsigned char* smem) {
;     ...
; #pragma unroll
;         for (int i = 1; i < 64; ++i) {
;             float a = X[i];
;             int dep; asm volatile("v_and_b32 %0, 0, %1" : "=v"(dep) : "v"(X[i - 1]));
;             const float* Lr = sL + i * 68 + dep;
;             float b0 = 0.f, b1 = 0.f, b2 = 0.f;
; #pragma unroll
;             for (int j4 = 0; j4 < (i + 3) / 4; ++j4) {
;                 const f32x4 l = *(const f32x4*)(Lr + 4 * j4);
;                 if (4 * j4 + 0 < i) a -= l.x * X[4 * j4 + 0];
;                 if (4 * j4 + 1 < i) b0 -= l.y * X[4 * j4 + 1];
;                 if (4 * j4 + 2 < i) b1 -= l.z * X[4 * j4 + 2];
;                 if (4 * j4 + 3 < i) b2 -= l.w * X[4 * j4 + 3];
;             }
;             X[i] = (a + b0) + (b1 + b2);
;         }
	v_pk_fma_f32 v[70:71], v[92:93], v[4:5], v[70:71] neg_lo:[1,0,0] neg_hi:[1,0,0]
	v_pk_fma_f32 v[72:73], v[94:95], v[6:7], v[72:73] neg_lo:[1,0,0] neg_hi:[1,0,0]
	v_add_f32_e32 v74, v74, v75
	ds_read_b128 v[92:95], v78 offset:14272
	s_waitcnt lgkmcnt(6)
	v_pk_fma_f32 v[70:71], v[96:97], v[8:9], v[70:71] neg_lo:[1,0,0] neg_hi:[1,0,0]
	v_pk_fma_f32 v[72:73], v[98:99], v[10:11], v[72:73] neg_lo:[1,0,0] neg_hi:[1,0,0]
	v_add_f32_e32 v76, v76, v77
	ds_read_b128 v[96:99], v78 offset:14288
	s_waitcnt lgkmcnt(6)
	v_pk_fma_f32 v[70:71], v[100:101], v[12:13], v[70:71] neg_lo:[1,0,0] neg_hi:[1,0,0]
	v_pk_fma_f32 v[72:73], v[102:103], v[14:15], v[72:73] neg_lo:[1,0,0] neg_hi:[1,0,0]
	v_add_f32_e32 v74, v74, v76
	ds_read_b128 v[100:103], v78 offset:14304
	s_waitcnt lgkmcnt(6)
	v_pk_fma_f32 v[70:71], v[104:105], v[16:17], v[70:71] neg_lo:[1,0,0] neg_hi:[1,0,0]
	v_pk_fma_f32 v[72:73], v[106:107], v[18:19], v[72:73] neg_lo:[1,0,0] neg_hi:[1,0,0]
	v_add_f32_e32 v55, v55, v74
	ds_read_b128 v[104:107], v78 offset:14320
	s_waitcnt lgkmcnt(6)
	v_pk_fma_f32 v[70:71], v[108:109], v[20:21], v[70:71] neg_lo:[1,0,0] neg_hi:[1,0,0]
	v_pk_fma_f32 v[72:73], v[110:111], v[22:23], v[72:73] neg_lo:[1,0,0] neg_hi:[1,0,0]
	ds_read_b128 v[108:111], v78 offset:14336
	s_waitcnt lgkmcnt(6)
	v_pk_fma_f32 v[70:71], v[84:85], v[24:25], v[70:71] neg_lo:[1,0,0] neg_hi:[1,0,0]
	v_pk_fma_f32 v[72:73], v[86:87], v[26:27], v[72:73] neg_lo:[1,0,0] neg_hi:[1,0,0]
	ds_read_b128 v[84:87], v78 offset:14416
	s_waitcnt lgkmcnt(6)
	v_pk_fma_f32 v[70:71], v[88:89], v[28:29], v[70:71] neg_lo:[1,0,0] neg_hi:[1,0,0]
	v_pk_fma_f32 v[72:73], v[90:91], v[30:31], v[72:73] neg_lo:[1,0,0] neg_hi:[1,0,0]
	ds_read_b128 v[88:91], v78 offset:14432
	s_waitcnt lgkmcnt(6)
	v_pk_fma_f32 v[70:71], v[92:93], v[34:35], v[70:71] neg_lo:[1,0,0] neg_hi:[1,0,0]
	v_pk_fma_f32 v[72:73], v[94:95], v[36:37], v[72:73] neg_lo:[1,0,0] neg_hi:[1,0,0]
	ds_read_b128 v[92:95], v78 offset:14448
	s_waitcnt lgkmcnt(6)
	v_pk_fma_f32 v[70:71], v[96:97], v[38:39], v[70:71] neg_lo:[1,0,0] neg_hi:[1,0,0]
	v_pk_fma_f32 v[72:73], v[98:99], v[40:41], v[72:73] neg_lo:[1,0,0] neg_hi:[1,0,0]
	ds_read_b128 v[96:99], v78 offset:14464
	s_waitcnt lgkmcnt(6)
	v_pk_fma_f32 v[70:71], v[100:101], v[42:43], v[70:71] neg_lo:[1,0,0] neg_hi:[1,0,0]
	v_pk_fma_f32 v[72:73], v[102:103], v[44:45], v[72:73] neg_lo:[1,0,0] neg_hi:[1,0,0]
	ds_read_b128 v[100:103], v78 offset:14480
	s_waitcnt lgkmcnt(6)
	v_pk_fma_f32 v[70:71], v[104:105], v[48:49], v[70:71] neg_lo:[1,0,0] neg_hi:[1,0,0]
	v_pk_fma_f32 v[72:73], v[106:107], v[50:51], v[72:73] neg_lo:[1,0,0] neg_hi:[1,0,0]
	ds_read_b128 v[104:107], v78 offset:14496
	s_waitcnt lgkmcnt(6)
	v_pk_fma_f32 v[70:71], v[108:109], v[52:53], v[70:71] neg_lo:[1,0,0] neg_hi:[1,0,0]
	v_fma_f32 v72, -v54, v110, v72
	v_mov_b32_e32 v68, v111
	ds_read_b128 v[108:111], v78 offset:14512
	s_waitcnt lgkmcnt(6)
	v_pk_fma_f32 v[74:75], v[84:85], v[0:1], 0 neg_lo:[1,0,0] neg_hi:[1,0,0]
	v_pk_fma_f32 v[76:77], v[86:87], v[2:3], 0 neg_lo:[1,0,0] neg_hi:[1,0,0]
	v_fma_f32 v73, -v55, v68, v73
	ds_read_b128 v[84:87], v78 offset:14528
	s_waitcnt lgkmcnt(6)
	v_pk_fma_f32 v[74:75], v[88:89], v[4:5], v[74:75] neg_lo:[1,0,0] neg_hi:[1,0,0]
	v_pk_fma_f32 v[76:77], v[90:91], v[6:7], v[76:77] neg_lo:[1,0,0] neg_hi:[1,0,0]
	v_add_f32_e32 v70, v70, v71
	ds_read_b128 v[88:91], v78 offset:14544
	s_waitcnt lgkmcnt(6)
	v_pk_fma_f32 v[74:75], v[92:93], v[8:9], v[74:75] neg_lo:[1,0,0] neg_hi:[1,0,0]
	v_pk_fma_f32 v[76:77], v[94:95], v[10:11], v[76:77] neg_lo:[1,0,0] neg_hi:[1,0,0]
	v_add_f32_e32 v72, v72, v73
	ds_read_b128 v[92:95], v78 offset:14560
	s_waitcnt lgkmcnt(6)
	v_pk_fma_f32 v[74:75], v[96:97], v[12:13], v[74:75] neg_lo:[1,0,0] neg_hi:[1,0,0]
	v_pk_fma_f32 v[76:77], v[98:99], v[14:15], v[76:77] neg_lo:[1,0,0] neg_hi:[1,0,0]
	v_add_f32_e32 v70, v70, v72
	ds_read_b128 v[96:99], v78 offset:14576
	s_waitcnt lgkmcnt(6)
	v_pk_fma_f32 v[74:75], v[100:101], v[16:17], v[74:75] neg_lo:[1,0,0] neg_hi:[1,0,0]
	v_pk_fma_f32 v[76:77], v[102:103], v[18:19], v[76:77] neg_lo:[1,0,0] neg_hi:[1,0,0]
	v_add_f32_e32 v56, v56, v70
	ds_read_b128 v[100:103], v78 offset:14592
	s_waitcnt lgkmcnt(6)
	v_pk_fma_f32 v[74:75], v[104:105], v[20:21], v[74:75] neg_lo:[1,0,0] neg_hi:[1,0,0]
	v_pk_fma_f32 v[76:77], v[106:107], v[22:23], v[76:77] neg_lo:[1,0,0] neg_hi:[1,0,0]
	ds_read_b128 v[104:107], v78 offset:14608
	s_waitcnt lgkmcnt(6)
	v_pk_fma_f32 v[74:75], v[108:109], v[24:25], v[74:75] neg_lo:[1,0,0] neg_hi:[1,0,0]
	v_pk_fma_f32 v[76:77], v[110:111], v[26:27], v[76:77] neg_lo:[1,0,0] neg_hi:[1,0,0]
	ds_read_b128 v[108:111], v78 offset:14624
	s_waitcnt lgkmcnt(6)
	v_pk_fma_f32 v[74:75], v[84:85], v[28:29], v[74:75] neg_lo:[1,0,0] neg_hi:[1,0,0]
	v_pk_fma_f32 v[76:77], v[86:87], v[30:31], v[76:77] neg_lo:[1,0,0] neg_hi:[1,0,0]
	ds_read_b128 v[84:87], v78 offset:14688
	s_waitcnt lgkmcnt(6)
	v_pk_fma_f32 v[74:75], v[88:89], v[34:35], v[74:75] neg_lo:[1,0,0] neg_hi:[1,0,0]
	v_pk_fma_f32 v[76:77], v[90:91], v[36:37], v[76:77] neg_lo:[1,0,0] neg_hi:[1,0,0]
	ds_read_b128 v[88:91], v78 offset:14704
	s_waitcnt lgkmcnt(6)
	v_pk_fma_f32 v[74:75], v[92:93], v[38:39], v[74:75] neg_lo:[1,0,0] neg_hi:[1,0,0]
	v_pk_fma_f32 v[76:77], v[94:95], v[40:41], v[76:77] neg_lo:[1,0,0] neg_hi:[1,0,0]
	ds_read_b128 v[92:95], v78 offset:14720
	s_waitcnt lgkmcnt(6)
	v_pk_fma_f32 v[74:75], v[96:97], v[42:43], v[74:75] neg_lo:[1,0,0] neg_hi:[1,0,0]
	v_pk_fma_f32 v[76:77], v[98:99], v[44:45], v[76:77] neg_lo:[1,0,0] neg_hi:[1,0,0]
	ds_read_b128 v[96:99], v78 offset:14736
	s_waitcnt lgkmcnt(6)
; DI void gdn_prep(const Params& p, int item, unsigned char* smem) {
;     ...
; #pragma unroll
;         for (int i = 1; i < 64; ++i) {
;             float a = X[i];
;             int dep; asm volatile("v_and_b32 %0, 0, %1" : "=v"(dep) : "v"(X[i - 1]));
;             const float* Lr = sL + i * 68 + dep;
;             float b0 = 0.f, b1 = 0.f, b2 = 0.f;
; #pragma unroll
;             for (int j4 = 0; j4 < (i + 3) / 4; ++j4) {
;                 const f32x4 l = *(const f32x4*)(Lr + 4 * j4);
;                 if (4 * j4 + 0 < i) a -= l.x * X[4 * j4 + 0];
;                 if (4 * j4 + 1 < i) b0 -= l.y * X[4 * j4 + 1];
;                 if (4 * j4 + 2 < i) b1 -= l.z * X[4 * j4 + 2];
;                 if (4 * j4 + 3 < i) b2 -= l.w * X[4 * j4 + 3];
;             }
;             X[i] = (a + b0) + (b1 + b2);
;         }
	v_pk_fma_f32 v[74:75], v[100:101], v[48:49], v[74:75] neg_lo:[1,0,0] neg_hi:[1,0,0]
	v_pk_fma_f32 v[76:77], v[102:103], v[50:51], v[76:77] neg_lo:[1,0,0] neg_hi:[1,0,0]
	ds_read_b128 v[100:103], v78 offset:14752
	s_waitcnt lgkmcnt(6)
	v_pk_fma_f32 v[74:75], v[104:105], v[52:53], v[74:75] neg_lo:[1,0,0] neg_hi:[1,0,0]
	v_pk_fma_f32 v[76:77], v[106:107], v[54:55], v[76:77] neg_lo:[1,0,0] neg_hi:[1,0,0]
	ds_read_b128 v[104:107], v78 offset:14768
	s_waitcnt lgkmcnt(6)
	v_mov_b32_e32 v69, v108
	ds_read_b128 v[108:111], v78 offset:14784
	s_waitcnt lgkmcnt(6)
	v_pk_fma_f32 v[70:71], v[84:85], v[0:1], 0 neg_lo:[1,0,0] neg_hi:[1,0,0]
	v_pk_fma_f32 v[72:73], v[86:87], v[2:3], 0 neg_lo:[1,0,0] neg_hi:[1,0,0]
	v_fma_f32 v74, -v56, v69, v74
	ds_read_b128 v[84:87], v78 offset:14800
	s_waitcnt lgkmcnt(6)
	v_pk_fma_f32 v[70:71], v[88:89], v[4:5], v[70:71] neg_lo:[1,0,0] neg_hi:[1,0,0]
	v_pk_fma_f32 v[72:73], v[90:91], v[6:7], v[72:73] neg_lo:[1,0,0] neg_hi:[1,0,0]
	v_add_f32_e32 v74, v74, v75
	ds_read_b128 v[88:91], v78 offset:14816
	s_waitcnt lgkmcnt(6)
	v_pk_fma_f32 v[70:71], v[92:93], v[8:9], v[70:71] neg_lo:[1,0,0] neg_hi:[1,0,0]
	v_pk_fma_f32 v[72:73], v[94:95], v[10:11], v[72:73] neg_lo:[1,0,0] neg_hi:[1,0,0]
	v_add_f32_e32 v76, v76, v77
	ds_read_b128 v[92:95], v78 offset:14832
	s_waitcnt lgkmcnt(6)
	v_pk_fma_f32 v[70:71], v[96:97], v[12:13], v[70:71] neg_lo:[1,0,0] neg_hi:[1,0,0]
	v_pk_fma_f32 v[72:73], v[98:99], v[14:15], v[72:73] neg_lo:[1,0,0] neg_hi:[1,0,0]
	v_add_f32_e32 v74, v74, v76
	ds_read_b128 v[96:99], v78 offset:14848
	s_waitcnt lgkmcnt(6)
	v_pk_fma_f32 v[70:71], v[100:101], v[16:17], v[70:71] neg_lo:[1,0,0] neg_hi:[1,0,0]
	v_pk_fma_f32 v[72:73], v[102:103], v[18:19], v[72:73] neg_lo:[1,0,0] neg_hi:[1,0,0]
	v_add_f32_e32 v57, v57, v74
	ds_read_b128 v[100:103], v78 offset:14864
	s_waitcnt lgkmcnt(6)
	v_pk_fma_f32 v[70:71], v[104:105], v[20:21], v[70:71] neg_lo:[1,0,0] neg_hi:[1,0,0]
	v_pk_fma_f32 v[72:73], v[106:107], v[22:23], v[72:73] neg_lo:[1,0,0] neg_hi:[1,0,0]
	ds_read_b128 v[104:107], v78 offset:14880
	s_waitcnt lgkmcnt(6)
	v_pk_fma_f32 v[70:71], v[108:109], v[24:25], v[70:71] neg_lo:[1,0,0] neg_hi:[1,0,0]
	v_pk_fma_f32 v[72:73], v[110:111], v[26:27], v[72:73] neg_lo:[1,0,0] neg_hi:[1,0,0]
	ds_read_b128 v[108:111], v78 offset:14896
	s_waitcnt lgkmcnt(6)
	v_pk_fma_f32 v[70:71], v[84:85], v[28:29], v[70:71] neg_lo:[1,0,0] neg_hi:[1,0,0]
	v_pk_fma_f32 v[72:73], v[86:87], v[30:31], v[72:73] neg_lo:[1,0,0] neg_hi:[1,0,0]
	ds_read_b128 v[84:87], v78 offset:14960
	s_waitcnt lgkmcnt(6)
	v_pk_fma_f32 v[70:71], v[88:89], v[34:35], v[70:71] neg_lo:[1,0,0] neg_hi:[1,0,0]
	v_pk_fma_f32 v[72:73], v[90:91], v[36:37], v[72:73] neg_lo:[1,0,0] neg_hi:[1,0,0]
	ds_read_b128 v[88:91], v78 offset:14976
	s_waitcnt lgkmcnt(6)
	v_pk_fma_f32 v[70:71], v[92:93], v[38:39], v[70:71] neg_lo:[1,0,0] neg_hi:[1,0,0]
	v_pk_fma_f32 v[72:73], v[94:95], v[40:41], v[72:73] neg_lo:[1,0,0] neg_hi:[1,0,0]
	ds_read_b128 v[92:95], v78 offset:14992
	s_waitcnt lgkmcnt(6)
	v_pk_fma_f32 v[70:71], v[96:97], v[42:43], v[70:71] neg_lo:[1,0,0] neg_hi:[1,0,0]
	v_pk_fma_f32 v[72:73], v[98:99], v[44:45], v[72:73] neg_lo:[1,0,0] neg_hi:[1,0,0]
	ds_read_b128 v[96:99], v78 offset:15008
	s_waitcnt lgkmcnt(6)
	v_pk_fma_f32 v[70:71], v[100:101], v[48:49], v[70:71] neg_lo:[1,0,0] neg_hi:[1,0,0]
	v_pk_fma_f32 v[72:73], v[102:103], v[50:51], v[72:73] neg_lo:[1,0,0] neg_hi:[1,0,0]
	ds_read_b128 v[100:103], v78 offset:15024
	s_waitcnt lgkmcnt(6)
	v_pk_fma_f32 v[70:71], v[104:105], v[52:53], v[70:71] neg_lo:[1,0,0] neg_hi:[1,0,0]
	v_pk_fma_f32 v[72:73], v[106:107], v[54:55], v[72:73] neg_lo:[1,0,0] neg_hi:[1,0,0]
	ds_read_b128 v[104:107], v78 offset:15040
	s_waitcnt lgkmcnt(6)
	v_fma_f32 v70, -v56, v108, v70
	v_mov_b32_e32 v68, v109
	ds_read_b128 v[108:111], v78 offset:15056
	s_waitcnt lgkmcnt(6)
	v_pk_fma_f32 v[74:75], v[84:85], v[0:1], 0 neg_lo:[1,0,0] neg_hi:[1,0,0]
	v_pk_fma_f32 v[76:77], v[86:87], v[2:3], 0 neg_lo:[1,0,0] neg_hi:[1,0,0]
	v_fma_f32 v71, -v57, v68, v71
	ds_read_b128 v[84:87], v78 offset:15072
	s_waitcnt lgkmcnt(6)
	v_pk_fma_f32 v[74:75], v[88:89], v[4:5], v[74:75] neg_lo:[1,0,0] neg_hi:[1,0,0]
	v_pk_fma_f32 v[76:77], v[90:91], v[6:7], v[76:77] neg_lo:[1,0,0] neg_hi:[1,0,0]
	v_add_f32_e32 v70, v70, v71
	ds_read_b128 v[88:91], v78 offset:15088
	s_waitcnt lgkmcnt(6)
	v_pk_fma_f32 v[74:75], v[92:93], v[8:9], v[74:75] neg_lo:[1,0,0] neg_hi:[1,0,0]
	v_pk_fma_f32 v[76:77], v[94:95], v[10:11], v[76:77] neg_lo:[1,0,0] neg_hi:[1,0,0]
	v_add_f32_e32 v72, v72, v73
	ds_read_b128 v[92:95], v78 offset:15104
	s_waitcnt lgkmcnt(6)
	v_pk_fma_f32 v[74:75], v[96:97], v[12:13], v[74:75] neg_lo:[1,0,0] neg_hi:[1,0,0]
	v_pk_fma_f32 v[76:77], v[98:99], v[14:15], v[76:77] neg_lo:[1,0,0] neg_hi:[1,0,0]
	v_add_f32_e32 v70, v70, v72
	ds_read_b128 v[96:99], v78 offset:15120
	s_waitcnt lgkmcnt(6)
	v_pk_fma_f32 v[74:75], v[100:101], v[16:17], v[74:75] neg_lo:[1,0,0] neg_hi:[1,0,0]
	v_pk_fma_f32 v[76:77], v[102:103], v[18:19], v[76:77] neg_lo:[1,0,0] neg_hi:[1,0,0]
	v_add_f32_e32 v58, v58, v70
	ds_read_b128 v[100:103], v78 offset:15136
	s_waitcnt lgkmcnt(6)
	v_pk_fma_f32 v[74:75], v[104:105], v[20:21], v[74:75] neg_lo:[1,0,0] neg_hi:[1,0,0]
	v_pk_fma_f32 v[76:77], v[106:107], v[22:23], v[76:77] neg_lo:[1,0,0] neg_hi:[1,0,0]
	ds_read_b128 v[104:107], v78 offset:15152
	s_waitcnt lgkmcnt(6)
	v_pk_fma_f32 v[74:75], v[108:109], v[24:25], v[74:75] neg_lo:[1,0,0] neg_hi:[1,0,0]
	v_pk_fma_f32 v[76:77], v[110:111], v[26:27], v[76:77] neg_lo:[1,0,0] neg_hi:[1,0,0]
	ds_read_b128 v[108:111], v78 offset:15168
	s_waitcnt lgkmcnt(6)
; DI void gdn_prep(const Params& p, int item, unsigned char* smem) {
;     ...
; #pragma unroll
;         for (int i = 1; i < 64; ++i) {
;             float a = X[i];
;             int dep; asm volatile("v_and_b32 %0, 0, %1" : "=v"(dep) : "v"(X[i - 1]));
;             const float* Lr = sL + i * 68 + dep;
;             float b0 = 0.f, b1 = 0.f, b2 = 0.f;
; #pragma unroll
;             for (int j4 = 0; j4 < (i + 3) / 4; ++j4) {
;                 const f32x4 l = *(const f32x4*)(Lr + 4 * j4);
;                 if (4 * j4 + 0 < i) a -= l.x * X[4 * j4 + 0];
;                 if (4 * j4 + 1 < i) b0 -= l.y * X[4 * j4 + 1];
;                 if (4 * j4 + 2 < i) b1 -= l.z * X[4 * j4 + 2];
;                 if (4 * j4 + 3 < i) b2 -= l.w * X[4 * j4 + 3];
;             }
;             X[i] = (a + b0) + (b1 + b2);
;         }
	v_pk_fma_f32 v[74:75], v[84:85], v[28:29], v[74:75] neg_lo:[1,0,0] neg_hi:[1,0,0]
	v_pk_fma_f32 v[76:77], v[86:87], v[30:31], v[76:77] neg_lo:[1,0,0] neg_hi:[1,0,0]
	ds_read_b128 v[84:87], v78 offset:15232
	s_waitcnt lgkmcnt(6)
	v_pk_fma_f32 v[74:75], v[88:89], v[34:35], v[74:75] neg_lo:[1,0,0] neg_hi:[1,0,0]
	v_pk_fma_f32 v[76:77], v[90:91], v[36:37], v[76:77] neg_lo:[1,0,0] neg_hi:[1,0,0]
	ds_read_b128 v[88:91], v78 offset:15248
	s_waitcnt lgkmcnt(6)
	v_pk_fma_f32 v[74:75], v[92:93], v[38:39], v[74:75] neg_lo:[1,0,0] neg_hi:[1,0,0]
	v_pk_fma_f32 v[76:77], v[94:95], v[40:41], v[76:77] neg_lo:[1,0,0] neg_hi:[1,0,0]
	ds_read_b128 v[92:95], v78 offset:15264
	s_waitcnt lgkmcnt(6)
	v_pk_fma_f32 v[74:75], v[96:97], v[42:43], v[74:75] neg_lo:[1,0,0] neg_hi:[1,0,0]
	v_pk_fma_f32 v[76:77], v[98:99], v[44:45], v[76:77] neg_lo:[1,0,0] neg_hi:[1,0,0]
	ds_read_b128 v[96:99], v78 offset:15280
	s_waitcnt lgkmcnt(6)
	v_pk_fma_f32 v[74:75], v[100:101], v[48:49], v[74:75] neg_lo:[1,0,0] neg_hi:[1,0,0]
	v_pk_fma_f32 v[76:77], v[102:103], v[50:51], v[76:77] neg_lo:[1,0,0] neg_hi:[1,0,0]
	ds_read_b128 v[100:103], v78 offset:15296
	s_waitcnt lgkmcnt(6)
	v_pk_fma_f32 v[74:75], v[104:105], v[52:53], v[74:75] neg_lo:[1,0,0] neg_hi:[1,0,0]
	v_pk_fma_f32 v[76:77], v[106:107], v[54:55], v[76:77] neg_lo:[1,0,0] neg_hi:[1,0,0]
	ds_read_b128 v[104:107], v78 offset:15312
	s_waitcnt lgkmcnt(6)
	v_pk_fma_f32 v[74:75], v[108:109], v[56:57], v[74:75] neg_lo:[1,0,0] neg_hi:[1,0,0]
	v_mov_b32_e32 v69, v110
	ds_read_b128 v[108:111], v78 offset:15328
	s_waitcnt lgkmcnt(6)
	v_pk_fma_f32 v[70:71], v[84:85], v[0:1], 0 neg_lo:[1,0,0] neg_hi:[1,0,0]
	v_pk_fma_f32 v[72:73], v[86:87], v[2:3], 0 neg_lo:[1,0,0] neg_hi:[1,0,0]
	v_fma_f32 v76, -v58, v69, v76
	ds_read_b128 v[84:87], v78 offset:15344
	s_waitcnt lgkmcnt(6)
	v_pk_fma_f32 v[70:71], v[88:89], v[4:5], v[70:71] neg_lo:[1,0,0] neg_hi:[1,0,0]
	v_pk_fma_f32 v[72:73], v[90:91], v[6:7], v[72:73] neg_lo:[1,0,0] neg_hi:[1,0,0]
	v_add_f32_e32 v74, v74, v75
	ds_read_b128 v[88:91], v78 offset:15360
	s_waitcnt lgkmcnt(6)
	v_pk_fma_f32 v[70:71], v[92:93], v[8:9], v[70:71] neg_lo:[1,0,0] neg_hi:[1,0,0]
	v_pk_fma_f32 v[72:73], v[94:95], v[10:11], v[72:73] neg_lo:[1,0,0] neg_hi:[1,0,0]
	v_add_f32_e32 v76, v76, v77
	ds_read_b128 v[92:95], v78 offset:15376
	s_waitcnt lgkmcnt(6)
	v_pk_fma_f32 v[70:71], v[96:97], v[12:13], v[70:71] neg_lo:[1,0,0] neg_hi:[1,0,0]
	v_pk_fma_f32 v[72:73], v[98:99], v[14:15], v[72:73] neg_lo:[1,0,0] neg_hi:[1,0,0]
	v_add_f32_e32 v74, v74, v76
	ds_read_b128 v[96:99], v78 offset:15392
	s_waitcnt lgkmcnt(6)
	v_pk_fma_f32 v[70:71], v[100:101], v[16:17], v[70:71] neg_lo:[1,0,0] neg_hi:[1,0,0]
	v_pk_fma_f32 v[72:73], v[102:103], v[18:19], v[72:73] neg_lo:[1,0,0] neg_hi:[1,0,0]
	v_add_f32_e32 v59, v59, v74
	ds_read_b128 v[100:103], v78 offset:15408
	s_waitcnt lgkmcnt(6)
	v_pk_fma_f32 v[70:71], v[104:105], v[20:21], v[70:71] neg_lo:[1,0,0] neg_hi:[1,0,0]
	v_pk_fma_f32 v[72:73], v[106:107], v[22:23], v[72:73] neg_lo:[1,0,0] neg_hi:[1,0,0]
	ds_read_b128 v[104:107], v78 offset:15424
	s_waitcnt lgkmcnt(6)
	v_pk_fma_f32 v[70:71], v[108:109], v[24:25], v[70:71] neg_lo:[1,0,0] neg_hi:[1,0,0]
	v_pk_fma_f32 v[72:73], v[110:111], v[26:27], v[72:73] neg_lo:[1,0,0] neg_hi:[1,0,0]
	ds_read_b128 v[108:111], v78 offset:15440
	s_waitcnt lgkmcnt(6)
	v_pk_fma_f32 v[70:71], v[84:85], v[28:29], v[70:71] neg_lo:[1,0,0] neg_hi:[1,0,0]
	v_pk_fma_f32 v[72:73], v[86:87], v[30:31], v[72:73] neg_lo:[1,0,0] neg_hi:[1,0,0]
	ds_read_b128 v[84:87], v78 offset:15504
	s_waitcnt lgkmcnt(6)
	v_pk_fma_f32 v[70:71], v[88:89], v[34:35], v[70:71] neg_lo:[1,0,0] neg_hi:[1,0,0]
	v_pk_fma_f32 v[72:73], v[90:91], v[36:37], v[72:73] neg_lo:[1,0,0] neg_hi:[1,0,0]
	ds_read_b128 v[88:91], v78 offset:15520
	s_waitcnt lgkmcnt(6)
	v_pk_fma_f32 v[70:71], v[92:93], v[38:39], v[70:71] neg_lo:[1,0,0] neg_hi:[1,0,0]
	v_pk_fma_f32 v[72:73], v[94:95], v[40:41], v[72:73] neg_lo:[1,0,0] neg_hi:[1,0,0]
	ds_read_b128 v[92:95], v78 offset:15536
	s_waitcnt lgkmcnt(6)
	v_pk_fma_f32 v[70:71], v[96:97], v[42:43], v[70:71] neg_lo:[1,0,0] neg_hi:[1,0,0]
	v_pk_fma_f32 v[72:73], v[98:99], v[44:45], v[72:73] neg_lo:[1,0,0] neg_hi:[1,0,0]
	ds_read_b128 v[96:99], v78 offset:15552
	s_waitcnt lgkmcnt(6)
	v_pk_fma_f32 v[70:71], v[100:101], v[48:49], v[70:71] neg_lo:[1,0,0] neg_hi:[1,0,0]
	v_pk_fma_f32 v[72:73], v[102:103], v[50:51], v[72:73] neg_lo:[1,0,0] neg_hi:[1,0,0]
	ds_read_b128 v[100:103], v78 offset:15568
	s_waitcnt lgkmcnt(6)
	v_pk_fma_f32 v[70:71], v[104:105], v[52:53], v[70:71] neg_lo:[1,0,0] neg_hi:[1,0,0]
	v_pk_fma_f32 v[72:73], v[106:107], v[54:55], v[72:73] neg_lo:[1,0,0] neg_hi:[1,0,0]
	ds_read_b128 v[104:107], v78 offset:15584
	s_waitcnt lgkmcnt(6)
	v_pk_fma_f32 v[70:71], v[108:109], v[56:57], v[70:71] neg_lo:[1,0,0] neg_hi:[1,0,0]
	v_fma_f32 v72, -v58, v110, v72
	v_mov_b32_e32 v68, v111
	ds_read_b128 v[108:111], v78 offset:15600
	s_waitcnt lgkmcnt(6)
	v_pk_fma_f32 v[74:75], v[84:85], v[0:1], 0 neg_lo:[1,0,0] neg_hi:[1,0,0]
	v_pk_fma_f32 v[76:77], v[86:87], v[2:3], 0 neg_lo:[1,0,0] neg_hi:[1,0,0]
	v_fma_f32 v73, -v59, v68, v73
	ds_read_b128 v[84:87], v78 offset:15616
	s_waitcnt lgkmcnt(6)
	v_pk_fma_f32 v[74:75], v[88:89], v[4:5], v[74:75] neg_lo:[1,0,0] neg_hi:[1,0,0]
	v_pk_fma_f32 v[76:77], v[90:91], v[6:7], v[76:77] neg_lo:[1,0,0] neg_hi:[1,0,0]
	v_add_f32_e32 v70, v70, v71
	ds_read_b128 v[88:91], v78 offset:15632
	s_waitcnt lgkmcnt(6)
	v_pk_fma_f32 v[74:75], v[92:93], v[8:9], v[74:75] neg_lo:[1,0,0] neg_hi:[1,0,0]
	v_pk_fma_f32 v[76:77], v[94:95], v[10:11], v[76:77] neg_lo:[1,0,0] neg_hi:[1,0,0]
	v_add_f32_e32 v72, v72, v73
	ds_read_b128 v[92:95], v78 offset:15648
	s_waitcnt lgkmcnt(6)
; DI void gdn_prep(const Params& p, int item, unsigned char* smem) {
;     ...
; #pragma unroll
;         for (int i = 1; i < 64; ++i) {
;             float a = X[i];
;             int dep; asm volatile("v_and_b32 %0, 0, %1" : "=v"(dep) : "v"(X[i - 1]));
;             const float* Lr = sL + i * 68 + dep;
;             float b0 = 0.f, b1 = 0.f, b2 = 0.f;
; #pragma unroll
;             for (int j4 = 0; j4 < (i + 3) / 4; ++j4) {
;                 const f32x4 l = *(const f32x4*)(Lr + 4 * j4);
;                 if (4 * j4 + 0 < i) a -= l.x * X[4 * j4 + 0];
;                 if (4 * j4 + 1 < i) b0 -= l.y * X[4 * j4 + 1];
;                 if (4 * j4 + 2 < i) b1 -= l.z * X[4 * j4 + 2];
;                 if (4 * j4 + 3 < i) b2 -= l.w * X[4 * j4 + 3];
;             }
;             X[i] = (a + b0) + (b1 + b2);
;         }
	v_pk_fma_f32 v[74:75], v[96:97], v[12:13], v[74:75] neg_lo:[1,0,0] neg_hi:[1,0,0]
	v_pk_fma_f32 v[76:77], v[98:99], v[14:15], v[76:77] neg_lo:[1,0,0] neg_hi:[1,0,0]
	v_add_f32_e32 v70, v70, v72
	ds_read_b128 v[96:99], v78 offset:15664
	s_waitcnt lgkmcnt(6)
	v_pk_fma_f32 v[74:75], v[100:101], v[16:17], v[74:75] neg_lo:[1,0,0] neg_hi:[1,0,0]
	v_pk_fma_f32 v[76:77], v[102:103], v[18:19], v[76:77] neg_lo:[1,0,0] neg_hi:[1,0,0]
	v_add_f32_e32 v60, v60, v70
	ds_read_b128 v[100:103], v78 offset:15680
	s_waitcnt lgkmcnt(6)
	v_pk_fma_f32 v[74:75], v[104:105], v[20:21], v[74:75] neg_lo:[1,0,0] neg_hi:[1,0,0]
	v_pk_fma_f32 v[76:77], v[106:107], v[22:23], v[76:77] neg_lo:[1,0,0] neg_hi:[1,0,0]
	ds_read_b128 v[104:107], v78 offset:15696
	s_waitcnt lgkmcnt(6)
	v_pk_fma_f32 v[74:75], v[108:109], v[24:25], v[74:75] neg_lo:[1,0,0] neg_hi:[1,0,0]
	v_pk_fma_f32 v[76:77], v[110:111], v[26:27], v[76:77] neg_lo:[1,0,0] neg_hi:[1,0,0]
	ds_read_b128 v[108:111], v78 offset:15712
	s_waitcnt lgkmcnt(6)
	v_pk_fma_f32 v[74:75], v[84:85], v[28:29], v[74:75] neg_lo:[1,0,0] neg_hi:[1,0,0]
	v_pk_fma_f32 v[76:77], v[86:87], v[30:31], v[76:77] neg_lo:[1,0,0] neg_hi:[1,0,0]
	ds_read_b128 v[84:87], v78 offset:15728
	s_waitcnt lgkmcnt(6)
	v_pk_fma_f32 v[74:75], v[88:89], v[34:35], v[74:75] neg_lo:[1,0,0] neg_hi:[1,0,0]
	v_pk_fma_f32 v[76:77], v[90:91], v[36:37], v[76:77] neg_lo:[1,0,0] neg_hi:[1,0,0]
	ds_read_b128 v[88:91], v78 offset:15776
	s_waitcnt lgkmcnt(6)
	v_pk_fma_f32 v[74:75], v[92:93], v[38:39], v[74:75] neg_lo:[1,0,0] neg_hi:[1,0,0]
	v_pk_fma_f32 v[76:77], v[94:95], v[40:41], v[76:77] neg_lo:[1,0,0] neg_hi:[1,0,0]
	ds_read_b128 v[92:95], v78 offset:15792
	s_waitcnt lgkmcnt(6)
	v_pk_fma_f32 v[74:75], v[96:97], v[42:43], v[74:75] neg_lo:[1,0,0] neg_hi:[1,0,0]
	v_pk_fma_f32 v[76:77], v[98:99], v[44:45], v[76:77] neg_lo:[1,0,0] neg_hi:[1,0,0]
	ds_read_b128 v[96:99], v78 offset:15808
	s_waitcnt lgkmcnt(6)
	v_pk_fma_f32 v[74:75], v[100:101], v[48:49], v[74:75] neg_lo:[1,0,0] neg_hi:[1,0,0]
	v_pk_fma_f32 v[76:77], v[102:103], v[50:51], v[76:77] neg_lo:[1,0,0] neg_hi:[1,0,0]
	ds_read_b128 v[100:103], v78 offset:15824
	s_waitcnt lgkmcnt(6)
	v_pk_fma_f32 v[74:75], v[104:105], v[52:53], v[74:75] neg_lo:[1,0,0] neg_hi:[1,0,0]
	v_pk_fma_f32 v[76:77], v[106:107], v[54:55], v[76:77] neg_lo:[1,0,0] neg_hi:[1,0,0]
	ds_read_b128 v[104:107], v78 offset:15840
	s_waitcnt lgkmcnt(6)
	v_pk_fma_f32 v[74:75], v[108:109], v[56:57], v[74:75] neg_lo:[1,0,0] neg_hi:[1,0,0]
	v_pk_fma_f32 v[76:77], v[110:111], v[58:59], v[76:77] neg_lo:[1,0,0] neg_hi:[1,0,0]
	ds_read_b128 v[108:111], v78 offset:15856
	s_waitcnt lgkmcnt(6)
	v_mov_b32_e32 v69, v84
	ds_read_b128 v[84:87], v78 offset:15872
	s_waitcnt lgkmcnt(6)
	v_pk_fma_f32 v[70:71], v[88:89], v[0:1], 0 neg_lo:[1,0,0] neg_hi:[1,0,0]
	v_pk_fma_f32 v[72:73], v[90:91], v[2:3], 0 neg_lo:[1,0,0] neg_hi:[1,0,0]
	v_fma_f32 v74, -v60, v69, v74
	ds_read_b128 v[88:91], v78 offset:15888
	s_waitcnt lgkmcnt(6)
	v_pk_fma_f32 v[70:71], v[92:93], v[4:5], v[70:71] neg_lo:[1,0,0] neg_hi:[1,0,0]
	v_pk_fma_f32 v[72:73], v[94:95], v[6:7], v[72:73] neg_lo:[1,0,0] neg_hi:[1,0,0]
	v_add_f32_e32 v74, v74, v75
	ds_read_b128 v[92:95], v78 offset:15904
	s_waitcnt lgkmcnt(6)
	v_pk_fma_f32 v[70:71], v[96:97], v[8:9], v[70:71] neg_lo:[1,0,0] neg_hi:[1,0,0]
	v_pk_fma_f32 v[72:73], v[98:99], v[10:11], v[72:73] neg_lo:[1,0,0] neg_hi:[1,0,0]
	v_add_f32_e32 v76, v76, v77
	ds_read_b128 v[96:99], v78 offset:15920
	s_waitcnt lgkmcnt(6)
	v_pk_fma_f32 v[70:71], v[100:101], v[12:13], v[70:71] neg_lo:[1,0,0] neg_hi:[1,0,0]
	v_pk_fma_f32 v[72:73], v[102:103], v[14:15], v[72:73] neg_lo:[1,0,0] neg_hi:[1,0,0]
	v_add_f32_e32 v74, v74, v76
	ds_read_b128 v[100:103], v78 offset:15936
	s_waitcnt lgkmcnt(6)
	v_pk_fma_f32 v[70:71], v[104:105], v[16:17], v[70:71] neg_lo:[1,0,0] neg_hi:[1,0,0]
	v_pk_fma_f32 v[72:73], v[106:107], v[18:19], v[72:73] neg_lo:[1,0,0] neg_hi:[1,0,0]
	v_add_f32_e32 v61, v61, v74
	ds_read_b128 v[104:107], v78 offset:15952
	s_waitcnt lgkmcnt(6)
	v_pk_fma_f32 v[70:71], v[108:109], v[20:21], v[70:71] neg_lo:[1,0,0] neg_hi:[1,0,0]
	v_pk_fma_f32 v[72:73], v[110:111], v[22:23], v[72:73] neg_lo:[1,0,0] neg_hi:[1,0,0]
	ds_read_b128 v[108:111], v78 offset:15968
	s_waitcnt lgkmcnt(6)
	v_pk_fma_f32 v[70:71], v[84:85], v[24:25], v[70:71] neg_lo:[1,0,0] neg_hi:[1,0,0]
	v_pk_fma_f32 v[72:73], v[86:87], v[26:27], v[72:73] neg_lo:[1,0,0] neg_hi:[1,0,0]
	ds_read_b128 v[84:87], v78 offset:15984
	s_waitcnt lgkmcnt(6)
	v_pk_fma_f32 v[70:71], v[88:89], v[28:29], v[70:71] neg_lo:[1,0,0] neg_hi:[1,0,0]
	v_pk_fma_f32 v[72:73], v[90:91], v[30:31], v[72:73] neg_lo:[1,0,0] neg_hi:[1,0,0]
	ds_read_b128 v[88:91], v78 offset:16000
	s_waitcnt lgkmcnt(6)
	v_pk_fma_f32 v[70:71], v[92:93], v[34:35], v[70:71] neg_lo:[1,0,0] neg_hi:[1,0,0]
	v_pk_fma_f32 v[72:73], v[94:95], v[36:37], v[72:73] neg_lo:[1,0,0] neg_hi:[1,0,0]
	ds_read_b128 v[92:95], v78 offset:16048
	s_waitcnt lgkmcnt(6)
	v_pk_fma_f32 v[70:71], v[96:97], v[38:39], v[70:71] neg_lo:[1,0,0] neg_hi:[1,0,0]
	v_pk_fma_f32 v[72:73], v[98:99], v[40:41], v[72:73] neg_lo:[1,0,0] neg_hi:[1,0,0]
	ds_read_b128 v[96:99], v78 offset:16064
	s_waitcnt lgkmcnt(6)
	v_pk_fma_f32 v[70:71], v[100:101], v[42:43], v[70:71] neg_lo:[1,0,0] neg_hi:[1,0,0]
	v_pk_fma_f32 v[72:73], v[102:103], v[44:45], v[72:73] neg_lo:[1,0,0] neg_hi:[1,0,0]
	ds_read_b128 v[100:103], v78 offset:16080
	s_waitcnt lgkmcnt(6)
	v_pk_fma_f32 v[70:71], v[104:105], v[48:49], v[70:71] neg_lo:[1,0,0] neg_hi:[1,0,0]
	v_pk_fma_f32 v[72:73], v[106:107], v[50:51], v[72:73] neg_lo:[1,0,0] neg_hi:[1,0,0]
	ds_read_b128 v[104:107], v78 offset:16096
	s_waitcnt lgkmcnt(6)
; DI void gdn_prep(const Params& p, int item, unsigned char* smem) {
;     ...
; #pragma unroll
;         for (int i = 1; i < 64; ++i) {
;             float a = X[i];
;             int dep; asm volatile("v_and_b32 %0, 0, %1" : "=v"(dep) : "v"(X[i - 1]));
;             const float* Lr = sL + i * 68 + dep;
;             float b0 = 0.f, b1 = 0.f, b2 = 0.f;
; #pragma unroll
;             for (int j4 = 0; j4 < (i + 3) / 4; ++j4) {
;                 const f32x4 l = *(const f32x4*)(Lr + 4 * j4);
;                 if (4 * j4 + 0 < i) a -= l.x * X[4 * j4 + 0];
;                 if (4 * j4 + 1 < i) b0 -= l.y * X[4 * j4 + 1];
;                 if (4 * j4 + 2 < i) b1 -= l.z * X[4 * j4 + 2];
;                 if (4 * j4 + 3 < i) b2 -= l.w * X[4 * j4 + 3];
;             }
;             X[i] = (a + b0) + (b1 + b2);
;         }
	v_pk_fma_f32 v[70:71], v[108:109], v[52:53], v[70:71] neg_lo:[1,0,0] neg_hi:[1,0,0]
	v_pk_fma_f32 v[72:73], v[110:111], v[54:55], v[72:73] neg_lo:[1,0,0] neg_hi:[1,0,0]
	ds_read_b128 v[108:111], v78 offset:16112
	s_waitcnt lgkmcnt(6)
	v_pk_fma_f32 v[70:71], v[84:85], v[56:57], v[70:71] neg_lo:[1,0,0] neg_hi:[1,0,0]
	v_pk_fma_f32 v[72:73], v[86:87], v[58:59], v[72:73] neg_lo:[1,0,0] neg_hi:[1,0,0]
	ds_read_b128 v[84:87], v78 offset:16128
	s_waitcnt lgkmcnt(6)
	v_fma_f32 v70, -v60, v88, v70
	v_mov_b32_e32 v68, v89
	ds_read_b128 v[88:91], v78 offset:16144
	s_waitcnt lgkmcnt(6)
	v_pk_fma_f32 v[74:75], v[92:93], v[0:1], 0 neg_lo:[1,0,0] neg_hi:[1,0,0]
	v_pk_fma_f32 v[76:77], v[94:95], v[2:3], 0 neg_lo:[1,0,0] neg_hi:[1,0,0]
	v_fma_f32 v71, -v61, v68, v71
	ds_read_b128 v[92:95], v78 offset:16160
	s_waitcnt lgkmcnt(6)
	v_pk_fma_f32 v[74:75], v[96:97], v[4:5], v[74:75] neg_lo:[1,0,0] neg_hi:[1,0,0]
	v_pk_fma_f32 v[76:77], v[98:99], v[6:7], v[76:77] neg_lo:[1,0,0] neg_hi:[1,0,0]
	v_add_f32_e32 v70, v70, v71
	ds_read_b128 v[96:99], v78 offset:16176
	s_waitcnt lgkmcnt(6)
	v_pk_fma_f32 v[74:75], v[100:101], v[8:9], v[74:75] neg_lo:[1,0,0] neg_hi:[1,0,0]
	v_pk_fma_f32 v[76:77], v[102:103], v[10:11], v[76:77] neg_lo:[1,0,0] neg_hi:[1,0,0]
	v_add_f32_e32 v72, v72, v73
	ds_read_b128 v[100:103], v78 offset:16192
	s_waitcnt lgkmcnt(6)
	v_pk_fma_f32 v[74:75], v[104:105], v[12:13], v[74:75] neg_lo:[1,0,0] neg_hi:[1,0,0]
	v_pk_fma_f32 v[76:77], v[106:107], v[14:15], v[76:77] neg_lo:[1,0,0] neg_hi:[1,0,0]
	v_add_f32_e32 v70, v70, v72
	ds_read_b128 v[104:107], v78 offset:16208
	s_waitcnt lgkmcnt(6)
	v_pk_fma_f32 v[74:75], v[108:109], v[16:17], v[74:75] neg_lo:[1,0,0] neg_hi:[1,0,0]
	v_pk_fma_f32 v[76:77], v[110:111], v[18:19], v[76:77] neg_lo:[1,0,0] neg_hi:[1,0,0]
	v_add_f32_e32 v62, v62, v70
	ds_read_b128 v[108:111], v78 offset:16224
	s_waitcnt lgkmcnt(6)
	v_pk_fma_f32 v[74:75], v[84:85], v[20:21], v[74:75] neg_lo:[1,0,0] neg_hi:[1,0,0]
	v_pk_fma_f32 v[76:77], v[86:87], v[22:23], v[76:77] neg_lo:[1,0,0] neg_hi:[1,0,0]
	ds_read_b128 v[84:87], v78 offset:16240
	s_waitcnt lgkmcnt(6)
	v_pk_fma_f32 v[74:75], v[88:89], v[24:25], v[74:75] neg_lo:[1,0,0] neg_hi:[1,0,0]
	v_pk_fma_f32 v[76:77], v[90:91], v[26:27], v[76:77] neg_lo:[1,0,0] neg_hi:[1,0,0]
	ds_read_b128 v[88:91], v78 offset:16256
	s_waitcnt lgkmcnt(6)
	v_pk_fma_f32 v[74:75], v[92:93], v[28:29], v[74:75] neg_lo:[1,0,0] neg_hi:[1,0,0]
	v_pk_fma_f32 v[76:77], v[94:95], v[30:31], v[76:77] neg_lo:[1,0,0] neg_hi:[1,0,0]
	ds_read_b128 v[92:95], v78 offset:16272
	s_waitcnt lgkmcnt(6)
	v_pk_fma_f32 v[74:75], v[96:97], v[34:35], v[74:75] neg_lo:[1,0,0] neg_hi:[1,0,0]
	v_pk_fma_f32 v[76:77], v[98:99], v[36:37], v[76:77] neg_lo:[1,0,0] neg_hi:[1,0,0]
	ds_read_b128 v[96:99], v78 offset:16320
	s_waitcnt lgkmcnt(6)
	v_pk_fma_f32 v[74:75], v[100:101], v[38:39], v[74:75] neg_lo:[1,0,0] neg_hi:[1,0,0]
	v_pk_fma_f32 v[76:77], v[102:103], v[40:41], v[76:77] neg_lo:[1,0,0] neg_hi:[1,0,0]
	ds_read_b128 v[100:103], v78 offset:16336
	s_waitcnt lgkmcnt(6)
	v_pk_fma_f32 v[74:75], v[104:105], v[42:43], v[74:75] neg_lo:[1,0,0] neg_hi:[1,0,0]
	v_pk_fma_f32 v[76:77], v[106:107], v[44:45], v[76:77] neg_lo:[1,0,0] neg_hi:[1,0,0]
	ds_read_b128 v[104:107], v78 offset:16352
	s_waitcnt lgkmcnt(6)
	v_pk_fma_f32 v[74:75], v[108:109], v[48:49], v[74:75] neg_lo:[1,0,0] neg_hi:[1,0,0]
	v_pk_fma_f32 v[76:77], v[110:111], v[50:51], v[76:77] neg_lo:[1,0,0] neg_hi:[1,0,0]
	ds_read_b128 v[108:111], v78 offset:16368
	s_waitcnt lgkmcnt(6)
	v_pk_fma_f32 v[74:75], v[84:85], v[52:53], v[74:75] neg_lo:[1,0,0] neg_hi:[1,0,0]
	v_pk_fma_f32 v[76:77], v[86:87], v[54:55], v[76:77] neg_lo:[1,0,0] neg_hi:[1,0,0]
	ds_read_b128 v[84:87], v78 offset:16384
	s_waitcnt lgkmcnt(6)
	v_pk_fma_f32 v[74:75], v[88:89], v[56:57], v[74:75] neg_lo:[1,0,0] neg_hi:[1,0,0]
	v_pk_fma_f32 v[76:77], v[90:91], v[58:59], v[76:77] neg_lo:[1,0,0] neg_hi:[1,0,0]
	ds_read_b128 v[88:91], v78 offset:16400
	s_waitcnt lgkmcnt(6)
	v_pk_fma_f32 v[74:75], v[92:93], v[60:61], v[74:75] neg_lo:[1,0,0] neg_hi:[1,0,0]
	v_mov_b32_e32 v69, v94
	ds_read_b128 v[92:95], v78 offset:16416
	s_waitcnt lgkmcnt(6)
	v_pk_fma_f32 v[70:71], v[96:97], v[0:1], 0 neg_lo:[1,0,0] neg_hi:[1,0,0]
	v_pk_fma_f32 v[72:73], v[98:99], v[2:3], 0 neg_lo:[1,0,0] neg_hi:[1,0,0]
	v_fma_f32 v76, -v62, v69, v76
	ds_read_b128 v[96:99], v78 offset:16432
	s_waitcnt lgkmcnt(6)
	v_pk_fma_f32 v[70:71], v[100:101], v[4:5], v[70:71] neg_lo:[1,0,0] neg_hi:[1,0,0]
	v_pk_fma_f32 v[72:73], v[102:103], v[6:7], v[72:73] neg_lo:[1,0,0] neg_hi:[1,0,0]
	v_add_f32_e32 v74, v74, v75
	ds_read_b128 v[100:103], v78 offset:16448
	s_waitcnt lgkmcnt(6)
	v_pk_fma_f32 v[70:71], v[104:105], v[8:9], v[70:71] neg_lo:[1,0,0] neg_hi:[1,0,0]
	v_pk_fma_f32 v[72:73], v[106:107], v[10:11], v[72:73] neg_lo:[1,0,0] neg_hi:[1,0,0]
	v_add_f32_e32 v76, v76, v77
	ds_read_b128 v[104:107], v78 offset:16464
	s_waitcnt lgkmcnt(6)
	v_pk_fma_f32 v[70:71], v[108:109], v[12:13], v[70:71] neg_lo:[1,0,0] neg_hi:[1,0,0]
	v_pk_fma_f32 v[72:73], v[110:111], v[14:15], v[72:73] neg_lo:[1,0,0] neg_hi:[1,0,0]
	v_add_f32_e32 v74, v74, v76
	ds_read_b128 v[108:111], v78 offset:16480
	s_waitcnt lgkmcnt(6)
	v_pk_fma_f32 v[70:71], v[84:85], v[16:17], v[70:71] neg_lo:[1,0,0] neg_hi:[1,0,0]
	v_pk_fma_f32 v[72:73], v[86:87], v[18:19], v[72:73] neg_lo:[1,0,0] neg_hi:[1,0,0]
	v_add_f32_e32 v63, v63, v74
	ds_read_b128 v[84:87], v78 offset:16496
	s_waitcnt lgkmcnt(6)
	v_pk_fma_f32 v[70:71], v[88:89], v[20:21], v[70:71] neg_lo:[1,0,0] neg_hi:[1,0,0]
	v_pk_fma_f32 v[72:73], v[90:91], v[22:23], v[72:73] neg_lo:[1,0,0] neg_hi:[1,0,0]
	ds_read_b128 v[88:91], v78 offset:16512
	s_waitcnt lgkmcnt(6)
; DI void gdn_prep(const Params& p, int item, unsigned char* smem) {
;     ...
; #pragma unroll
;         for (int i = 1; i < 64; ++i) {
;             float a = X[i];
;             int dep; asm volatile("v_and_b32 %0, 0, %1" : "=v"(dep) : "v"(X[i - 1]));
;             const float* Lr = sL + i * 68 + dep;
;             float b0 = 0.f, b1 = 0.f, b2 = 0.f;
; #pragma unroll
;             for (int j4 = 0; j4 < (i + 3) / 4; ++j4) {
;                 const f32x4 l = *(const f32x4*)(Lr + 4 * j4);
;                 if (4 * j4 + 0 < i) a -= l.x * X[4 * j4 + 0];
;                 if (4 * j4 + 1 < i) b0 -= l.y * X[4 * j4 + 1];
;                 if (4 * j4 + 2 < i) b1 -= l.z * X[4 * j4 + 2];
;                 if (4 * j4 + 3 < i) b2 -= l.w * X[4 * j4 + 3];
;             }
;             X[i] = (a + b0) + (b1 + b2);
;         }
	v_pk_fma_f32 v[70:71], v[92:93], v[24:25], v[70:71] neg_lo:[1,0,0] neg_hi:[1,0,0]
	v_pk_fma_f32 v[72:73], v[94:95], v[26:27], v[72:73] neg_lo:[1,0,0] neg_hi:[1,0,0]
	ds_read_b128 v[92:95], v78 offset:16528
	s_waitcnt lgkmcnt(6)
	v_pk_fma_f32 v[70:71], v[96:97], v[28:29], v[70:71] neg_lo:[1,0,0] neg_hi:[1,0,0]
	v_pk_fma_f32 v[72:73], v[98:99], v[30:31], v[72:73] neg_lo:[1,0,0] neg_hi:[1,0,0]
	ds_read_b128 v[96:99], v78 offset:16544
	s_waitcnt lgkmcnt(6)
	v_pk_fma_f32 v[70:71], v[100:101], v[34:35], v[70:71] neg_lo:[1,0,0] neg_hi:[1,0,0]
	v_pk_fma_f32 v[72:73], v[102:103], v[36:37], v[72:73] neg_lo:[1,0,0] neg_hi:[1,0,0]
	ds_read_b128 v[100:103], v78 offset:16592
	s_waitcnt lgkmcnt(6)
	v_pk_fma_f32 v[70:71], v[104:105], v[38:39], v[70:71] neg_lo:[1,0,0] neg_hi:[1,0,0]
	v_pk_fma_f32 v[72:73], v[106:107], v[40:41], v[72:73] neg_lo:[1,0,0] neg_hi:[1,0,0]
	ds_read_b128 v[104:107], v78 offset:16608
	s_waitcnt lgkmcnt(6)
	v_pk_fma_f32 v[70:71], v[108:109], v[42:43], v[70:71] neg_lo:[1,0,0] neg_hi:[1,0,0]
	v_pk_fma_f32 v[72:73], v[110:111], v[44:45], v[72:73] neg_lo:[1,0,0] neg_hi:[1,0,0]
	ds_read_b128 v[108:111], v78 offset:16624
	s_waitcnt lgkmcnt(6)
	v_pk_fma_f32 v[70:71], v[84:85], v[48:49], v[70:71] neg_lo:[1,0,0] neg_hi:[1,0,0]
	v_pk_fma_f32 v[72:73], v[86:87], v[50:51], v[72:73] neg_lo:[1,0,0] neg_hi:[1,0,0]
	ds_read_b128 v[84:87], v78 offset:16640
	s_waitcnt lgkmcnt(6)
	v_pk_fma_f32 v[70:71], v[88:89], v[52:53], v[70:71] neg_lo:[1,0,0] neg_hi:[1,0,0]
	v_pk_fma_f32 v[72:73], v[90:91], v[54:55], v[72:73] neg_lo:[1,0,0] neg_hi:[1,0,0]
	ds_read_b128 v[88:91], v78 offset:16656
	s_waitcnt lgkmcnt(6)
	v_pk_fma_f32 v[70:71], v[92:93], v[56:57], v[70:71] neg_lo:[1,0,0] neg_hi:[1,0,0]
	v_pk_fma_f32 v[72:73], v[94:95], v[58:59], v[72:73] neg_lo:[1,0,0] neg_hi:[1,0,0]
	ds_read_b128 v[92:95], v78 offset:16672
	s_waitcnt lgkmcnt(6)
	v_pk_fma_f32 v[70:71], v[96:97], v[60:61], v[70:71] neg_lo:[1,0,0] neg_hi:[1,0,0]
	v_fma_f32 v72, -v62, v98, v72
	v_mov_b32_e32 v68, v99
	ds_read_b128 v[96:99], v78 offset:16688
	s_waitcnt lgkmcnt(6)
	v_pk_fma_f32 v[74:75], v[100:101], v[0:1], 0 neg_lo:[1,0,0] neg_hi:[1,0,0]
	v_pk_fma_f32 v[76:77], v[102:103], v[2:3], 0 neg_lo:[1,0,0] neg_hi:[1,0,0]
	v_fma_f32 v73, -v63, v68, v73
	ds_read_b128 v[100:103], v78 offset:16704
	s_waitcnt lgkmcnt(6)
	v_pk_fma_f32 v[74:75], v[104:105], v[4:5], v[74:75] neg_lo:[1,0,0] neg_hi:[1,0,0]
	v_pk_fma_f32 v[76:77], v[106:107], v[6:7], v[76:77] neg_lo:[1,0,0] neg_hi:[1,0,0]
	v_add_f32_e32 v70, v70, v71
	ds_read_b128 v[104:107], v78 offset:16720
	s_waitcnt lgkmcnt(6)
	v_pk_fma_f32 v[74:75], v[108:109], v[8:9], v[74:75] neg_lo:[1,0,0] neg_hi:[1,0,0]
	v_pk_fma_f32 v[76:77], v[110:111], v[10:11], v[76:77] neg_lo:[1,0,0] neg_hi:[1,0,0]
	v_add_f32_e32 v72, v72, v73
	ds_read_b128 v[108:111], v78 offset:16736
	s_waitcnt lgkmcnt(6)
	v_pk_fma_f32 v[74:75], v[84:85], v[12:13], v[74:75] neg_lo:[1,0,0] neg_hi:[1,0,0]
	v_pk_fma_f32 v[76:77], v[86:87], v[14:15], v[76:77] neg_lo:[1,0,0] neg_hi:[1,0,0]
	v_add_f32_e32 v70, v70, v72
	ds_read_b128 v[84:87], v78 offset:16752
	s_waitcnt lgkmcnt(6)
	v_pk_fma_f32 v[74:75], v[88:89], v[16:17], v[74:75] neg_lo:[1,0,0] neg_hi:[1,0,0]
	v_pk_fma_f32 v[76:77], v[90:91], v[18:19], v[76:77] neg_lo:[1,0,0] neg_hi:[1,0,0]
	v_add_f32_e32 v64, v64, v70
	ds_read_b128 v[88:91], v78 offset:16768
	s_waitcnt lgkmcnt(6)
	v_pk_fma_f32 v[74:75], v[92:93], v[20:21], v[74:75] neg_lo:[1,0,0] neg_hi:[1,0,0]
	v_pk_fma_f32 v[76:77], v[94:95], v[22:23], v[76:77] neg_lo:[1,0,0] neg_hi:[1,0,0]
	ds_read_b128 v[92:95], v78 offset:16784
	s_waitcnt lgkmcnt(6)
	v_pk_fma_f32 v[74:75], v[96:97], v[24:25], v[74:75] neg_lo:[1,0,0] neg_hi:[1,0,0]
	v_pk_fma_f32 v[76:77], v[98:99], v[26:27], v[76:77] neg_lo:[1,0,0] neg_hi:[1,0,0]
	ds_read_b128 v[96:99], v78 offset:16800
	s_waitcnt lgkmcnt(6)
	v_pk_fma_f32 v[74:75], v[100:101], v[28:29], v[74:75] neg_lo:[1,0,0] neg_hi:[1,0,0]
	v_pk_fma_f32 v[76:77], v[102:103], v[30:31], v[76:77] neg_lo:[1,0,0] neg_hi:[1,0,0]
	ds_read_b128 v[100:103], v78 offset:16816
	s_waitcnt lgkmcnt(6)
	v_pk_fma_f32 v[74:75], v[104:105], v[34:35], v[74:75] neg_lo:[1,0,0] neg_hi:[1,0,0]
	v_pk_fma_f32 v[76:77], v[106:107], v[36:37], v[76:77] neg_lo:[1,0,0] neg_hi:[1,0,0]
	ds_read_b128 v[104:107], v78 offset:16832
	s_waitcnt lgkmcnt(6)
	v_pk_fma_f32 v[74:75], v[108:109], v[38:39], v[74:75] neg_lo:[1,0,0] neg_hi:[1,0,0]
	v_pk_fma_f32 v[76:77], v[110:111], v[40:41], v[76:77] neg_lo:[1,0,0] neg_hi:[1,0,0]
	ds_read_b128 v[108:111], v78 offset:16864
	s_waitcnt lgkmcnt(6)
	v_pk_fma_f32 v[74:75], v[84:85], v[42:43], v[74:75] neg_lo:[1,0,0] neg_hi:[1,0,0]
	v_pk_fma_f32 v[76:77], v[86:87], v[44:45], v[76:77] neg_lo:[1,0,0] neg_hi:[1,0,0]
	ds_read_b128 v[84:87], v78 offset:16880
	s_waitcnt lgkmcnt(6)
	v_pk_fma_f32 v[74:75], v[88:89], v[48:49], v[74:75] neg_lo:[1,0,0] neg_hi:[1,0,0]
	v_pk_fma_f32 v[76:77], v[90:91], v[50:51], v[76:77] neg_lo:[1,0,0] neg_hi:[1,0,0]
	ds_read_b128 v[88:91], v78 offset:16896
	s_waitcnt lgkmcnt(6)
	v_pk_fma_f32 v[74:75], v[92:93], v[52:53], v[74:75] neg_lo:[1,0,0] neg_hi:[1,0,0]
	v_pk_fma_f32 v[76:77], v[94:95], v[54:55], v[76:77] neg_lo:[1,0,0] neg_hi:[1,0,0]
	ds_read_b128 v[92:95], v78 offset:16912
	s_waitcnt lgkmcnt(6)
	v_pk_fma_f32 v[74:75], v[96:97], v[56:57], v[74:75] neg_lo:[1,0,0] neg_hi:[1,0,0]
	v_pk_fma_f32 v[76:77], v[98:99], v[58:59], v[76:77] neg_lo:[1,0,0] neg_hi:[1,0,0]
	ds_read_b128 v[96:99], v78 offset:16928
	s_waitcnt lgkmcnt(6)
	v_pk_fma_f32 v[74:75], v[100:101], v[60:61], v[74:75] neg_lo:[1,0,0] neg_hi:[1,0,0]
	v_pk_fma_f32 v[76:77], v[102:103], v[62:63], v[76:77] neg_lo:[1,0,0] neg_hi:[1,0,0]
	ds_read_b128 v[100:103], v78 offset:16944
	s_waitcnt lgkmcnt(6)
; DI void gdn_prep(const Params& p, int item, unsigned char* smem) {
;     ...
; #pragma unroll
;         for (int i = 1; i < 64; ++i) {
;             float a = X[i];
;             int dep; asm volatile("v_and_b32 %0, 0, %1" : "=v"(dep) : "v"(X[i - 1]));
;             const float* Lr = sL + i * 68 + dep;
;             float b0 = 0.f, b1 = 0.f, b2 = 0.f;
; #pragma unroll
;             for (int j4 = 0; j4 < (i + 3) / 4; ++j4) {
;                 const f32x4 l = *(const f32x4*)(Lr + 4 * j4);
;                 if (4 * j4 + 0 < i) a -= l.x * X[4 * j4 + 0];
;                 if (4 * j4 + 1 < i) b0 -= l.y * X[4 * j4 + 1];
;                 if (4 * j4 + 2 < i) b1 -= l.z * X[4 * j4 + 2];
;                 if (4 * j4 + 3 < i) b2 -= l.w * X[4 * j4 + 3];
;             }
;             X[i] = (a + b0) + (b1 + b2);
;         }
	v_mov_b32_e32 v69, v104
	ds_read_b128 v[104:107], v78 offset:16960
	s_waitcnt lgkmcnt(6)
	v_pk_fma_f32 v[70:71], v[108:109], v[0:1], 0 neg_lo:[1,0,0] neg_hi:[1,0,0]
	v_pk_fma_f32 v[72:73], v[110:111], v[2:3], 0 neg_lo:[1,0,0] neg_hi:[1,0,0]
	v_fma_f32 v74, -v64, v69, v74
	ds_read_b128 v[108:111], v78 offset:16976
	s_waitcnt lgkmcnt(6)
	v_pk_fma_f32 v[70:71], v[84:85], v[4:5], v[70:71] neg_lo:[1,0,0] neg_hi:[1,0,0]
	v_pk_fma_f32 v[72:73], v[86:87], v[6:7], v[72:73] neg_lo:[1,0,0] neg_hi:[1,0,0]
	v_add_f32_e32 v74, v74, v75
	ds_read_b128 v[84:87], v78 offset:16992
	s_waitcnt lgkmcnt(6)
	v_pk_fma_f32 v[70:71], v[88:89], v[8:9], v[70:71] neg_lo:[1,0,0] neg_hi:[1,0,0]
	v_pk_fma_f32 v[72:73], v[90:91], v[10:11], v[72:73] neg_lo:[1,0,0] neg_hi:[1,0,0]
	v_add_f32_e32 v76, v76, v77
	ds_read_b128 v[88:91], v78 offset:17008
	s_waitcnt lgkmcnt(6)
	v_pk_fma_f32 v[70:71], v[92:93], v[12:13], v[70:71] neg_lo:[1,0,0] neg_hi:[1,0,0]
	v_pk_fma_f32 v[72:73], v[94:95], v[14:15], v[72:73] neg_lo:[1,0,0] neg_hi:[1,0,0]
	v_add_f32_e32 v74, v74, v76
	ds_read_b128 v[92:95], v78 offset:17024
	s_waitcnt lgkmcnt(6)
	v_pk_fma_f32 v[70:71], v[96:97], v[16:17], v[70:71] neg_lo:[1,0,0] neg_hi:[1,0,0]
	v_pk_fma_f32 v[72:73], v[98:99], v[18:19], v[72:73] neg_lo:[1,0,0] neg_hi:[1,0,0]
	v_add_f32_e32 v65, v65, v74
	ds_read_b128 v[96:99], v78 offset:17040
	s_waitcnt lgkmcnt(6)
	v_pk_fma_f32 v[70:71], v[100:101], v[20:21], v[70:71] neg_lo:[1,0,0] neg_hi:[1,0,0]
	v_pk_fma_f32 v[72:73], v[102:103], v[22:23], v[72:73] neg_lo:[1,0,0] neg_hi:[1,0,0]
	ds_read_b128 v[100:103], v78 offset:17056
	s_waitcnt lgkmcnt(6)
	v_pk_fma_f32 v[70:71], v[104:105], v[24:25], v[70:71] neg_lo:[1,0,0] neg_hi:[1,0,0]
	v_pk_fma_f32 v[72:73], v[106:107], v[26:27], v[72:73] neg_lo:[1,0,0] neg_hi:[1,0,0]
	ds_read_b128 v[104:107], v78 offset:17072
	s_waitcnt lgkmcnt(6)
	v_pk_fma_f32 v[70:71], v[108:109], v[28:29], v[70:71] neg_lo:[1,0,0] neg_hi:[1,0,0]
	v_pk_fma_f32 v[72:73], v[110:111], v[30:31], v[72:73] neg_lo:[1,0,0] neg_hi:[1,0,0]
	ds_read_b128 v[108:111], v78 offset:17088
	s_waitcnt lgkmcnt(6)
	v_pk_fma_f32 v[70:71], v[84:85], v[34:35], v[70:71] neg_lo:[1,0,0] neg_hi:[1,0,0]
	v_pk_fma_f32 v[72:73], v[86:87], v[36:37], v[72:73] neg_lo:[1,0,0] neg_hi:[1,0,0]
	ds_read_b128 v[84:87], v78 offset:17104
	s_waitcnt lgkmcnt(6)
	v_pk_fma_f32 v[70:71], v[88:89], v[38:39], v[70:71] neg_lo:[1,0,0] neg_hi:[1,0,0]
	v_pk_fma_f32 v[72:73], v[90:91], v[40:41], v[72:73] neg_lo:[1,0,0] neg_hi:[1,0,0]
	ds_read_b128 v[88:91], v78 offset:17136
	s_waitcnt lgkmcnt(6)
	v_pk_fma_f32 v[70:71], v[92:93], v[42:43], v[70:71] neg_lo:[1,0,0] neg_hi:[1,0,0]
	v_pk_fma_f32 v[72:73], v[94:95], v[44:45], v[72:73] neg_lo:[1,0,0] neg_hi:[1,0,0]
	ds_read_b128 v[92:95], v78 offset:17152
	s_waitcnt lgkmcnt(6)
	v_pk_fma_f32 v[70:71], v[96:97], v[48:49], v[70:71] neg_lo:[1,0,0] neg_hi:[1,0,0]
	v_pk_fma_f32 v[72:73], v[98:99], v[50:51], v[72:73] neg_lo:[1,0,0] neg_hi:[1,0,0]
	ds_read_b128 v[96:99], v78 offset:17168
	s_waitcnt lgkmcnt(6)
	v_pk_fma_f32 v[70:71], v[100:101], v[52:53], v[70:71] neg_lo:[1,0,0] neg_hi:[1,0,0]
	v_pk_fma_f32 v[72:73], v[102:103], v[54:55], v[72:73] neg_lo:[1,0,0] neg_hi:[1,0,0]
	ds_read_b128 v[100:103], v78 offset:17184
	s_waitcnt lgkmcnt(6)
	v_pk_fma_f32 v[70:71], v[104:105], v[56:57], v[70:71] neg_lo:[1,0,0] neg_hi:[1,0,0]
	v_pk_fma_f32 v[72:73], v[106:107], v[58:59], v[72:73] neg_lo:[1,0,0] neg_hi:[1,0,0]
	ds_read_b128 v[104:107], v78 offset:17200
	s_waitcnt lgkmcnt(6)
	v_pk_fma_f32 v[70:71], v[108:109], v[60:61], v[70:71] neg_lo:[1,0,0] neg_hi:[1,0,0]
	v_pk_fma_f32 v[72:73], v[110:111], v[62:63], v[72:73] neg_lo:[1,0,0] neg_hi:[1,0,0]
	ds_read_b128 v[108:111], v78 offset:17216
	s_waitcnt lgkmcnt(6)
	v_fma_f32 v70, -v64, v84, v70
	v_mov_b32_e32 v68, v85
	ds_read_b128 v[84:87], v78 offset:17232
	s_waitcnt lgkmcnt(6)
	v_pk_fma_f32 v[74:75], v[88:89], v[0:1], 0 neg_lo:[1,0,0] neg_hi:[1,0,0]
	v_pk_fma_f32 v[76:77], v[90:91], v[2:3], 0 neg_lo:[1,0,0] neg_hi:[1,0,0]
	v_fma_f32 v71, -v65, v68, v71
	ds_read_b128 v[88:91], v78 offset:17248
	s_waitcnt lgkmcnt(6)
	v_pk_fma_f32 v[74:75], v[92:93], v[4:5], v[74:75] neg_lo:[1,0,0] neg_hi:[1,0,0]
	v_pk_fma_f32 v[76:77], v[94:95], v[6:7], v[76:77] neg_lo:[1,0,0] neg_hi:[1,0,0]
	v_add_f32_e32 v70, v70, v71
	ds_read_b128 v[92:95], v78 offset:17264
	s_waitcnt lgkmcnt(6)
	v_pk_fma_f32 v[74:75], v[96:97], v[8:9], v[74:75] neg_lo:[1,0,0] neg_hi:[1,0,0]
	v_pk_fma_f32 v[76:77], v[98:99], v[10:11], v[76:77] neg_lo:[1,0,0] neg_hi:[1,0,0]
	v_add_f32_e32 v72, v72, v73
	ds_read_b128 v[96:99], v78 offset:17280
	s_waitcnt lgkmcnt(6)
	v_pk_fma_f32 v[74:75], v[100:101], v[12:13], v[74:75] neg_lo:[1,0,0] neg_hi:[1,0,0]
	v_pk_fma_f32 v[76:77], v[102:103], v[14:15], v[76:77] neg_lo:[1,0,0] neg_hi:[1,0,0]
	v_add_f32_e32 v70, v70, v72
	ds_read_b128 v[100:103], v78 offset:17296
	s_waitcnt lgkmcnt(6)
	v_pk_fma_f32 v[74:75], v[104:105], v[16:17], v[74:75] neg_lo:[1,0,0] neg_hi:[1,0,0]
	v_pk_fma_f32 v[76:77], v[106:107], v[18:19], v[76:77] neg_lo:[1,0,0] neg_hi:[1,0,0]
	v_add_f32_e32 v66, v66, v70
	ds_read_b128 v[104:107], v78 offset:17312
	s_waitcnt lgkmcnt(6)
	v_pk_fma_f32 v[74:75], v[108:109], v[20:21], v[74:75] neg_lo:[1,0,0] neg_hi:[1,0,0]
	v_pk_fma_f32 v[76:77], v[110:111], v[22:23], v[76:77] neg_lo:[1,0,0] neg_hi:[1,0,0]
	ds_read_b128 v[108:111], v78 offset:17328
	s_waitcnt lgkmcnt(6)
	v_pk_fma_f32 v[74:75], v[84:85], v[24:25], v[74:75] neg_lo:[1,0,0] neg_hi:[1,0,0]
	v_pk_fma_f32 v[76:77], v[86:87], v[26:27], v[76:77] neg_lo:[1,0,0] neg_hi:[1,0,0]
	ds_read_b128 v[84:87], v78 offset:17344
	s_waitcnt lgkmcnt(6)
; DI void gdn_prep(const Params& p, int item, unsigned char* smem) {
;     ...
; #pragma unroll
;         for (int i = 1; i < 64; ++i) {
;             float a = X[i];
;             int dep; asm volatile("v_and_b32 %0, 0, %1" : "=v"(dep) : "v"(X[i - 1]));
;             const float* Lr = sL + i * 68 + dep;
;             float b0 = 0.f, b1 = 0.f, b2 = 0.f;
; #pragma unroll
;             for (int j4 = 0; j4 < (i + 3) / 4; ++j4) {
;                 const f32x4 l = *(const f32x4*)(Lr + 4 * j4);
;                 if (4 * j4 + 0 < i) a -= l.x * X[4 * j4 + 0];
;                 if (4 * j4 + 1 < i) b0 -= l.y * X[4 * j4 + 1];
;                 if (4 * j4 + 2 < i) b1 -= l.z * X[4 * j4 + 2];
;                 if (4 * j4 + 3 < i) b2 -= l.w * X[4 * j4 + 3];
;             }
;             X[i] = (a + b0) + (b1 + b2);
;         }
;         if (tid < 128) {
	v_pk_fma_f32 v[74:75], v[88:89], v[28:29], v[74:75] neg_lo:[1,0,0] neg_hi:[1,0,0]
	v_pk_fma_f32 v[76:77], v[90:91], v[30:31], v[76:77] neg_lo:[1,0,0] neg_hi:[1,0,0]
	ds_read_b128 v[88:91], v78 offset:17360
	s_waitcnt lgkmcnt(6)
	v_pk_fma_f32 v[74:75], v[92:93], v[34:35], v[74:75] neg_lo:[1,0,0] neg_hi:[1,0,0]
	v_pk_fma_f32 v[76:77], v[94:95], v[36:37], v[76:77] neg_lo:[1,0,0] neg_hi:[1,0,0]
	ds_read_b128 v[92:95], v78 offset:17376
	s_waitcnt lgkmcnt(6)
	v_pk_fma_f32 v[74:75], v[96:97], v[38:39], v[74:75] neg_lo:[1,0,0] neg_hi:[1,0,0]
	v_pk_fma_f32 v[76:77], v[98:99], v[40:41], v[76:77] neg_lo:[1,0,0] neg_hi:[1,0,0]
	s_waitcnt lgkmcnt(5)
	v_pk_fma_f32 v[74:75], v[100:101], v[42:43], v[74:75] neg_lo:[1,0,0] neg_hi:[1,0,0]
	v_pk_fma_f32 v[76:77], v[102:103], v[44:45], v[76:77] neg_lo:[1,0,0] neg_hi:[1,0,0]
	s_waitcnt lgkmcnt(4)
	v_pk_fma_f32 v[74:75], v[104:105], v[48:49], v[74:75] neg_lo:[1,0,0] neg_hi:[1,0,0]
	v_pk_fma_f32 v[76:77], v[106:107], v[50:51], v[76:77] neg_lo:[1,0,0] neg_hi:[1,0,0]
	s_waitcnt lgkmcnt(3)
	v_pk_fma_f32 v[74:75], v[108:109], v[52:53], v[74:75] neg_lo:[1,0,0] neg_hi:[1,0,0]
	v_pk_fma_f32 v[76:77], v[110:111], v[54:55], v[76:77] neg_lo:[1,0,0] neg_hi:[1,0,0]
	s_waitcnt lgkmcnt(2)
	v_pk_fma_f32 v[74:75], v[84:85], v[56:57], v[74:75] neg_lo:[1,0,0] neg_hi:[1,0,0]
	v_pk_fma_f32 v[76:77], v[86:87], v[58:59], v[76:77] neg_lo:[1,0,0] neg_hi:[1,0,0]
	s_waitcnt lgkmcnt(1)
	v_pk_fma_f32 v[74:75], v[88:89], v[60:61], v[74:75] neg_lo:[1,0,0] neg_hi:[1,0,0]
	v_pk_fma_f32 v[76:77], v[90:91], v[62:63], v[76:77] neg_lo:[1,0,0] neg_hi:[1,0,0]
	s_waitcnt lgkmcnt(0)
	v_pk_fma_f32 v[74:75], v[92:93], v[64:65], v[74:75] neg_lo:[1,0,0] neg_hi:[1,0,0]
	v_mov_b32_e32 v69, v94
	v_fma_f32 v76, -v66, v69, v76
	v_add_f32_e32 v74, v74, v75
	v_add_f32_e32 v76, v76, v77
	v_add_f32_e32 v74, v74, v76
	v_add_f32_e32 v67, v67, v74
	v_mov_b32_e32 v33, v28
	v_mov_b32_e32 v28, v65
	v_mov_b32_e32 v65, v49
	v_mov_b32_e32 v49, v39
	v_mov_b32_e32 v39, v34
	v_mov_b32_e32 v34, v29
	v_mov_b32_e32 v29, v26
	v_mov_b32_e32 v26, v24
	v_mov_b32_e32 v24, v22
	v_mov_b32_e32 v22, v20
	v_mov_b32_e32 v20, v18
	v_mov_b32_e32 v18, v16
	v_mov_b32_e32 v16, v14
	v_mov_b32_e32 v14, v12
	v_mov_b32_e32 v12, v10
	v_mov_b32_e32 v10, v8
	v_mov_b32_e32 v8, v6
	v_mov_b32_e32 v6, v4
	v_mov_b32_e32 v4, v1
	v_mov_b32_e32 v68, v67
	v_mov_b32_e32 v67, v66
	v_mov_b32_e32 v66, v58
	v_mov_b32_e32 v58, v44
	v_mov_b32_e32 v44, v37
	v_mov_b32_e32 v37, v31
	v_mov_b32_e32 v31, v64
	v_mov_b32_e32 v64, v50
	v_mov_b32_e32 v50, v57
	v_mov_b32_e32 v57, v54
	v_mov_b32_e32 v54, v42
	v_mov_b32_e32 v42, v36
	v_mov_b32_e32 v36, v30
	v_mov_b32_e32 v30, v27
	v_mov_b32_e32 v27, v25
	v_mov_b32_e32 v25, v23
	v_mov_b32_e32 v23, v21
	v_mov_b32_e32 v21, v19
	v_mov_b32_e32 v19, v17
	v_mov_b32_e32 v17, v15
	v_mov_b32_e32 v15, v13
	v_mov_b32_e32 v13, v11
	v_mov_b32_e32 v11, v9
	v_mov_b32_e32 v9, v7
	v_mov_b32_e32 v7, v5
	v_mov_b32_e32 v5, v3
	v_mov_b32_e32 v3, v2
	v_mov_b32_e32 v2, v0
	v_mov_b32_e32 v83, v35
	v_mov_b32_e32 v35, v63
	v_mov_b32_e32 v63, v48
	v_mov_b32_e32 v48, v38
	v_mov_b32_e32 v38, v62
	v_mov_b32_e32 v62, v51
	v_mov_b32_e32 v51, v40
	v_mov_b32_e32 v40, v61
	v_mov_b32_e32 v61, v45
	v_mov_b32_e32 v45, v59
	v_mov_b32_e32 v59, v53
	v_mov_b32_e32 v53, v41
	v_mov_b32_e32 v41, v83
	v_mov_b32_e32 v83, v43
	v_mov_b32_e32 v43, v60
	v_mov_b32_e32 v60, v52
	v_mov_b32_e32 v52, v56
	v_mov_b32_e32 v56, v83
	s_and_saveexec_b64 s[4:5], vcc
	s_xor_b64 s[4:5], exec, s[4:5]
	s_cbranch_execz .LBB0_409
; DI bf16_t f2bf(float a) { return (bf16_t)(pk2(a, 0.f) & 0xffffu); }
; DI void gdn_prep(const Params& p, int item, unsigned char* smem) {
;     ...
;             bf16_t* wg = (bf16_t*)(p.ws + WS_W) + (size_t)item * 8192 + (tid - 128);
; #pragma unroll
;             for (int i = 0; i < 64; ++i) wg[i * 128] = f2bf(X[i]);
	s_add_u32 s74, s72, s30
	v_mov_b32_e32 v47, v117
	s_addc_u32 s75, s73, s31
	v_lshl_add_u64 v[0:1], v[46:47], 1, s[74:75]
	v_add_co_u32_e32 v70, vcc, 0x1ddc4000, v0
	v_cvt_pk_bf16_f32 v2, v2, s0
	s_nop 0
	v_addc_co_u32_e32 v71, vcc, 0, v1, vcc
	global_store_short v[70:71], v2, off offset:3840
	v_add_co_u32_e32 v70, vcc, 0x1ddc5000, v0
	v_cvt_pk_bf16_f32 v2, v4, s0
	s_nop 0
	v_addc_co_u32_e32 v71, vcc, 0, v1, vcc
	global_store_short v[70:71], v2, off
	v_cvt_pk_bf16_f32 v2, v3, s0
	global_store_short v[70:71], v2, off offset:256
	v_cvt_pk_bf16_f32 v2, v5, s0
	global_store_short v[70:71], v2, off offset:512
	v_cvt_pk_bf16_f32 v2, v6, s0
	global_store_short v[70:71], v2, off offset:768
	v_cvt_pk_bf16_f32 v2, v7, s0
	global_store_short v[70:71], v2, off offset:1024
	v_cvt_pk_bf16_f32 v2, v8, s0
	global_store_short v[70:71], v2, off offset:1280
	v_cvt_pk_bf16_f32 v2, v9, s0
	global_store_short v[70:71], v2, off offset:1536
	v_cvt_pk_bf16_f32 v2, v10, s0
	global_store_short v[70:71], v2, off offset:1792
	v_cvt_pk_bf16_f32 v2, v11, s0
	global_store_short v[70:71], v2, off offset:2048
	v_cvt_pk_bf16_f32 v2, v12, s0
	global_store_short v[70:71], v2, off offset:2304
	v_cvt_pk_bf16_f32 v2, v13, s0
	global_store_short v[70:71], v2, off offset:2560
	v_cvt_pk_bf16_f32 v2, v14, s0
	global_store_short v[70:71], v2, off offset:2816
	v_cvt_pk_bf16_f32 v2, v15, s0
	global_store_short v[70:71], v2, off offset:3072
	v_cvt_pk_bf16_f32 v2, v16, s0
	global_store_short v[70:71], v2, off offset:3328
	v_cvt_pk_bf16_f32 v2, v17, s0
	global_store_short v[70:71], v2, off offset:3584
	v_cvt_pk_bf16_f32 v2, v18, s0
	s_mov_b32 s15, 0x1ddc6000
	global_store_short v[70:71], v2, off offset:3840
	v_add_co_u32_e32 v2, vcc, s15, v0
	s_mov_b32 s15, 0x1ddc7000
	s_nop 0
	v_addc_co_u32_e32 v3, vcc, 0, v1, vcc
	v_add_co_u32_e32 v4, vcc, s15, v0
	v_cvt_pk_bf16_f32 v6, v19, s0
	s_nop 0
	v_addc_co_u32_e32 v5, vcc, 0, v1, vcc
	global_store_short v[4:5], v6, off offset:-4096
	v_cvt_pk_bf16_f32 v6, v20, s0
	global_store_short v[2:3], v6, off offset:256
	v_cvt_pk_bf16_f32 v6, v21, s0
	global_store_short v[2:3], v6, off offset:512
	v_cvt_pk_bf16_f32 v6, v22, s0
	global_store_short v[2:3], v6, off offset:768
	v_cvt_pk_bf16_f32 v6, v23, s0
	global_store_short v[2:3], v6, off offset:1024
	v_cvt_pk_bf16_f32 v6, v24, s0
	global_store_short v[2:3], v6, off offset:1280
	v_cvt_pk_bf16_f32 v6, v25, s0
	global_store_short v[2:3], v6, off offset:1536
	v_cvt_pk_bf16_f32 v6, v26, s0
	global_store_short v[2:3], v6, off offset:1792
	v_cvt_pk_bf16_f32 v6, v27, s0
	global_store_short v[2:3], v6, off offset:2048
	v_cvt_pk_bf16_f32 v6, v29, s0
	global_store_short v[2:3], v6, off offset:2304
	v_cvt_pk_bf16_f32 v6, v30, s0
	global_store_short v[2:3], v6, off offset:2560
	v_cvt_pk_bf16_f32 v6, v33, s0
	global_store_short v[2:3], v6, off offset:2816
	v_cvt_pk_bf16_f32 v6, v34, s0
	global_store_short v[2:3], v6, off offset:3072
	v_cvt_pk_bf16_f32 v6, v36, s0
	global_store_short v[2:3], v6, off offset:3328
	v_cvt_pk_bf16_f32 v6, v37, s0
	global_store_short v[2:3], v6, off offset:3584
	v_cvt_pk_bf16_f32 v6, v39, s0
	global_store_short v[2:3], v6, off offset:3840
	v_cvt_pk_bf16_f32 v2, v41, s0
	global_store_short v[4:5], v2, off
	v_cvt_pk_bf16_f32 v2, v42, s0
	global_store_short v[4:5], v2, off offset:256
	v_cvt_pk_bf16_f32 v2, v44, s0
	global_store_short v[4:5], v2, off offset:512
	v_cvt_pk_bf16_f32 v2, v48, s0
	global_store_short v[4:5], v2, off offset:768
	v_cvt_pk_bf16_f32 v2, v49, s0
	global_store_short v[4:5], v2, off offset:1024
	v_cvt_pk_bf16_f32 v2, v51, s0
	global_store_short v[4:5], v2, off offset:1280
	v_cvt_pk_bf16_f32 v2, v53, s0
	global_store_short v[4:5], v2, off offset:1536
	v_cvt_pk_bf16_f32 v2, v54, s0
	global_store_short v[4:5], v2, off offset:1792
	v_cvt_pk_bf16_f32 v2, v56, s0
	global_store_short v[4:5], v2, off offset:2048
	v_cvt_pk_bf16_f32 v2, v58, s0
	global_store_short v[4:5], v2, off offset:2304
	v_cvt_pk_bf16_f32 v2, v61, s0
	global_store_short v[4:5], v2, off offset:2560
	v_cvt_pk_bf16_f32 v2, v63, s0
	global_store_short v[4:5], v2, off offset:2816
	v_cvt_pk_bf16_f32 v2, v65, s0
	global_store_short v[4:5], v2, off offset:3072
	v_cvt_pk_bf16_f32 v2, v64, s0
	global_store_short v[4:5], v2, off offset:3328
	v_cvt_pk_bf16_f32 v2, v62, s0
	s_mov_b32 s15, 0x1ddc8000
	global_store_short v[4:5], v2, off offset:3584
	v_cvt_pk_bf16_f32 v2, v60, s0
	v_add_co_u32_e32 v0, vcc, s15, v0
	global_store_short v[4:5], v2, off offset:3840
	v_cvt_pk_bf16_f32 v2, v59, s0
	v_addc_co_u32_e32 v1, vcc, 0, v1, vcc
	global_store_short v[0:1], v2, off
	v_cvt_pk_bf16_f32 v2, v57, s0
	global_store_short v[0:1], v2, off offset:256
	v_cvt_pk_bf16_f32 v2, v55, s0
	global_store_short v[0:1], v2, off offset:512
	v_cvt_pk_bf16_f32 v2, v52, s0
	global_store_short v[0:1], v2, off offset:768
	v_cvt_pk_bf16_f32 v2, v50, s0
	global_store_short v[0:1], v2, off offset:1024
	v_cvt_pk_bf16_f32 v2, v66, s0
	global_store_short v[0:1], v2, off offset:1280
	v_cvt_pk_bf16_f32 v2, v45, s0
	global_store_short v[0:1], v2, off offset:1536
	v_cvt_pk_bf16_f32 v2, v43, s0
	global_store_short v[0:1], v2, off offset:1792
	v_cvt_pk_bf16_f32 v2, v40, s0
	global_store_short v[0:1], v2, off offset:2048
	v_cvt_pk_bf16_f32 v2, v38, s0
	global_store_short v[0:1], v2, off offset:2304
	v_cvt_pk_bf16_f32 v2, v35, s0
	global_store_short v[0:1], v2, off offset:2560
	v_cvt_pk_bf16_f32 v2, v31, s0
	global_store_short v[0:1], v2, off offset:2816
	v_cvt_pk_bf16_f32 v2, v28, s0
	global_store_short v[0:1], v2, off offset:3072
	v_cvt_pk_bf16_f32 v2, v67, s0
	global_store_short v[0:1], v2, off offset:3328
	v_cvt_pk_bf16_f32 v2, v68, s0
	global_store_short v[0:1], v2, off offset:3584
